# v27 plus projection epilogue row-statistic loads halved (each lane half loads 4 of the 8 partials, cross-half add by permlane32 swap)
# baseline (speedup 1.0000x reference)
.Lpe_entry_L0:
	s_nop 7
	s_and_b32 s24, s99, 7
	s_lshl_b32 s24, s24, 3
	s_bfe_u32 s25, s99, 0x30003
	s_or_b32 s24, s24, s25
	s_lshr_b32 s25, s99, 6
	v_readfirstlane_b32 s26, v178
	v_readlane_b32 s72, v254, 0
	v_readlane_b32 s73, v254, 1
	s_lshr_b32 s26, s26, 6
	s_lshr_b32 s27, s26, 2
	s_and_b32 s28, s26, 3
	s_lshl_b32 s29, s24, 8
	s_lshl_b32 s30, s27, 7
	s_add_u32 s29, s29, s30
	s_lshl_b32 s30, s25, 8
	s_lshl_b32 s31, s28, 6
	s_add_u32 s30, s30, s31
	s_lshl_b32 s31, s29, 5
	s_add_u32 s94, s72, 0x1ad20000
	s_addc_u32 s95, s73, 0
	s_add_u32 s94, s94, s31
	s_addc_u32 s95, s95, 0
	v_and_b32_e32 v197, 31, v179
	v_lshrrev_b32_e32 v146, 5, v179
	v_lshlrev_b32_e32 v180, 5, v197
	v_lshlrev_b32_e32 v146, 4, v146
	v_add_u32_e32 v180, v180, v146
	global_load_dwordx4 v[128:131], v180, s[94:95] offset:0
	global_load_dwordx4 v[136:139], v180, s[94:95] offset:1024
	global_load_dwordx4 v[164:167], v180, s[94:95] offset:2048
	global_load_dwordx4 v[246:249], v180, s[94:95] offset:3072
	s_mul_i32 s31, s29, 0x2200
	s_lshl_b32 s32, s30, 1
	s_add_u32 s31, s31, s32
	s_add_u32 s74, s72, 0xc120000
	s_addc_u32 s75, s73, 0
	s_add_u32 s74, s74, s31
	s_addc_u32 s75, s75, 0
	v_and_b32_e32 v181, 0x1c, v197
	v_mul_u32_u24_e32 v181, 0x2200, v181
	v_and_b32_e32 v198, 3, v197
	v_lshl_add_u32 v181, v198, 5, v181
	v_add_u32_e32 v181, v181, v146
	s_sub_u32 s34, s25, 4
	s_cmp_lt_u32 s34, 2
	s_cbranch_scc1 .Lpe_vt_all_L0
	s_cmp_eq_u32 s25, 8
	s_cbranch_scc0 .Lpe_notv_L0
	s_barrier
	s_cmp_ge_u32 s28, 2
	s_cbranch_scc1 .Lpe_vt_L0
	s_branch .Lpe_notv_L0

.Lpe_notv_L0:
	s_cmp_ge_u32 s25, 9
	s_cbranch_scc1 .Lpe_gates_L0
	s_lshr_b32 s34, s25, 1
	s_cmp_ge_u32 s25, 6
	s_cselect_b32 s35, 1, 0
	s_sub_u32 s34, s34, s35
	s_lshl_b32 s35, s98, 2
	s_add_u32 s35, s35, s34
	s_lshl_b32 s35, s35, 8
	v_readlane_b32 s82, v254, 14
	v_readlane_b32 s83, v254, 15
	s_add_u32 s82, s82, s35
	s_addc_u32 s83, s83, 0
	global_load_dwordx4 v[198:201], v146, s[82:83] offset:0
	global_load_dwordx4 v[202:205], v146, s[82:83] offset:32
	global_load_dwordx4 v[206:209], v146, s[82:83] offset:64
	global_load_dwordx4 v[210:213], v146, s[82:83] offset:96
	global_load_dwordx4 v[214:217], v146, s[82:83] offset:128
	global_load_dwordx4 v[218:221], v146, s[82:83] offset:160
	global_load_dwordx4 v[222:225], v146, s[82:83] offset:192
	global_load_dwordx4 v[226:229], v146, s[82:83] offset:224
	s_and_b32 s35, s34, 1
	s_cmp_eq_u32 s35, 0
	s_cselect_b32 s36, 0x3e000000, 1.0
	s_and_b32 s35, s29, 0x7ff
	s_lshl_b32 s35, s35, 7
	s_add_u32 s96, s72, 0x1ada0000
	s_addc_u32 s97, s73, 0
	s_add_u32 s96, s96, s35
	s_addc_u32 s97, s97, 0
	s_add_u32 s100, s96, 0x40000
	s_addc_u32 s101, s97, 0
	s_cmp_ge_u32 s34, 2
	s_cselect_b32 s37, 1, 0
	s_waitcnt vmcnt(8)
	v_lshlrev_b32_e32 v180, 7, v197
	v_add_u32_e32 v180, v180, v146
	v_mov_b32_e32 v197, 0x358637bd
	v_pk_add_f32 v[128:129], v[128:129], v[130:131]
	v_pk_add_f32 v[136:137], v[136:137], v[138:139]
	v_pk_add_f32 v[164:165], v[164:165], v[166:167]
	v_pk_add_f32 v[246:247], v[246:247], v[248:249]
	v_add_f32_e32 v128, v128, v129
	v_add_f32_e32 v136, v136, v137
	v_add_f32_e32 v164, v164, v165
	v_add_f32_e32 v246, v246, v247
	v_mov_b32_e32 v132, v128
	v_mov_b32_e32 v140, v136
	v_mov_b32_e32 v168, v164
	v_mov_b32_e32 v250, v246
	s_nop 1
	v_permlane32_swap_b32_e32 v132, v128
	v_permlane32_swap_b32_e32 v140, v136
	v_permlane32_swap_b32_e32 v168, v164
	v_permlane32_swap_b32_e32 v250, v246
	v_add_f32_e32 v128, v128, v132
	v_add_f32_e32 v136, v136, v140
	v_add_f32_e32 v164, v164, v168
	v_add_f32_e32 v246, v246, v250
	v_fmamk_f32 v128, v128, 0x3a800000, v197
	v_fmamk_f32 v136, v136, 0x3a800000, v197
	v_fmamk_f32 v164, v164, 0x3a800000, v197
	v_fmamk_f32 v246, v246, 0x3a800000, v197
	v_rsq_f32_e32 v172, v128
	v_rsq_f32_e32 v173, v136
	v_rsq_f32_e32 v174, v164
	v_rsq_f32_e32 v175, v246
	s_nop 0
	s_add_u32 s76, s99, s90
	s_cmp_lt_u32 s76, 0x440
	s_cselect_b32 s80, 1, 0
	s_cselect_b32 s83, 0x200000, 0
	s_lshl_b32 s76, s24, 19
	s_lshl_b32 s77, s26, 16
	s_add_u32 s76, s76, s77
	s_and_b32 s77, s24, 7
	s_lshl_b32 s77, s77, 8
	s_add_u32 s76, s76, s77
	s_add_u32 s78, s72, 0xa120000
	s_addc_u32 s79, s73, 0
	s_add_u32 s78, s78, s76
	s_addc_u32 s79, s79, 0
	s_lshl_b32 s76, s25, 19
	s_add_u32 s76, s76, s83
	s_add_u32 s76, s76, s77
	s_lshl_b32 s77, s26, 16
	s_add_u32 s76, s76, s77
	s_add_u32 s82, s72, 0x0
	s_addc_u32 s83, s73, 0
	s_add_u32 s82, s82, s76
	s_addc_u32 s83, s83, 0
	s_lshl_b32 s76, s26, 12
	s_mov_b32 m0, s76
	s_nop 0
	global_load_lds_dwordx4 v145, s[78:79]
	s_add_u32 s78, s78, 0x4000
	s_addc_u32 s79, s79, 0
	s_add_u32 s76, s76, 0x400
	s_mov_b32 m0, s76
	s_nop 0
	global_load_lds_dwordx4 v185, s[78:79]
	s_add_u32 s78, s78, 0x4000
	s_addc_u32 s79, s79, 0
	s_add_u32 s76, s76, 0x400
	s_mov_b32 m0, s76
	s_nop 0
	global_load_lds_dwordx4 v145, s[78:79]
	s_add_u32 s78, s78, 0x4000
	s_addc_u32 s79, s79, 0
	s_add_u32 s76, s76, 0x400
	s_mov_b32 m0, s76
	s_nop 0
	global_load_lds_dwordx4 v185, s[78:79]
	s_add_u32 s78, s78, 0x4000
	s_addc_u32 s79, s79, 0
	s_add_u32 s76, s76, 0x400
	s_add_u32 s76, s76, 0x7000
	s_mov_b32 m0, s76
	s_nop 0
	global_load_lds_dwordx4 v145, s[82:83]
	s_add_u32 s82, s82, 0x4000
	s_addc_u32 s83, s83, 0
	s_add_u32 s76, s76, 0x400
	s_mov_b32 m0, s76
	s_nop 0
	global_load_lds_dwordx4 v185, s[82:83]
	s_add_u32 s82, s82, 0x4000
	s_addc_u32 s83, s83, 0
	s_add_u32 s76, s76, 0x400
	s_mov_b32 m0, s76
	s_nop 0
	global_load_lds_dwordx4 v145, s[82:83]
	s_add_u32 s82, s82, 0x4000
	s_addc_u32 s83, s83, 0
	s_add_u32 s76, s76, 0x400
	s_mov_b32 m0, s76
	s_nop 0
	global_load_lds_dwordx4 v185, s[82:83]
	s_add_u32 s82, s82, 0x4000
	s_addc_u32 s83, s83, 0
	s_add_u32 s76, s76, 0x400
	s_cmp_eq_u32 s37, 0
	s_cbranch_scc1 .Lpe_norope_ld_L0
	global_load_dwordx4 v[230:233], v180, s[96:97] offset:0
	global_load_dwordx4 v[234:237], v180, s[96:97] offset:32
	global_load_dwordx4 v[238:241], v180, s[96:97] offset:64
	global_load_dwordx4 v[242:245], v180, s[96:97] offset:96
	global_load_dwordx4 v[148:151], v180, s[100:101] offset:0
	global_load_dwordx4 v[152:155], v180, s[100:101] offset:32
	global_load_dwordx4 v[156:159], v180, s[100:101] offset:64
	global_load_dwordx4 v[160:163], v180, s[100:101] offset:96

.Lpe_gates_L0:
	s_lshl_b32 s35, s98, 11
	s_add_u32 s35, s35, s30
	s_sub_u32 s35, s35, 0x900
	s_lshl_b32 s35, s35, 2
	v_readlane_b32 s82, v254, 12
	v_readlane_b32 s83, v254, 13
	s_add_u32 s82, s82, s35
	s_addc_u32 s83, s83, 0
	global_load_dwordx4 v[198:201], v146, s[82:83] offset:0
	global_load_dwordx4 v[202:205], v146, s[82:83] offset:32
	global_load_dwordx4 v[206:209], v146, s[82:83] offset:64
	global_load_dwordx4 v[210:213], v146, s[82:83] offset:96
	global_load_dwordx4 v[214:217], v146, s[82:83] offset:128
	global_load_dwordx4 v[218:221], v146, s[82:83] offset:160
	global_load_dwordx4 v[222:225], v146, s[82:83] offset:192
	global_load_dwordx4 v[226:229], v146, s[82:83] offset:224
	s_waitcnt vmcnt(8)
	v_mov_b32_e32 v197, 0x358637bd
	v_pk_add_f32 v[128:129], v[128:129], v[130:131]
	v_pk_add_f32 v[136:137], v[136:137], v[138:139]
	v_pk_add_f32 v[164:165], v[164:165], v[166:167]
	v_pk_add_f32 v[246:247], v[246:247], v[248:249]
	v_add_f32_e32 v128, v128, v129
	v_add_f32_e32 v136, v136, v137
	v_add_f32_e32 v164, v164, v165
	v_add_f32_e32 v246, v246, v247
	v_mov_b32_e32 v132, v128
	v_mov_b32_e32 v140, v136
	v_mov_b32_e32 v168, v164
	v_mov_b32_e32 v250, v246
	s_nop 1
	v_permlane32_swap_b32_e32 v132, v128
	v_permlane32_swap_b32_e32 v140, v136
	v_permlane32_swap_b32_e32 v168, v164
	v_permlane32_swap_b32_e32 v250, v246
	v_add_f32_e32 v128, v128, v132
	v_add_f32_e32 v136, v136, v140
	v_add_f32_e32 v164, v164, v168
	v_add_f32_e32 v246, v246, v250
	v_fmamk_f32 v128, v128, 0x3a800000, v197
	v_fmamk_f32 v136, v136, 0x3a800000, v197
	v_fmamk_f32 v164, v164, 0x3a800000, v197
	v_fmamk_f32 v246, v246, 0x3a800000, v197
	v_rsq_f32_e32 v172, v128
	v_rsq_f32_e32 v173, v136
	v_rsq_f32_e32 v174, v164
	v_rsq_f32_e32 v175, v246
	s_nop 0
	s_add_u32 s76, s99, s90
	s_cmp_lt_u32 s76, 0x440
	s_cselect_b32 s80, 1, 0
	s_cselect_b32 s83, 0x200000, 0
	s_lshl_b32 s76, s24, 19
	s_lshl_b32 s77, s26, 16
	s_add_u32 s76, s76, s77
	s_and_b32 s77, s24, 7
	s_lshl_b32 s77, s77, 8
	s_add_u32 s76, s76, s77
	s_add_u32 s78, s72, 0xa120000
	s_addc_u32 s79, s73, 0
	s_add_u32 s78, s78, s76
	s_addc_u32 s79, s79, 0
	s_lshl_b32 s76, s25, 19
	s_add_u32 s76, s76, s83
	s_add_u32 s76, s76, s77
	s_lshl_b32 s77, s26, 16
	s_add_u32 s76, s76, s77
	s_add_u32 s82, s72, 0x0
	s_addc_u32 s83, s73, 0
	s_add_u32 s82, s82, s76
	s_addc_u32 s83, s83, 0
	s_lshl_b32 s76, s26, 12
	s_mov_b32 m0, s76
	s_nop 0
	global_load_lds_dwordx4 v145, s[78:79]
	s_add_u32 s78, s78, 0x4000
	s_addc_u32 s79, s79, 0
	s_add_u32 s76, s76, 0x400
	s_mov_b32 m0, s76
	s_nop 0
	global_load_lds_dwordx4 v185, s[78:79]
	s_add_u32 s78, s78, 0x4000
	s_addc_u32 s79, s79, 0
	s_add_u32 s76, s76, 0x400
	s_mov_b32 m0, s76
	s_nop 0
	global_load_lds_dwordx4 v145, s[78:79]
	s_add_u32 s78, s78, 0x4000
	s_addc_u32 s79, s79, 0
	s_add_u32 s76, s76, 0x400
	s_mov_b32 m0, s76
	s_nop 0
	global_load_lds_dwordx4 v185, s[78:79]
	s_add_u32 s78, s78, 0x4000
	s_addc_u32 s79, s79, 0
	s_add_u32 s76, s76, 0x400
	s_add_u32 s76, s76, 0x7000
	s_mov_b32 m0, s76
	s_nop 0
	global_load_lds_dwordx4 v145, s[82:83]
	s_add_u32 s82, s82, 0x4000
	s_addc_u32 s83, s83, 0
	s_add_u32 s76, s76, 0x400
	s_mov_b32 m0, s76
	s_nop 0
	global_load_lds_dwordx4 v185, s[82:83]
	s_add_u32 s82, s82, 0x4000
	s_addc_u32 s83, s83, 0
	s_add_u32 s76, s76, 0x400
	s_mov_b32 m0, s76
	s_nop 0
	global_load_lds_dwordx4 v145, s[82:83]
	s_add_u32 s82, s82, 0x4000
	s_addc_u32 s83, s83, 0
	s_add_u32 s76, s76, 0x400
	s_mov_b32 m0, s76
	s_nop 0
	global_load_lds_dwordx4 v185, s[82:83]
	s_add_u32 s82, s82, 0x4000
	s_addc_u32 s83, s83, 0
	s_add_u32 s76, s76, 0x400
	v_mul_f32_e32 v172, 0xbfb8aa3b, v172
	v_mul_f32_e32 v173, 0xbfb8aa3b, v173
	v_mul_f32_e32 v174, 0xbfb8aa3b, v174
	v_mul_f32_e32 v175, 0xbfb8aa3b, v175
	s_waitcnt vmcnt(8)
	v_mul_f32_e32 v198, 0xbfb8aa3b, v198
	v_mul_f32_e32 v199, 0xbfb8aa3b, v199
	v_mul_f32_e32 v200, 0xbfb8aa3b, v200
	v_mul_f32_e32 v201, 0xbfb8aa3b, v201
	v_mul_f32_e32 v202, 0xbfb8aa3b, v202
	v_mul_f32_e32 v203, 0xbfb8aa3b, v203
	v_mul_f32_e32 v204, 0xbfb8aa3b, v204
	v_mul_f32_e32 v205, 0xbfb8aa3b, v205
	v_mul_f32_e32 v206, 0xbfb8aa3b, v206
	v_mul_f32_e32 v207, 0xbfb8aa3b, v207
	v_mul_f32_e32 v208, 0xbfb8aa3b, v208
	v_mul_f32_e32 v209, 0xbfb8aa3b, v209
	v_mul_f32_e32 v210, 0xbfb8aa3b, v210
	v_mul_f32_e32 v211, 0xbfb8aa3b, v211
	v_mul_f32_e32 v212, 0xbfb8aa3b, v212
	v_mul_f32_e32 v213, 0xbfb8aa3b, v213
	v_mul_f32_e32 v214, 0xbfb8aa3b, v214
	v_mul_f32_e32 v215, 0xbfb8aa3b, v215
	v_mul_f32_e32 v216, 0xbfb8aa3b, v216
	v_mul_f32_e32 v217, 0xbfb8aa3b, v217
	v_mul_f32_e32 v218, 0xbfb8aa3b, v218
	v_mul_f32_e32 v219, 0xbfb8aa3b, v219
	v_mul_f32_e32 v220, 0xbfb8aa3b, v220
	v_mul_f32_e32 v221, 0xbfb8aa3b, v221
	v_mul_f32_e32 v222, 0xbfb8aa3b, v222
	v_mul_f32_e32 v223, 0xbfb8aa3b, v223
	v_mul_f32_e32 v224, 0xbfb8aa3b, v224
	v_mul_f32_e32 v225, 0xbfb8aa3b, v225
	v_mul_f32_e32 v226, 0xbfb8aa3b, v226
	v_mul_f32_e32 v227, 0xbfb8aa3b, v227
	v_mul_f32_e32 v228, 0xbfb8aa3b, v228
	v_mul_f32_e32 v229, 0xbfb8aa3b, v229
	v_pk_fma_f32 v[0:1], v[0:1], v[172:173], v[198:199] op_sel_hi:[1,0,1]
	v_pk_fma_f32 v[2:3], v[2:3], v[172:173], v[200:201] op_sel_hi:[1,0,1]
	v_pk_fma_f32 v[4:5], v[4:5], v[172:173], v[202:203] op_sel_hi:[1,0,1]
	v_pk_fma_f32 v[6:7], v[6:7], v[172:173], v[204:205] op_sel_hi:[1,0,1]
	v_pk_fma_f32 v[8:9], v[8:9], v[172:173], v[206:207] op_sel_hi:[1,0,1]
	v_pk_fma_f32 v[10:11], v[10:11], v[172:173], v[208:209] op_sel_hi:[1,0,1]
	v_pk_fma_f32 v[12:13], v[12:13], v[172:173], v[210:211] op_sel_hi:[1,0,1]
	v_pk_fma_f32 v[14:15], v[14:15], v[172:173], v[212:213] op_sel_hi:[1,0,1]
	v_pk_fma_f32 v[16:17], v[16:17], v[172:173], v[214:215] op_sel_hi:[1,0,1]
	v_pk_fma_f32 v[18:19], v[18:19], v[172:173], v[216:217] op_sel_hi:[1,0,1]
	v_pk_fma_f32 v[20:21], v[20:21], v[172:173], v[218:219] op_sel_hi:[1,0,1]
	v_pk_fma_f32 v[22:23], v[22:23], v[172:173], v[220:221] op_sel_hi:[1,0,1]
	v_pk_fma_f32 v[24:25], v[24:25], v[172:173], v[222:223] op_sel_hi:[1,0,1]
	v_pk_fma_f32 v[26:27], v[26:27], v[172:173], v[224:225] op_sel_hi:[1,0,1]
	v_pk_fma_f32 v[28:29], v[28:29], v[172:173], v[226:227] op_sel_hi:[1,0,1]
	v_pk_fma_f32 v[30:31], v[30:31], v[172:173], v[228:229] op_sel_hi:[1,0,1]
	v_exp_f32_e32 v0, v0
	v_exp_f32_e32 v1, v1
	v_exp_f32_e32 v2, v2
	v_exp_f32_e32 v3, v3
	v_exp_f32_e32 v4, v4
	v_exp_f32_e32 v5, v5
	v_exp_f32_e32 v6, v6
	v_exp_f32_e32 v7, v7
	v_exp_f32_e32 v8, v8
	v_exp_f32_e32 v9, v9
	v_exp_f32_e32 v10, v10
	v_exp_f32_e32 v11, v11
	v_exp_f32_e32 v12, v12
	v_exp_f32_e32 v13, v13
	v_exp_f32_e32 v14, v14
	v_exp_f32_e32 v15, v15
	v_exp_f32_e32 v16, v16
	v_exp_f32_e32 v17, v17
	v_exp_f32_e32 v18, v18
	v_exp_f32_e32 v19, v19
	v_exp_f32_e32 v20, v20
	v_exp_f32_e32 v21, v21
	v_exp_f32_e32 v22, v22
	v_exp_f32_e32 v23, v23
	v_exp_f32_e32 v24, v24
	v_exp_f32_e32 v25, v25
	v_exp_f32_e32 v26, v26
	v_exp_f32_e32 v27, v27
	v_exp_f32_e32 v28, v28
	v_exp_f32_e32 v29, v29
	v_exp_f32_e32 v30, v30
	v_exp_f32_e32 v31, v31
	v_pk_add_f32 v[0:1], v[0:1], 1.0 op_sel_hi:[1,0]
	v_pk_add_f32 v[2:3], v[2:3], 1.0 op_sel_hi:[1,0]
	v_pk_add_f32 v[4:5], v[4:5], 1.0 op_sel_hi:[1,0]
	v_pk_add_f32 v[6:7], v[6:7], 1.0 op_sel_hi:[1,0]
	v_pk_add_f32 v[8:9], v[8:9], 1.0 op_sel_hi:[1,0]
	v_pk_add_f32 v[10:11], v[10:11], 1.0 op_sel_hi:[1,0]
	v_pk_add_f32 v[12:13], v[12:13], 1.0 op_sel_hi:[1,0]
	v_pk_add_f32 v[14:15], v[14:15], 1.0 op_sel_hi:[1,0]
	v_pk_add_f32 v[16:17], v[16:17], 1.0 op_sel_hi:[1,0]
	v_pk_add_f32 v[18:19], v[18:19], 1.0 op_sel_hi:[1,0]
	v_pk_add_f32 v[20:21], v[20:21], 1.0 op_sel_hi:[1,0]
	v_pk_add_f32 v[22:23], v[22:23], 1.0 op_sel_hi:[1,0]
	v_pk_add_f32 v[24:25], v[24:25], 1.0 op_sel_hi:[1,0]
	v_pk_add_f32 v[26:27], v[26:27], 1.0 op_sel_hi:[1,0]
	v_pk_add_f32 v[28:29], v[28:29], 1.0 op_sel_hi:[1,0]
	v_pk_add_f32 v[30:31], v[30:31], 1.0 op_sel_hi:[1,0]
	v_rcp_f32_e32 v0, v0
	v_rcp_f32_e32 v1, v1
	v_rcp_f32_e32 v2, v2
	v_rcp_f32_e32 v3, v3
	v_rcp_f32_e32 v4, v4
	v_rcp_f32_e32 v5, v5
	v_rcp_f32_e32 v6, v6
	v_rcp_f32_e32 v7, v7
	v_rcp_f32_e32 v8, v8
	v_rcp_f32_e32 v9, v9
	v_rcp_f32_e32 v10, v10
	v_rcp_f32_e32 v11, v11
	v_rcp_f32_e32 v12, v12
	v_rcp_f32_e32 v13, v13
	v_rcp_f32_e32 v14, v14
	v_rcp_f32_e32 v15, v15
	v_rcp_f32_e32 v16, v16
	v_rcp_f32_e32 v17, v17
	v_rcp_f32_e32 v18, v18
	v_rcp_f32_e32 v19, v19
	v_rcp_f32_e32 v20, v20
	v_rcp_f32_e32 v21, v21
	v_rcp_f32_e32 v22, v22
	v_rcp_f32_e32 v23, v23
	v_rcp_f32_e32 v24, v24
	v_rcp_f32_e32 v25, v25
	v_rcp_f32_e32 v26, v26
	v_rcp_f32_e32 v27, v27
	v_rcp_f32_e32 v28, v28
	v_rcp_f32_e32 v29, v29
	v_rcp_f32_e32 v30, v30
	v_rcp_f32_e32 v31, v31
	s_nop 0
	v_cvt_pk_bf16_f32 v0, v0, v1
	v_cvt_pk_bf16_f32 v1, v2, v3
	v_cvt_pk_bf16_f32 v2, v4, v5
	v_cvt_pk_bf16_f32 v3, v6, v7
	v_cvt_pk_bf16_f32 v4, v8, v9
	v_cvt_pk_bf16_f32 v5, v10, v11
	v_cvt_pk_bf16_f32 v6, v12, v13
	v_cvt_pk_bf16_f32 v7, v14, v15
	v_cvt_pk_bf16_f32 v16, v16, v17
	v_cvt_pk_bf16_f32 v17, v18, v19
	v_cvt_pk_bf16_f32 v18, v20, v21
	v_cvt_pk_bf16_f32 v19, v22, v23
	v_cvt_pk_bf16_f32 v20, v24, v25
	v_cvt_pk_bf16_f32 v21, v26, v27
	v_cvt_pk_bf16_f32 v22, v28, v29
	v_cvt_pk_bf16_f32 v23, v30, v31
	v_permlane32_swap_b32_e32 v0, v2
	v_permlane32_swap_b32_e32 v1, v3
	v_permlane32_swap_b32_e32 v4, v6
	v_permlane32_swap_b32_e32 v5, v7
	v_permlane32_swap_b32_e32 v16, v18
	v_permlane32_swap_b32_e32 v17, v19
	v_permlane32_swap_b32_e32 v20, v22
	v_permlane32_swap_b32_e32 v21, v23
	s_nop 1
	s_mov_b32 vcc_lo, 0x55555555
	s_mov_b32 vcc_hi, 0x55555555
	v_cndmask_b32_dpp v128, v4, v0, vcc quad_perm:[1,0,3,2] row_mask:0xf bank_mask:0xf
	v_cndmask_b32_dpp v129, v5, v1, vcc quad_perm:[1,0,3,2] row_mask:0xf bank_mask:0xf
	v_cndmask_b32_dpp v130, v6, v2, vcc quad_perm:[1,0,3,2] row_mask:0xf bank_mask:0xf
	v_cndmask_b32_dpp v131, v7, v3, vcc quad_perm:[1,0,3,2] row_mask:0xf bank_mask:0xf
	v_cndmask_b32_dpp v136, v20, v16, vcc quad_perm:[1,0,3,2] row_mask:0xf bank_mask:0xf
	v_cndmask_b32_dpp v137, v21, v17, vcc quad_perm:[1,0,3,2] row_mask:0xf bank_mask:0xf
	v_cndmask_b32_dpp v138, v22, v18, vcc quad_perm:[1,0,3,2] row_mask:0xf bank_mask:0xf
	v_cndmask_b32_dpp v139, v23, v19, vcc quad_perm:[1,0,3,2] row_mask:0xf bank_mask:0xf
	s_mov_b32 vcc_lo, 0xaaaaaaaa
	s_mov_b32 vcc_hi, 0xaaaaaaaa
	v_cndmask_b32_dpp v132, v0, v4, vcc quad_perm:[1,0,3,2] row_mask:0xf bank_mask:0xf
	v_cndmask_b32_dpp v133, v1, v5, vcc quad_perm:[1,0,3,2] row_mask:0xf bank_mask:0xf
	v_cndmask_b32_dpp v134, v2, v6, vcc quad_perm:[1,0,3,2] row_mask:0xf bank_mask:0xf
	v_cndmask_b32_dpp v135, v3, v7, vcc quad_perm:[1,0,3,2] row_mask:0xf bank_mask:0xf
	v_cndmask_b32_dpp v140, v16, v20, vcc quad_perm:[1,0,3,2] row_mask:0xf bank_mask:0xf
	v_cndmask_b32_dpp v141, v17, v21, vcc quad_perm:[1,0,3,2] row_mask:0xf bank_mask:0xf
	v_cndmask_b32_dpp v142, v18, v22, vcc quad_perm:[1,0,3,2] row_mask:0xf bank_mask:0xf
	v_cndmask_b32_dpp v143, v19, v23, vcc quad_perm:[1,0,3,2] row_mask:0xf bank_mask:0xf
	s_nop 1
	s_mov_b32 vcc_lo, 0x33333333
	s_mov_b32 vcc_hi, 0x33333333
	v_cndmask_b32_dpp v0, v136, v128, vcc quad_perm:[2,3,0,1] row_mask:0xf bank_mask:0xf
	v_cndmask_b32_dpp v1, v137, v129, vcc quad_perm:[2,3,0,1] row_mask:0xf bank_mask:0xf
	v_cndmask_b32_dpp v2, v138, v130, vcc quad_perm:[2,3,0,1] row_mask:0xf bank_mask:0xf
	v_cndmask_b32_dpp v3, v139, v131, vcc quad_perm:[2,3,0,1] row_mask:0xf bank_mask:0xf
	v_cndmask_b32_dpp v4, v140, v132, vcc quad_perm:[2,3,0,1] row_mask:0xf bank_mask:0xf
	v_cndmask_b32_dpp v5, v141, v133, vcc quad_perm:[2,3,0,1] row_mask:0xf bank_mask:0xf
	v_cndmask_b32_dpp v6, v142, v134, vcc quad_perm:[2,3,0,1] row_mask:0xf bank_mask:0xf
	v_cndmask_b32_dpp v7, v143, v135, vcc quad_perm:[2,3,0,1] row_mask:0xf bank_mask:0xf
	s_mov_b32 vcc_lo, 0xcccccccc
	s_mov_b32 vcc_hi, 0xcccccccc
	v_cndmask_b32_dpp v16, v128, v136, vcc quad_perm:[2,3,0,1] row_mask:0xf bank_mask:0xf
	v_cndmask_b32_dpp v17, v129, v137, vcc quad_perm:[2,3,0,1] row_mask:0xf bank_mask:0xf
	v_cndmask_b32_dpp v18, v130, v138, vcc quad_perm:[2,3,0,1] row_mask:0xf bank_mask:0xf
	v_cndmask_b32_dpp v19, v131, v139, vcc quad_perm:[2,3,0,1] row_mask:0xf bank_mask:0xf
	v_cndmask_b32_dpp v20, v132, v140, vcc quad_perm:[2,3,0,1] row_mask:0xf bank_mask:0xf
	v_cndmask_b32_dpp v21, v133, v141, vcc quad_perm:[2,3,0,1] row_mask:0xf bank_mask:0xf
	v_cndmask_b32_dpp v22, v134, v142, vcc quad_perm:[2,3,0,1] row_mask:0xf bank_mask:0xf
	v_cndmask_b32_dpp v23, v135, v143, vcc quad_perm:[2,3,0,1] row_mask:0xf bank_mask:0xf
	s_add_u32 s76, s74, 0x0
	s_addc_u32 s77, s75, 0
	global_store_dwordx4 v181, v[0:3], s[76:77]
	s_add_u32 s76, s74, 0x2200
	s_addc_u32 s77, s75, 0
	global_store_dwordx4 v181, v[4:7], s[76:77]
	s_add_u32 s76, s74, 0x4400
	s_addc_u32 s77, s75, 0
	global_store_dwordx4 v181, v[16:19], s[76:77]
	s_add_u32 s76, s74, 0x6600
	s_addc_u32 s77, s75, 0
	global_store_dwordx4 v181, v[20:23], s[76:77]
	s_add_u32 s74, s74, 0x44000
	s_addc_u32 s75, s75, 0
	v_pk_fma_f32 v[32:33], v[32:33], v[172:173], v[198:199] op_sel:[0,1,0] op_sel_hi:[1,1,1]
	v_pk_fma_f32 v[34:35], v[34:35], v[172:173], v[200:201] op_sel:[0,1,0] op_sel_hi:[1,1,1]
	v_pk_fma_f32 v[36:37], v[36:37], v[172:173], v[202:203] op_sel:[0,1,0] op_sel_hi:[1,1,1]
	v_pk_fma_f32 v[38:39], v[38:39], v[172:173], v[204:205] op_sel:[0,1,0] op_sel_hi:[1,1,1]
	v_pk_fma_f32 v[40:41], v[40:41], v[172:173], v[206:207] op_sel:[0,1,0] op_sel_hi:[1,1,1]
	v_pk_fma_f32 v[42:43], v[42:43], v[172:173], v[208:209] op_sel:[0,1,0] op_sel_hi:[1,1,1]
	v_pk_fma_f32 v[44:45], v[44:45], v[172:173], v[210:211] op_sel:[0,1,0] op_sel_hi:[1,1,1]
	v_pk_fma_f32 v[46:47], v[46:47], v[172:173], v[212:213] op_sel:[0,1,0] op_sel_hi:[1,1,1]
	v_pk_fma_f32 v[48:49], v[48:49], v[172:173], v[214:215] op_sel:[0,1,0] op_sel_hi:[1,1,1]
	v_pk_fma_f32 v[50:51], v[50:51], v[172:173], v[216:217] op_sel:[0,1,0] op_sel_hi:[1,1,1]
	v_pk_fma_f32 v[52:53], v[52:53], v[172:173], v[218:219] op_sel:[0,1,0] op_sel_hi:[1,1,1]
	v_pk_fma_f32 v[54:55], v[54:55], v[172:173], v[220:221] op_sel:[0,1,0] op_sel_hi:[1,1,1]
	v_pk_fma_f32 v[56:57], v[56:57], v[172:173], v[222:223] op_sel:[0,1,0] op_sel_hi:[1,1,1]
	v_pk_fma_f32 v[58:59], v[58:59], v[172:173], v[224:225] op_sel:[0,1,0] op_sel_hi:[1,1,1]
	v_pk_fma_f32 v[60:61], v[60:61], v[172:173], v[226:227] op_sel:[0,1,0] op_sel_hi:[1,1,1]
	v_pk_fma_f32 v[62:63], v[62:63], v[172:173], v[228:229] op_sel:[0,1,0] op_sel_hi:[1,1,1]
	v_exp_f32_e32 v32, v32
	v_exp_f32_e32 v33, v33
	v_exp_f32_e32 v34, v34
	v_exp_f32_e32 v35, v35
	v_exp_f32_e32 v36, v36
	v_exp_f32_e32 v37, v37
	v_exp_f32_e32 v38, v38
	v_exp_f32_e32 v39, v39
	v_exp_f32_e32 v40, v40
	v_exp_f32_e32 v41, v41
	v_exp_f32_e32 v42, v42
	v_exp_f32_e32 v43, v43
	v_exp_f32_e32 v44, v44
	v_exp_f32_e32 v45, v45
	v_exp_f32_e32 v46, v46
	v_exp_f32_e32 v47, v47
	v_exp_f32_e32 v48, v48
	v_exp_f32_e32 v49, v49
	v_exp_f32_e32 v50, v50
	v_exp_f32_e32 v51, v51
	v_exp_f32_e32 v52, v52
	v_exp_f32_e32 v53, v53
	v_exp_f32_e32 v54, v54
	v_exp_f32_e32 v55, v55
	v_exp_f32_e32 v56, v56
	v_exp_f32_e32 v57, v57
	v_exp_f32_e32 v58, v58
	v_exp_f32_e32 v59, v59
	v_exp_f32_e32 v60, v60
	v_exp_f32_e32 v61, v61
	v_exp_f32_e32 v62, v62
	v_exp_f32_e32 v63, v63
	v_pk_add_f32 v[32:33], v[32:33], 1.0 op_sel_hi:[1,0]
	v_pk_add_f32 v[34:35], v[34:35], 1.0 op_sel_hi:[1,0]
	v_pk_add_f32 v[36:37], v[36:37], 1.0 op_sel_hi:[1,0]
	v_pk_add_f32 v[38:39], v[38:39], 1.0 op_sel_hi:[1,0]
	v_pk_add_f32 v[40:41], v[40:41], 1.0 op_sel_hi:[1,0]
	v_pk_add_f32 v[42:43], v[42:43], 1.0 op_sel_hi:[1,0]
	v_pk_add_f32 v[44:45], v[44:45], 1.0 op_sel_hi:[1,0]
	v_pk_add_f32 v[46:47], v[46:47], 1.0 op_sel_hi:[1,0]
	v_pk_add_f32 v[48:49], v[48:49], 1.0 op_sel_hi:[1,0]
	v_pk_add_f32 v[50:51], v[50:51], 1.0 op_sel_hi:[1,0]
	v_pk_add_f32 v[52:53], v[52:53], 1.0 op_sel_hi:[1,0]
	v_pk_add_f32 v[54:55], v[54:55], 1.0 op_sel_hi:[1,0]
	v_pk_add_f32 v[56:57], v[56:57], 1.0 op_sel_hi:[1,0]
	v_pk_add_f32 v[58:59], v[58:59], 1.0 op_sel_hi:[1,0]
	v_pk_add_f32 v[60:61], v[60:61], 1.0 op_sel_hi:[1,0]
	v_pk_add_f32 v[62:63], v[62:63], 1.0 op_sel_hi:[1,0]
	v_rcp_f32_e32 v32, v32
	v_rcp_f32_e32 v33, v33
	v_rcp_f32_e32 v34, v34
	v_rcp_f32_e32 v35, v35
	v_rcp_f32_e32 v36, v36
	v_rcp_f32_e32 v37, v37
	v_rcp_f32_e32 v38, v38
	v_rcp_f32_e32 v39, v39
	v_rcp_f32_e32 v40, v40
	v_rcp_f32_e32 v41, v41
	v_rcp_f32_e32 v42, v42
	v_rcp_f32_e32 v43, v43
	v_rcp_f32_e32 v44, v44
	v_rcp_f32_e32 v45, v45
	v_rcp_f32_e32 v46, v46
	v_rcp_f32_e32 v47, v47
	v_rcp_f32_e32 v48, v48
	v_rcp_f32_e32 v49, v49
	v_rcp_f32_e32 v50, v50
	v_rcp_f32_e32 v51, v51
	v_rcp_f32_e32 v52, v52
	v_rcp_f32_e32 v53, v53
	v_rcp_f32_e32 v54, v54
	v_rcp_f32_e32 v55, v55
	v_rcp_f32_e32 v56, v56
	v_rcp_f32_e32 v57, v57
	v_rcp_f32_e32 v58, v58
	v_rcp_f32_e32 v59, v59
	v_rcp_f32_e32 v60, v60
	v_rcp_f32_e32 v61, v61
	v_rcp_f32_e32 v62, v62
	v_rcp_f32_e32 v63, v63
	s_nop 0
	v_cvt_pk_bf16_f32 v32, v32, v33
	v_cvt_pk_bf16_f32 v33, v34, v35
	v_cvt_pk_bf16_f32 v34, v36, v37
	v_cvt_pk_bf16_f32 v35, v38, v39
	v_cvt_pk_bf16_f32 v36, v40, v41
	v_cvt_pk_bf16_f32 v37, v42, v43
	v_cvt_pk_bf16_f32 v38, v44, v45
	v_cvt_pk_bf16_f32 v39, v46, v47
	v_cvt_pk_bf16_f32 v48, v48, v49
	v_cvt_pk_bf16_f32 v49, v50, v51
	v_cvt_pk_bf16_f32 v50, v52, v53
	v_cvt_pk_bf16_f32 v51, v54, v55
	v_cvt_pk_bf16_f32 v52, v56, v57
	v_cvt_pk_bf16_f32 v53, v58, v59
	v_cvt_pk_bf16_f32 v54, v60, v61
	v_cvt_pk_bf16_f32 v55, v62, v63
	v_permlane32_swap_b32_e32 v32, v34
	v_permlane32_swap_b32_e32 v33, v35
	v_permlane32_swap_b32_e32 v36, v38
	v_permlane32_swap_b32_e32 v37, v39
	v_permlane32_swap_b32_e32 v48, v50
	v_permlane32_swap_b32_e32 v49, v51
	v_permlane32_swap_b32_e32 v52, v54
	v_permlane32_swap_b32_e32 v53, v55
	s_nop 1
	s_mov_b32 vcc_lo, 0x55555555
	s_mov_b32 vcc_hi, 0x55555555
	v_cndmask_b32_dpp v128, v36, v32, vcc quad_perm:[1,0,3,2] row_mask:0xf bank_mask:0xf
	v_cndmask_b32_dpp v129, v37, v33, vcc quad_perm:[1,0,3,2] row_mask:0xf bank_mask:0xf
	v_cndmask_b32_dpp v130, v38, v34, vcc quad_perm:[1,0,3,2] row_mask:0xf bank_mask:0xf
	v_cndmask_b32_dpp v131, v39, v35, vcc quad_perm:[1,0,3,2] row_mask:0xf bank_mask:0xf
	v_cndmask_b32_dpp v136, v52, v48, vcc quad_perm:[1,0,3,2] row_mask:0xf bank_mask:0xf
	v_cndmask_b32_dpp v137, v53, v49, vcc quad_perm:[1,0,3,2] row_mask:0xf bank_mask:0xf
	v_cndmask_b32_dpp v138, v54, v50, vcc quad_perm:[1,0,3,2] row_mask:0xf bank_mask:0xf
	v_cndmask_b32_dpp v139, v55, v51, vcc quad_perm:[1,0,3,2] row_mask:0xf bank_mask:0xf
	s_mov_b32 vcc_lo, 0xaaaaaaaa
	s_mov_b32 vcc_hi, 0xaaaaaaaa
	v_cndmask_b32_dpp v132, v32, v36, vcc quad_perm:[1,0,3,2] row_mask:0xf bank_mask:0xf
	v_cndmask_b32_dpp v133, v33, v37, vcc quad_perm:[1,0,3,2] row_mask:0xf bank_mask:0xf
	v_cndmask_b32_dpp v134, v34, v38, vcc quad_perm:[1,0,3,2] row_mask:0xf bank_mask:0xf
	v_cndmask_b32_dpp v135, v35, v39, vcc quad_perm:[1,0,3,2] row_mask:0xf bank_mask:0xf
	v_cndmask_b32_dpp v140, v48, v52, vcc quad_perm:[1,0,3,2] row_mask:0xf bank_mask:0xf
	v_cndmask_b32_dpp v141, v49, v53, vcc quad_perm:[1,0,3,2] row_mask:0xf bank_mask:0xf
	v_cndmask_b32_dpp v142, v50, v54, vcc quad_perm:[1,0,3,2] row_mask:0xf bank_mask:0xf
	v_cndmask_b32_dpp v143, v51, v55, vcc quad_perm:[1,0,3,2] row_mask:0xf bank_mask:0xf
	s_nop 1
	s_mov_b32 vcc_lo, 0x33333333
	s_mov_b32 vcc_hi, 0x33333333
	v_cndmask_b32_dpp v32, v136, v128, vcc quad_perm:[2,3,0,1] row_mask:0xf bank_mask:0xf
	v_cndmask_b32_dpp v33, v137, v129, vcc quad_perm:[2,3,0,1] row_mask:0xf bank_mask:0xf
	v_cndmask_b32_dpp v34, v138, v130, vcc quad_perm:[2,3,0,1] row_mask:0xf bank_mask:0xf
	v_cndmask_b32_dpp v35, v139, v131, vcc quad_perm:[2,3,0,1] row_mask:0xf bank_mask:0xf
	v_cndmask_b32_dpp v36, v140, v132, vcc quad_perm:[2,3,0,1] row_mask:0xf bank_mask:0xf
	v_cndmask_b32_dpp v37, v141, v133, vcc quad_perm:[2,3,0,1] row_mask:0xf bank_mask:0xf
	v_cndmask_b32_dpp v38, v142, v134, vcc quad_perm:[2,3,0,1] row_mask:0xf bank_mask:0xf
	v_cndmask_b32_dpp v39, v143, v135, vcc quad_perm:[2,3,0,1] row_mask:0xf bank_mask:0xf
	s_mov_b32 vcc_lo, 0xcccccccc
	s_mov_b32 vcc_hi, 0xcccccccc
	v_cndmask_b32_dpp v48, v128, v136, vcc quad_perm:[2,3,0,1] row_mask:0xf bank_mask:0xf
	v_cndmask_b32_dpp v49, v129, v137, vcc quad_perm:[2,3,0,1] row_mask:0xf bank_mask:0xf
	v_cndmask_b32_dpp v50, v130, v138, vcc quad_perm:[2,3,0,1] row_mask:0xf bank_mask:0xf
	v_cndmask_b32_dpp v51, v131, v139, vcc quad_perm:[2,3,0,1] row_mask:0xf bank_mask:0xf
	v_cndmask_b32_dpp v52, v132, v140, vcc quad_perm:[2,3,0,1] row_mask:0xf bank_mask:0xf
	v_cndmask_b32_dpp v53, v133, v141, vcc quad_perm:[2,3,0,1] row_mask:0xf bank_mask:0xf
	v_cndmask_b32_dpp v54, v134, v142, vcc quad_perm:[2,3,0,1] row_mask:0xf bank_mask:0xf
	v_cndmask_b32_dpp v55, v135, v143, vcc quad_perm:[2,3,0,1] row_mask:0xf bank_mask:0xf
	s_add_u32 s76, s74, 0x0
	s_addc_u32 s77, s75, 0
	global_store_dwordx4 v181, v[32:35], s[76:77]
	s_add_u32 s76, s74, 0x2200
	s_addc_u32 s77, s75, 0
	global_store_dwordx4 v181, v[36:39], s[76:77]
	s_add_u32 s76, s74, 0x4400
	s_addc_u32 s77, s75, 0
	global_store_dwordx4 v181, v[48:51], s[76:77]
	s_add_u32 s76, s74, 0x6600
	s_addc_u32 s77, s75, 0
	global_store_dwordx4 v181, v[52:55], s[76:77]
	s_add_u32 s74, s74, 0x44000
	s_addc_u32 s75, s75, 0
	v_pk_fma_f32 v[64:65], v[64:65], v[174:175], v[198:199] op_sel_hi:[1,0,1]
	v_pk_fma_f32 v[66:67], v[66:67], v[174:175], v[200:201] op_sel_hi:[1,0,1]
	v_pk_fma_f32 v[68:69], v[68:69], v[174:175], v[202:203] op_sel_hi:[1,0,1]
	v_pk_fma_f32 v[70:71], v[70:71], v[174:175], v[204:205] op_sel_hi:[1,0,1]
	v_pk_fma_f32 v[72:73], v[72:73], v[174:175], v[206:207] op_sel_hi:[1,0,1]
	v_pk_fma_f32 v[74:75], v[74:75], v[174:175], v[208:209] op_sel_hi:[1,0,1]
	v_pk_fma_f32 v[76:77], v[76:77], v[174:175], v[210:211] op_sel_hi:[1,0,1]
	v_pk_fma_f32 v[78:79], v[78:79], v[174:175], v[212:213] op_sel_hi:[1,0,1]
	v_pk_fma_f32 v[80:81], v[80:81], v[174:175], v[214:215] op_sel_hi:[1,0,1]
	v_pk_fma_f32 v[82:83], v[82:83], v[174:175], v[216:217] op_sel_hi:[1,0,1]
	v_pk_fma_f32 v[84:85], v[84:85], v[174:175], v[218:219] op_sel_hi:[1,0,1]
	v_pk_fma_f32 v[86:87], v[86:87], v[174:175], v[220:221] op_sel_hi:[1,0,1]
	v_pk_fma_f32 v[88:89], v[88:89], v[174:175], v[222:223] op_sel_hi:[1,0,1]
	v_pk_fma_f32 v[90:91], v[90:91], v[174:175], v[224:225] op_sel_hi:[1,0,1]
	v_pk_fma_f32 v[92:93], v[92:93], v[174:175], v[226:227] op_sel_hi:[1,0,1]
	v_pk_fma_f32 v[94:95], v[94:95], v[174:175], v[228:229] op_sel_hi:[1,0,1]
	v_exp_f32_e32 v64, v64
	v_exp_f32_e32 v65, v65
	v_exp_f32_e32 v66, v66
	v_exp_f32_e32 v67, v67
	v_exp_f32_e32 v68, v68
	v_exp_f32_e32 v69, v69
	v_exp_f32_e32 v70, v70
	v_exp_f32_e32 v71, v71
	v_exp_f32_e32 v72, v72
	v_exp_f32_e32 v73, v73
	v_exp_f32_e32 v74, v74
	v_exp_f32_e32 v75, v75
	v_exp_f32_e32 v76, v76
	v_exp_f32_e32 v77, v77
	v_exp_f32_e32 v78, v78
	v_exp_f32_e32 v79, v79
	v_exp_f32_e32 v80, v80
	v_exp_f32_e32 v81, v81
	v_exp_f32_e32 v82, v82
	v_exp_f32_e32 v83, v83
	v_exp_f32_e32 v84, v84
	v_exp_f32_e32 v85, v85
	v_exp_f32_e32 v86, v86
	v_exp_f32_e32 v87, v87
	v_exp_f32_e32 v88, v88
	v_exp_f32_e32 v89, v89
	v_exp_f32_e32 v90, v90
	v_exp_f32_e32 v91, v91
	v_exp_f32_e32 v92, v92
	v_exp_f32_e32 v93, v93
	v_exp_f32_e32 v94, v94
	v_exp_f32_e32 v95, v95
	v_pk_add_f32 v[64:65], v[64:65], 1.0 op_sel_hi:[1,0]
	v_pk_add_f32 v[66:67], v[66:67], 1.0 op_sel_hi:[1,0]
	v_pk_add_f32 v[68:69], v[68:69], 1.0 op_sel_hi:[1,0]
	v_pk_add_f32 v[70:71], v[70:71], 1.0 op_sel_hi:[1,0]
	v_pk_add_f32 v[72:73], v[72:73], 1.0 op_sel_hi:[1,0]
	v_pk_add_f32 v[74:75], v[74:75], 1.0 op_sel_hi:[1,0]
	v_pk_add_f32 v[76:77], v[76:77], 1.0 op_sel_hi:[1,0]
	v_pk_add_f32 v[78:79], v[78:79], 1.0 op_sel_hi:[1,0]
	v_pk_add_f32 v[80:81], v[80:81], 1.0 op_sel_hi:[1,0]
	v_pk_add_f32 v[82:83], v[82:83], 1.0 op_sel_hi:[1,0]
	v_pk_add_f32 v[84:85], v[84:85], 1.0 op_sel_hi:[1,0]
	v_pk_add_f32 v[86:87], v[86:87], 1.0 op_sel_hi:[1,0]
	v_pk_add_f32 v[88:89], v[88:89], 1.0 op_sel_hi:[1,0]
	v_pk_add_f32 v[90:91], v[90:91], 1.0 op_sel_hi:[1,0]
	v_pk_add_f32 v[92:93], v[92:93], 1.0 op_sel_hi:[1,0]
	v_pk_add_f32 v[94:95], v[94:95], 1.0 op_sel_hi:[1,0]
	v_rcp_f32_e32 v64, v64
	v_rcp_f32_e32 v65, v65
	v_rcp_f32_e32 v66, v66
	v_rcp_f32_e32 v67, v67
	v_rcp_f32_e32 v68, v68
	v_rcp_f32_e32 v69, v69
	v_rcp_f32_e32 v70, v70
	v_rcp_f32_e32 v71, v71
	v_rcp_f32_e32 v72, v72
	v_rcp_f32_e32 v73, v73
	v_rcp_f32_e32 v74, v74
	v_rcp_f32_e32 v75, v75
	v_rcp_f32_e32 v76, v76
	v_rcp_f32_e32 v77, v77
	v_rcp_f32_e32 v78, v78
	v_rcp_f32_e32 v79, v79
	v_rcp_f32_e32 v80, v80
	v_rcp_f32_e32 v81, v81
	v_rcp_f32_e32 v82, v82
	v_rcp_f32_e32 v83, v83
	v_rcp_f32_e32 v84, v84
	v_rcp_f32_e32 v85, v85
	v_rcp_f32_e32 v86, v86
	v_rcp_f32_e32 v87, v87
	v_rcp_f32_e32 v88, v88
	v_rcp_f32_e32 v89, v89
	v_rcp_f32_e32 v90, v90
	v_rcp_f32_e32 v91, v91
	v_rcp_f32_e32 v92, v92
	v_rcp_f32_e32 v93, v93
	v_rcp_f32_e32 v94, v94
	v_rcp_f32_e32 v95, v95
	s_nop 0
	v_cvt_pk_bf16_f32 v64, v64, v65
	v_cvt_pk_bf16_f32 v65, v66, v67
	v_cvt_pk_bf16_f32 v66, v68, v69
	v_cvt_pk_bf16_f32 v67, v70, v71
	v_cvt_pk_bf16_f32 v68, v72, v73
	v_cvt_pk_bf16_f32 v69, v74, v75
	v_cvt_pk_bf16_f32 v70, v76, v77
	v_cvt_pk_bf16_f32 v71, v78, v79
	v_cvt_pk_bf16_f32 v80, v80, v81
	v_cvt_pk_bf16_f32 v81, v82, v83
	v_cvt_pk_bf16_f32 v82, v84, v85
	v_cvt_pk_bf16_f32 v83, v86, v87
	v_cvt_pk_bf16_f32 v84, v88, v89
	v_cvt_pk_bf16_f32 v85, v90, v91
	v_cvt_pk_bf16_f32 v86, v92, v93
	v_cvt_pk_bf16_f32 v87, v94, v95
	v_permlane32_swap_b32_e32 v64, v66
	v_permlane32_swap_b32_e32 v65, v67
	v_permlane32_swap_b32_e32 v68, v70
	v_permlane32_swap_b32_e32 v69, v71
	v_permlane32_swap_b32_e32 v80, v82
	v_permlane32_swap_b32_e32 v81, v83
	v_permlane32_swap_b32_e32 v84, v86
	v_permlane32_swap_b32_e32 v85, v87
	s_nop 1
	s_mov_b32 vcc_lo, 0x55555555
	s_mov_b32 vcc_hi, 0x55555555
	v_cndmask_b32_dpp v128, v68, v64, vcc quad_perm:[1,0,3,2] row_mask:0xf bank_mask:0xf
	v_cndmask_b32_dpp v129, v69, v65, vcc quad_perm:[1,0,3,2] row_mask:0xf bank_mask:0xf
	v_cndmask_b32_dpp v130, v70, v66, vcc quad_perm:[1,0,3,2] row_mask:0xf bank_mask:0xf
	v_cndmask_b32_dpp v131, v71, v67, vcc quad_perm:[1,0,3,2] row_mask:0xf bank_mask:0xf
	v_cndmask_b32_dpp v136, v84, v80, vcc quad_perm:[1,0,3,2] row_mask:0xf bank_mask:0xf
	v_cndmask_b32_dpp v137, v85, v81, vcc quad_perm:[1,0,3,2] row_mask:0xf bank_mask:0xf
	v_cndmask_b32_dpp v138, v86, v82, vcc quad_perm:[1,0,3,2] row_mask:0xf bank_mask:0xf
	v_cndmask_b32_dpp v139, v87, v83, vcc quad_perm:[1,0,3,2] row_mask:0xf bank_mask:0xf
	s_mov_b32 vcc_lo, 0xaaaaaaaa
	s_mov_b32 vcc_hi, 0xaaaaaaaa
	v_cndmask_b32_dpp v132, v64, v68, vcc quad_perm:[1,0,3,2] row_mask:0xf bank_mask:0xf
	v_cndmask_b32_dpp v133, v65, v69, vcc quad_perm:[1,0,3,2] row_mask:0xf bank_mask:0xf
	v_cndmask_b32_dpp v134, v66, v70, vcc quad_perm:[1,0,3,2] row_mask:0xf bank_mask:0xf
	v_cndmask_b32_dpp v135, v67, v71, vcc quad_perm:[1,0,3,2] row_mask:0xf bank_mask:0xf
	v_cndmask_b32_dpp v140, v80, v84, vcc quad_perm:[1,0,3,2] row_mask:0xf bank_mask:0xf
	v_cndmask_b32_dpp v141, v81, v85, vcc quad_perm:[1,0,3,2] row_mask:0xf bank_mask:0xf
	v_cndmask_b32_dpp v142, v82, v86, vcc quad_perm:[1,0,3,2] row_mask:0xf bank_mask:0xf
	v_cndmask_b32_dpp v143, v83, v87, vcc quad_perm:[1,0,3,2] row_mask:0xf bank_mask:0xf
	s_nop 1
	s_mov_b32 vcc_lo, 0x33333333
	s_mov_b32 vcc_hi, 0x33333333
	v_cndmask_b32_dpp v64, v136, v128, vcc quad_perm:[2,3,0,1] row_mask:0xf bank_mask:0xf
	v_cndmask_b32_dpp v65, v137, v129, vcc quad_perm:[2,3,0,1] row_mask:0xf bank_mask:0xf
	v_cndmask_b32_dpp v66, v138, v130, vcc quad_perm:[2,3,0,1] row_mask:0xf bank_mask:0xf
	v_cndmask_b32_dpp v67, v139, v131, vcc quad_perm:[2,3,0,1] row_mask:0xf bank_mask:0xf
	v_cndmask_b32_dpp v68, v140, v132, vcc quad_perm:[2,3,0,1] row_mask:0xf bank_mask:0xf
	v_cndmask_b32_dpp v69, v141, v133, vcc quad_perm:[2,3,0,1] row_mask:0xf bank_mask:0xf
	v_cndmask_b32_dpp v70, v142, v134, vcc quad_perm:[2,3,0,1] row_mask:0xf bank_mask:0xf
	v_cndmask_b32_dpp v71, v143, v135, vcc quad_perm:[2,3,0,1] row_mask:0xf bank_mask:0xf
	s_mov_b32 vcc_lo, 0xcccccccc
	s_mov_b32 vcc_hi, 0xcccccccc
	v_cndmask_b32_dpp v80, v128, v136, vcc quad_perm:[2,3,0,1] row_mask:0xf bank_mask:0xf
	v_cndmask_b32_dpp v81, v129, v137, vcc quad_perm:[2,3,0,1] row_mask:0xf bank_mask:0xf
	v_cndmask_b32_dpp v82, v130, v138, vcc quad_perm:[2,3,0,1] row_mask:0xf bank_mask:0xf
	v_cndmask_b32_dpp v83, v131, v139, vcc quad_perm:[2,3,0,1] row_mask:0xf bank_mask:0xf
	v_cndmask_b32_dpp v84, v132, v140, vcc quad_perm:[2,3,0,1] row_mask:0xf bank_mask:0xf
	v_cndmask_b32_dpp v85, v133, v141, vcc quad_perm:[2,3,0,1] row_mask:0xf bank_mask:0xf
	v_cndmask_b32_dpp v86, v134, v142, vcc quad_perm:[2,3,0,1] row_mask:0xf bank_mask:0xf
	v_cndmask_b32_dpp v87, v135, v143, vcc quad_perm:[2,3,0,1] row_mask:0xf bank_mask:0xf
	s_add_u32 s76, s74, 0x0
	s_addc_u32 s77, s75, 0
	global_store_dwordx4 v181, v[64:67], s[76:77]
	s_add_u32 s76, s74, 0x2200
	s_addc_u32 s77, s75, 0
	global_store_dwordx4 v181, v[68:71], s[76:77]
	s_add_u32 s76, s74, 0x4400
	s_addc_u32 s77, s75, 0
	global_store_dwordx4 v181, v[80:83], s[76:77]
	s_add_u32 s76, s74, 0x6600
	s_addc_u32 s77, s75, 0
	global_store_dwordx4 v181, v[84:87], s[76:77]
	s_add_u32 s74, s74, 0x44000
	s_addc_u32 s75, s75, 0
	v_pk_fma_f32 v[96:97], v[96:97], v[174:175], v[198:199] op_sel:[0,1,0] op_sel_hi:[1,1,1]
	v_pk_fma_f32 v[98:99], v[98:99], v[174:175], v[200:201] op_sel:[0,1,0] op_sel_hi:[1,1,1]
	v_pk_fma_f32 v[100:101], v[100:101], v[174:175], v[202:203] op_sel:[0,1,0] op_sel_hi:[1,1,1]
	v_pk_fma_f32 v[102:103], v[102:103], v[174:175], v[204:205] op_sel:[0,1,0] op_sel_hi:[1,1,1]
	v_pk_fma_f32 v[104:105], v[104:105], v[174:175], v[206:207] op_sel:[0,1,0] op_sel_hi:[1,1,1]
	v_pk_fma_f32 v[106:107], v[106:107], v[174:175], v[208:209] op_sel:[0,1,0] op_sel_hi:[1,1,1]
	v_pk_fma_f32 v[108:109], v[108:109], v[174:175], v[210:211] op_sel:[0,1,0] op_sel_hi:[1,1,1]
	v_pk_fma_f32 v[110:111], v[110:111], v[174:175], v[212:213] op_sel:[0,1,0] op_sel_hi:[1,1,1]
	v_pk_fma_f32 v[112:113], v[112:113], v[174:175], v[214:215] op_sel:[0,1,0] op_sel_hi:[1,1,1]
	v_pk_fma_f32 v[114:115], v[114:115], v[174:175], v[216:217] op_sel:[0,1,0] op_sel_hi:[1,1,1]
	v_pk_fma_f32 v[116:117], v[116:117], v[174:175], v[218:219] op_sel:[0,1,0] op_sel_hi:[1,1,1]
	v_pk_fma_f32 v[118:119], v[118:119], v[174:175], v[220:221] op_sel:[0,1,0] op_sel_hi:[1,1,1]
	v_pk_fma_f32 v[120:121], v[120:121], v[174:175], v[222:223] op_sel:[0,1,0] op_sel_hi:[1,1,1]
	v_pk_fma_f32 v[122:123], v[122:123], v[174:175], v[224:225] op_sel:[0,1,0] op_sel_hi:[1,1,1]
	v_pk_fma_f32 v[124:125], v[124:125], v[174:175], v[226:227] op_sel:[0,1,0] op_sel_hi:[1,1,1]
	v_pk_fma_f32 v[126:127], v[126:127], v[174:175], v[228:229] op_sel:[0,1,0] op_sel_hi:[1,1,1]
	v_exp_f32_e32 v96, v96
	v_exp_f32_e32 v97, v97
	v_exp_f32_e32 v98, v98
	v_exp_f32_e32 v99, v99
	v_exp_f32_e32 v100, v100
	v_exp_f32_e32 v101, v101
	v_exp_f32_e32 v102, v102
	v_exp_f32_e32 v103, v103
	v_exp_f32_e32 v104, v104
	v_exp_f32_e32 v105, v105
	v_exp_f32_e32 v106, v106
	v_exp_f32_e32 v107, v107
	v_exp_f32_e32 v108, v108
	v_exp_f32_e32 v109, v109
	v_exp_f32_e32 v110, v110
	v_exp_f32_e32 v111, v111
	v_exp_f32_e32 v112, v112
	v_exp_f32_e32 v113, v113
	v_exp_f32_e32 v114, v114
	v_exp_f32_e32 v115, v115
	v_exp_f32_e32 v116, v116
	v_exp_f32_e32 v117, v117
	v_exp_f32_e32 v118, v118
	v_exp_f32_e32 v119, v119
	v_exp_f32_e32 v120, v120
	v_exp_f32_e32 v121, v121
	v_exp_f32_e32 v122, v122
	v_exp_f32_e32 v123, v123
	v_exp_f32_e32 v124, v124
	v_exp_f32_e32 v125, v125
	v_exp_f32_e32 v126, v126
	v_exp_f32_e32 v127, v127
	v_pk_add_f32 v[96:97], v[96:97], 1.0 op_sel_hi:[1,0]
	v_pk_add_f32 v[98:99], v[98:99], 1.0 op_sel_hi:[1,0]
	v_pk_add_f32 v[100:101], v[100:101], 1.0 op_sel_hi:[1,0]
	v_pk_add_f32 v[102:103], v[102:103], 1.0 op_sel_hi:[1,0]
	v_pk_add_f32 v[104:105], v[104:105], 1.0 op_sel_hi:[1,0]
	v_pk_add_f32 v[106:107], v[106:107], 1.0 op_sel_hi:[1,0]
	v_pk_add_f32 v[108:109], v[108:109], 1.0 op_sel_hi:[1,0]
	v_pk_add_f32 v[110:111], v[110:111], 1.0 op_sel_hi:[1,0]
	v_pk_add_f32 v[112:113], v[112:113], 1.0 op_sel_hi:[1,0]
	v_pk_add_f32 v[114:115], v[114:115], 1.0 op_sel_hi:[1,0]
	v_pk_add_f32 v[116:117], v[116:117], 1.0 op_sel_hi:[1,0]
	v_pk_add_f32 v[118:119], v[118:119], 1.0 op_sel_hi:[1,0]
	v_pk_add_f32 v[120:121], v[120:121], 1.0 op_sel_hi:[1,0]
	v_pk_add_f32 v[122:123], v[122:123], 1.0 op_sel_hi:[1,0]
	v_pk_add_f32 v[124:125], v[124:125], 1.0 op_sel_hi:[1,0]
	v_pk_add_f32 v[126:127], v[126:127], 1.0 op_sel_hi:[1,0]
	v_rcp_f32_e32 v96, v96
	v_rcp_f32_e32 v97, v97
	v_rcp_f32_e32 v98, v98
	v_rcp_f32_e32 v99, v99
	v_rcp_f32_e32 v100, v100
	v_rcp_f32_e32 v101, v101
	v_rcp_f32_e32 v102, v102
	v_rcp_f32_e32 v103, v103
	v_rcp_f32_e32 v104, v104
	v_rcp_f32_e32 v105, v105
	v_rcp_f32_e32 v106, v106
	v_rcp_f32_e32 v107, v107
	v_rcp_f32_e32 v108, v108
	v_rcp_f32_e32 v109, v109
	v_rcp_f32_e32 v110, v110
	v_rcp_f32_e32 v111, v111
	v_rcp_f32_e32 v112, v112
	v_rcp_f32_e32 v113, v113
	v_rcp_f32_e32 v114, v114
	v_rcp_f32_e32 v115, v115
	v_rcp_f32_e32 v116, v116
	v_rcp_f32_e32 v117, v117
	v_rcp_f32_e32 v118, v118
	v_rcp_f32_e32 v119, v119
	v_rcp_f32_e32 v120, v120
	v_rcp_f32_e32 v121, v121
	v_rcp_f32_e32 v122, v122
	v_rcp_f32_e32 v123, v123
	v_rcp_f32_e32 v124, v124
	v_rcp_f32_e32 v125, v125
	v_rcp_f32_e32 v126, v126
	v_rcp_f32_e32 v127, v127
	s_nop 0
	v_cvt_pk_bf16_f32 v96, v96, v97
	v_cvt_pk_bf16_f32 v97, v98, v99
	v_cvt_pk_bf16_f32 v98, v100, v101
	v_cvt_pk_bf16_f32 v99, v102, v103
	v_cvt_pk_bf16_f32 v100, v104, v105
	v_cvt_pk_bf16_f32 v101, v106, v107
	v_cvt_pk_bf16_f32 v102, v108, v109
	v_cvt_pk_bf16_f32 v103, v110, v111
	v_cvt_pk_bf16_f32 v112, v112, v113
	v_cvt_pk_bf16_f32 v113, v114, v115
	v_cvt_pk_bf16_f32 v114, v116, v117
	v_cvt_pk_bf16_f32 v115, v118, v119
	v_cvt_pk_bf16_f32 v116, v120, v121
	v_cvt_pk_bf16_f32 v117, v122, v123
	v_cvt_pk_bf16_f32 v118, v124, v125
	v_cvt_pk_bf16_f32 v119, v126, v127
	v_permlane32_swap_b32_e32 v96, v98
	v_permlane32_swap_b32_e32 v97, v99
	v_permlane32_swap_b32_e32 v100, v102
	v_permlane32_swap_b32_e32 v101, v103
	v_permlane32_swap_b32_e32 v112, v114
	v_permlane32_swap_b32_e32 v113, v115
	v_permlane32_swap_b32_e32 v116, v118
	v_permlane32_swap_b32_e32 v117, v119
	s_nop 1
	s_mov_b32 vcc_lo, 0x55555555
	s_mov_b32 vcc_hi, 0x55555555
	v_cndmask_b32_dpp v128, v100, v96, vcc quad_perm:[1,0,3,2] row_mask:0xf bank_mask:0xf
	v_cndmask_b32_dpp v129, v101, v97, vcc quad_perm:[1,0,3,2] row_mask:0xf bank_mask:0xf
	v_cndmask_b32_dpp v130, v102, v98, vcc quad_perm:[1,0,3,2] row_mask:0xf bank_mask:0xf
	v_cndmask_b32_dpp v131, v103, v99, vcc quad_perm:[1,0,3,2] row_mask:0xf bank_mask:0xf
	v_cndmask_b32_dpp v136, v116, v112, vcc quad_perm:[1,0,3,2] row_mask:0xf bank_mask:0xf
	v_cndmask_b32_dpp v137, v117, v113, vcc quad_perm:[1,0,3,2] row_mask:0xf bank_mask:0xf
	v_cndmask_b32_dpp v138, v118, v114, vcc quad_perm:[1,0,3,2] row_mask:0xf bank_mask:0xf
	v_cndmask_b32_dpp v139, v119, v115, vcc quad_perm:[1,0,3,2] row_mask:0xf bank_mask:0xf
	s_mov_b32 vcc_lo, 0xaaaaaaaa
	s_mov_b32 vcc_hi, 0xaaaaaaaa
	v_cndmask_b32_dpp v132, v96, v100, vcc quad_perm:[1,0,3,2] row_mask:0xf bank_mask:0xf
	v_cndmask_b32_dpp v133, v97, v101, vcc quad_perm:[1,0,3,2] row_mask:0xf bank_mask:0xf
	v_cndmask_b32_dpp v134, v98, v102, vcc quad_perm:[1,0,3,2] row_mask:0xf bank_mask:0xf
	v_cndmask_b32_dpp v135, v99, v103, vcc quad_perm:[1,0,3,2] row_mask:0xf bank_mask:0xf
	v_cndmask_b32_dpp v140, v112, v116, vcc quad_perm:[1,0,3,2] row_mask:0xf bank_mask:0xf
	v_cndmask_b32_dpp v141, v113, v117, vcc quad_perm:[1,0,3,2] row_mask:0xf bank_mask:0xf
	v_cndmask_b32_dpp v142, v114, v118, vcc quad_perm:[1,0,3,2] row_mask:0xf bank_mask:0xf
	v_cndmask_b32_dpp v143, v115, v119, vcc quad_perm:[1,0,3,2] row_mask:0xf bank_mask:0xf
	s_nop 1
	s_mov_b32 vcc_lo, 0x33333333
	s_mov_b32 vcc_hi, 0x33333333
	v_cndmask_b32_dpp v96, v136, v128, vcc quad_perm:[2,3,0,1] row_mask:0xf bank_mask:0xf
	v_cndmask_b32_dpp v97, v137, v129, vcc quad_perm:[2,3,0,1] row_mask:0xf bank_mask:0xf
	v_cndmask_b32_dpp v98, v138, v130, vcc quad_perm:[2,3,0,1] row_mask:0xf bank_mask:0xf
	v_cndmask_b32_dpp v99, v139, v131, vcc quad_perm:[2,3,0,1] row_mask:0xf bank_mask:0xf
	v_cndmask_b32_dpp v100, v140, v132, vcc quad_perm:[2,3,0,1] row_mask:0xf bank_mask:0xf
	v_cndmask_b32_dpp v101, v141, v133, vcc quad_perm:[2,3,0,1] row_mask:0xf bank_mask:0xf
	v_cndmask_b32_dpp v102, v142, v134, vcc quad_perm:[2,3,0,1] row_mask:0xf bank_mask:0xf
	v_cndmask_b32_dpp v103, v143, v135, vcc quad_perm:[2,3,0,1] row_mask:0xf bank_mask:0xf
	s_mov_b32 vcc_lo, 0xcccccccc
	s_mov_b32 vcc_hi, 0xcccccccc
	v_cndmask_b32_dpp v112, v128, v136, vcc quad_perm:[2,3,0,1] row_mask:0xf bank_mask:0xf
	v_cndmask_b32_dpp v113, v129, v137, vcc quad_perm:[2,3,0,1] row_mask:0xf bank_mask:0xf
	v_cndmask_b32_dpp v114, v130, v138, vcc quad_perm:[2,3,0,1] row_mask:0xf bank_mask:0xf
	v_cndmask_b32_dpp v115, v131, v139, vcc quad_perm:[2,3,0,1] row_mask:0xf bank_mask:0xf
	v_cndmask_b32_dpp v116, v132, v140, vcc quad_perm:[2,3,0,1] row_mask:0xf bank_mask:0xf
	v_cndmask_b32_dpp v117, v133, v141, vcc quad_perm:[2,3,0,1] row_mask:0xf bank_mask:0xf
	v_cndmask_b32_dpp v118, v134, v142, vcc quad_perm:[2,3,0,1] row_mask:0xf bank_mask:0xf
	v_cndmask_b32_dpp v119, v135, v143, vcc quad_perm:[2,3,0,1] row_mask:0xf bank_mask:0xf
	s_add_u32 s76, s74, 0x0
	s_addc_u32 s77, s75, 0
	global_store_dwordx4 v181, v[96:99], s[76:77]
	s_add_u32 s76, s74, 0x2200
	s_addc_u32 s77, s75, 0
	global_store_dwordx4 v181, v[100:103], s[76:77]
	s_add_u32 s76, s74, 0x4400
	s_addc_u32 s77, s75, 0
	global_store_dwordx4 v181, v[112:115], s[76:77]
	s_add_u32 s76, s74, 0x6600
	s_addc_u32 s77, s75, 0
	global_store_dwordx4 v181, v[116:119], s[76:77]
	s_branch .Lpe_ret_L0
.Lpe_vt_L0:
	s_lshl_b32 s35, s34, 2
	s_add_u32 s35, s35, s28
	s_add_u32 s36, s28, 6
	s_cmp_eq_u32 s25, 8
	s_cselect_b32 s35, s36, s35
	s_lshr_b32 s36, s29, 11
	s_mul_i32 s36, s36, 10
	s_add_u32 s36, s36, s35
	s_lshl_b32 s36, s36, 18
	s_and_b32 s37, s29, 0x7ff
	s_lshl_b32 s37, s37, 1
	s_add_u32 s36, s36, s37
	s_add_u32 s38, s72, 0x14920000
	s_addc_u32 s39, s73, 0
	s_add_u32 s38, s38, s36
	s_addc_u32 s39, s39, 0
	s_mul_i32 s36, s26, 10240
	s_add_u32 s36, s36, 0x10000
	v_lshlrev_b32_e32 v180, 1, v197
	v_mul_u32_u24_e32 v181, 36, v146
	v_add3_u32 v180, v180, v181, s36
	v_lshrrev_b32_e32 v181, 3, v179
	v_and_b32_e32 v146, 7, v179
	v_lshlrev_b32_e32 v146, 4, v146
	v_mul_u32_u24_e32 v198, 144, v181
	v_add3_u32 v198, v198, v146, s36
	v_lshl_add_u32 v199, v181, 12, v146
	s_waitcnt vmcnt(0)
	v_mov_b32_e32 v197, 0x358637bd
	v_pk_add_f32 v[128:129], v[128:129], v[130:131]
	v_pk_add_f32 v[136:137], v[136:137], v[138:139]
	v_pk_add_f32 v[164:165], v[164:165], v[166:167]
	v_pk_add_f32 v[246:247], v[246:247], v[248:249]
	v_add_f32_e32 v128, v128, v129
	v_add_f32_e32 v136, v136, v137
	v_add_f32_e32 v164, v164, v165
	v_add_f32_e32 v246, v246, v247
	v_mov_b32_e32 v132, v128
	v_mov_b32_e32 v140, v136
	v_mov_b32_e32 v168, v164
	v_mov_b32_e32 v250, v246
	s_nop 1
	v_permlane32_swap_b32_e32 v132, v128
	v_permlane32_swap_b32_e32 v140, v136
	v_permlane32_swap_b32_e32 v168, v164
	v_permlane32_swap_b32_e32 v250, v246
	v_add_f32_e32 v128, v128, v132
	v_add_f32_e32 v136, v136, v140
	v_add_f32_e32 v164, v164, v168
	v_add_f32_e32 v246, v246, v250
	v_fmamk_f32 v128, v128, 0x3a800000, v197
	v_fmamk_f32 v136, v136, 0x3a800000, v197
	v_fmamk_f32 v164, v164, 0x3a800000, v197
	v_fmamk_f32 v246, v246, 0x3a800000, v197
	v_rsq_f32_e32 v172, v128
	v_rsq_f32_e32 v173, v136
	v_rsq_f32_e32 v174, v164
	v_rsq_f32_e32 v175, v246
	s_nop 0
	s_add_u32 s76, s99, s90
	s_cmp_lt_u32 s76, 0x440
	s_cselect_b32 s80, 1, 0
	s_cselect_b32 s83, 0x200000, 0
	s_lshl_b32 s76, s24, 19
	s_lshl_b32 s77, s26, 16
	s_add_u32 s76, s76, s77
	s_and_b32 s77, s24, 7
	s_lshl_b32 s77, s77, 8
	s_add_u32 s76, s76, s77
	s_add_u32 s78, s72, 0xa120000
	s_addc_u32 s79, s73, 0
	s_add_u32 s78, s78, s76
	s_addc_u32 s79, s79, 0
	s_lshl_b32 s76, s25, 19
	s_add_u32 s76, s76, s83
	s_add_u32 s76, s76, s77
	s_lshl_b32 s77, s26, 16
	s_add_u32 s76, s76, s77
	s_add_u32 s82, s72, 0x0
	s_addc_u32 s83, s73, 0
	s_add_u32 s82, s82, s76
	s_addc_u32 s83, s83, 0
	s_lshl_b32 s76, s26, 12
	s_mov_b32 m0, s76
	s_nop 0
	global_load_lds_dwordx4 v145, s[78:79]
	s_add_u32 s78, s78, 0x4000
	s_addc_u32 s79, s79, 0
	s_add_u32 s76, s76, 0x400
	s_mov_b32 m0, s76
	s_nop 0
	global_load_lds_dwordx4 v185, s[78:79]
	s_add_u32 s78, s78, 0x4000
	s_addc_u32 s79, s79, 0
	s_add_u32 s76, s76, 0x400
	s_mov_b32 m0, s76
	s_nop 0
	global_load_lds_dwordx4 v145, s[78:79]
	s_add_u32 s78, s78, 0x4000
	s_addc_u32 s79, s79, 0
	s_add_u32 s76, s76, 0x400
	s_mov_b32 m0, s76
	s_nop 0
	global_load_lds_dwordx4 v185, s[78:79]
	s_add_u32 s78, s78, 0x4000
	s_addc_u32 s79, s79, 0
	s_add_u32 s76, s76, 0x400
	s_add_u32 s76, s76, 0x7000
	s_mov_b32 m0, s76
	s_nop 0
	global_load_lds_dwordx4 v145, s[82:83]
	s_add_u32 s82, s82, 0x4000
	s_addc_u32 s83, s83, 0
	s_add_u32 s76, s76, 0x400
	s_mov_b32 m0, s76
	s_nop 0
	global_load_lds_dwordx4 v185, s[82:83]
	s_add_u32 s82, s82, 0x4000
	s_addc_u32 s83, s83, 0
	s_add_u32 s76, s76, 0x400
	s_mov_b32 m0, s76
	s_nop 0
	global_load_lds_dwordx4 v145, s[82:83]
	s_add_u32 s82, s82, 0x4000
	s_addc_u32 s83, s83, 0
	s_add_u32 s76, s76, 0x400
	s_mov_b32 m0, s76
	s_nop 0
	global_load_lds_dwordx4 v185, s[82:83]
	s_add_u32 s82, s82, 0x4000
	s_addc_u32 s83, s83, 0
	s_add_u32 s76, s76, 0x400
	v_pk_mul_f32 v[0:1], v[0:1], v[172:173] op_sel_hi:[1,0]
	v_pk_mul_f32 v[2:3], v[2:3], v[172:173] op_sel_hi:[1,0]
	v_pk_mul_f32 v[4:5], v[4:5], v[172:173] op_sel_hi:[1,0]
	v_pk_mul_f32 v[6:7], v[6:7], v[172:173] op_sel_hi:[1,0]
	v_pk_mul_f32 v[8:9], v[8:9], v[172:173] op_sel_hi:[1,0]
	v_pk_mul_f32 v[10:11], v[10:11], v[172:173] op_sel_hi:[1,0]
	v_pk_mul_f32 v[12:13], v[12:13], v[172:173] op_sel_hi:[1,0]
	v_pk_mul_f32 v[14:15], v[14:15], v[172:173] op_sel_hi:[1,0]
	v_pk_mul_f32 v[16:17], v[16:17], v[172:173] op_sel_hi:[1,0]
	v_pk_mul_f32 v[18:19], v[18:19], v[172:173] op_sel_hi:[1,0]
	v_pk_mul_f32 v[20:21], v[20:21], v[172:173] op_sel_hi:[1,0]
	v_pk_mul_f32 v[22:23], v[22:23], v[172:173] op_sel_hi:[1,0]
	v_pk_mul_f32 v[24:25], v[24:25], v[172:173] op_sel_hi:[1,0]
	v_pk_mul_f32 v[26:27], v[26:27], v[172:173] op_sel_hi:[1,0]
	v_pk_mul_f32 v[28:29], v[28:29], v[172:173] op_sel_hi:[1,0]
	v_pk_mul_f32 v[30:31], v[30:31], v[172:173] op_sel_hi:[1,0]
	v_pk_mul_f32 v[32:33], v[32:33], v[172:173] op_sel:[0,1] op_sel_hi:[1,1]
	v_pk_mul_f32 v[34:35], v[34:35], v[172:173] op_sel:[0,1] op_sel_hi:[1,1]
	v_pk_mul_f32 v[36:37], v[36:37], v[172:173] op_sel:[0,1] op_sel_hi:[1,1]
	v_pk_mul_f32 v[38:39], v[38:39], v[172:173] op_sel:[0,1] op_sel_hi:[1,1]
	v_pk_mul_f32 v[40:41], v[40:41], v[172:173] op_sel:[0,1] op_sel_hi:[1,1]
	v_pk_mul_f32 v[42:43], v[42:43], v[172:173] op_sel:[0,1] op_sel_hi:[1,1]
	v_pk_mul_f32 v[44:45], v[44:45], v[172:173] op_sel:[0,1] op_sel_hi:[1,1]
	v_pk_mul_f32 v[46:47], v[46:47], v[172:173] op_sel:[0,1] op_sel_hi:[1,1]
	v_pk_mul_f32 v[48:49], v[48:49], v[172:173] op_sel:[0,1] op_sel_hi:[1,1]
	v_pk_mul_f32 v[50:51], v[50:51], v[172:173] op_sel:[0,1] op_sel_hi:[1,1]
	v_pk_mul_f32 v[52:53], v[52:53], v[172:173] op_sel:[0,1] op_sel_hi:[1,1]
	v_pk_mul_f32 v[54:55], v[54:55], v[172:173] op_sel:[0,1] op_sel_hi:[1,1]
	v_pk_mul_f32 v[56:57], v[56:57], v[172:173] op_sel:[0,1] op_sel_hi:[1,1]
	v_pk_mul_f32 v[58:59], v[58:59], v[172:173] op_sel:[0,1] op_sel_hi:[1,1]
	v_pk_mul_f32 v[60:61], v[60:61], v[172:173] op_sel:[0,1] op_sel_hi:[1,1]
	v_pk_mul_f32 v[62:63], v[62:63], v[172:173] op_sel:[0,1] op_sel_hi:[1,1]
	v_pk_mul_f32 v[64:65], v[64:65], v[174:175] op_sel_hi:[1,0]
	v_pk_mul_f32 v[66:67], v[66:67], v[174:175] op_sel_hi:[1,0]
	v_pk_mul_f32 v[68:69], v[68:69], v[174:175] op_sel_hi:[1,0]
	v_pk_mul_f32 v[70:71], v[70:71], v[174:175] op_sel_hi:[1,0]
	v_pk_mul_f32 v[72:73], v[72:73], v[174:175] op_sel_hi:[1,0]
	v_pk_mul_f32 v[74:75], v[74:75], v[174:175] op_sel_hi:[1,0]
	v_pk_mul_f32 v[76:77], v[76:77], v[174:175] op_sel_hi:[1,0]
	v_pk_mul_f32 v[78:79], v[78:79], v[174:175] op_sel_hi:[1,0]
	v_pk_mul_f32 v[80:81], v[80:81], v[174:175] op_sel_hi:[1,0]
	v_pk_mul_f32 v[82:83], v[82:83], v[174:175] op_sel_hi:[1,0]
	v_pk_mul_f32 v[84:85], v[84:85], v[174:175] op_sel_hi:[1,0]
	v_pk_mul_f32 v[86:87], v[86:87], v[174:175] op_sel_hi:[1,0]
	v_pk_mul_f32 v[88:89], v[88:89], v[174:175] op_sel_hi:[1,0]
	v_pk_mul_f32 v[90:91], v[90:91], v[174:175] op_sel_hi:[1,0]
	v_pk_mul_f32 v[92:93], v[92:93], v[174:175] op_sel_hi:[1,0]
	v_pk_mul_f32 v[94:95], v[94:95], v[174:175] op_sel_hi:[1,0]
	v_pk_mul_f32 v[96:97], v[96:97], v[174:175] op_sel:[0,1] op_sel_hi:[1,1]
	v_pk_mul_f32 v[98:99], v[98:99], v[174:175] op_sel:[0,1] op_sel_hi:[1,1]
	v_pk_mul_f32 v[100:101], v[100:101], v[174:175] op_sel:[0,1] op_sel_hi:[1,1]
	v_pk_mul_f32 v[102:103], v[102:103], v[174:175] op_sel:[0,1] op_sel_hi:[1,1]
	v_pk_mul_f32 v[104:105], v[104:105], v[174:175] op_sel:[0,1] op_sel_hi:[1,1]
	v_pk_mul_f32 v[106:107], v[106:107], v[174:175] op_sel:[0,1] op_sel_hi:[1,1]
	v_pk_mul_f32 v[108:109], v[108:109], v[174:175] op_sel:[0,1] op_sel_hi:[1,1]
	v_pk_mul_f32 v[110:111], v[110:111], v[174:175] op_sel:[0,1] op_sel_hi:[1,1]
	v_pk_mul_f32 v[112:113], v[112:113], v[174:175] op_sel:[0,1] op_sel_hi:[1,1]
	v_pk_mul_f32 v[114:115], v[114:115], v[174:175] op_sel:[0,1] op_sel_hi:[1,1]
	v_pk_mul_f32 v[116:117], v[116:117], v[174:175] op_sel:[0,1] op_sel_hi:[1,1]
	v_pk_mul_f32 v[118:119], v[118:119], v[174:175] op_sel:[0,1] op_sel_hi:[1,1]
	v_pk_mul_f32 v[120:121], v[120:121], v[174:175] op_sel:[0,1] op_sel_hi:[1,1]
	v_pk_mul_f32 v[122:123], v[122:123], v[174:175] op_sel:[0,1] op_sel_hi:[1,1]
	v_pk_mul_f32 v[124:125], v[124:125], v[174:175] op_sel:[0,1] op_sel_hi:[1,1]
	v_pk_mul_f32 v[126:127], v[126:127], v[174:175] op_sel:[0,1] op_sel_hi:[1,1]
	v_cvt_pk_bf16_f32 v0, v0, v1
	v_cvt_pk_bf16_f32 v1, v2, v3
	v_cvt_pk_bf16_f32 v2, v4, v5
	v_cvt_pk_bf16_f32 v3, v6, v7
	v_cvt_pk_bf16_f32 v4, v8, v9
	v_cvt_pk_bf16_f32 v5, v10, v11
	v_cvt_pk_bf16_f32 v6, v12, v13
	v_cvt_pk_bf16_f32 v7, v14, v15
	ds_write_b16 v180, v0 offset:0
	ds_write_b16_d16_hi v180, v0 offset:144
	ds_write_b16 v180, v1 offset:288
	ds_write_b16_d16_hi v180, v1 offset:432
	ds_write_b16 v180, v2 offset:1152
	ds_write_b16_d16_hi v180, v2 offset:1296
	ds_write_b16 v180, v3 offset:1440
	ds_write_b16_d16_hi v180, v3 offset:1584
	ds_write_b16 v180, v4 offset:2304
	ds_write_b16_d16_hi v180, v4 offset:2448
	ds_write_b16 v180, v5 offset:2592
	ds_write_b16_d16_hi v180, v5 offset:2736
	ds_write_b16 v180, v6 offset:3456
	ds_write_b16_d16_hi v180, v6 offset:3600
	ds_write_b16 v180, v7 offset:3744
	ds_write_b16_d16_hi v180, v7 offset:3888
	v_cvt_pk_bf16_f32 v16, v16, v17
	v_cvt_pk_bf16_f32 v17, v18, v19
	v_cvt_pk_bf16_f32 v18, v20, v21
	v_cvt_pk_bf16_f32 v19, v22, v23
	v_cvt_pk_bf16_f32 v20, v24, v25
	v_cvt_pk_bf16_f32 v21, v26, v27
	v_cvt_pk_bf16_f32 v22, v28, v29
	v_cvt_pk_bf16_f32 v23, v30, v31
	ds_write_b16 v180, v16 offset:4608
	ds_write_b16_d16_hi v180, v16 offset:4752
	ds_write_b16 v180, v17 offset:4896
	ds_write_b16_d16_hi v180, v17 offset:5040
	ds_write_b16 v180, v18 offset:5760
	ds_write_b16_d16_hi v180, v18 offset:5904
	ds_write_b16 v180, v19 offset:6048
	ds_write_b16_d16_hi v180, v19 offset:6192
	ds_write_b16 v180, v20 offset:6912
	ds_write_b16_d16_hi v180, v20 offset:7056
	ds_write_b16 v180, v21 offset:7200
	ds_write_b16_d16_hi v180, v21 offset:7344
	ds_write_b16 v180, v22 offset:8064
	ds_write_b16_d16_hi v180, v22 offset:8208
	ds_write_b16 v180, v23 offset:8352
	ds_write_b16_d16_hi v180, v23 offset:8496
	v_cvt_pk_bf16_f32 v32, v32, v33
	v_cvt_pk_bf16_f32 v33, v34, v35
	v_cvt_pk_bf16_f32 v34, v36, v37
	v_cvt_pk_bf16_f32 v35, v38, v39
	v_cvt_pk_bf16_f32 v36, v40, v41
	v_cvt_pk_bf16_f32 v37, v42, v43
	v_cvt_pk_bf16_f32 v38, v44, v45
	v_cvt_pk_bf16_f32 v39, v46, v47
	ds_write_b16 v180, v32 offset:64
	ds_write_b16_d16_hi v180, v32 offset:208
	ds_write_b16 v180, v33 offset:352
	ds_write_b16_d16_hi v180, v33 offset:496
	ds_write_b16 v180, v34 offset:1216
	ds_write_b16_d16_hi v180, v34 offset:1360
	ds_write_b16 v180, v35 offset:1504
	ds_write_b16_d16_hi v180, v35 offset:1648
	ds_write_b16 v180, v36 offset:2368
	ds_write_b16_d16_hi v180, v36 offset:2512
	ds_write_b16 v180, v37 offset:2656
	ds_write_b16_d16_hi v180, v37 offset:2800
	ds_write_b16 v180, v38 offset:3520
	ds_write_b16_d16_hi v180, v38 offset:3664
	ds_write_b16 v180, v39 offset:3808
	ds_write_b16_d16_hi v180, v39 offset:3952
	v_cvt_pk_bf16_f32 v48, v48, v49
	v_cvt_pk_bf16_f32 v49, v50, v51
	v_cvt_pk_bf16_f32 v50, v52, v53
	v_cvt_pk_bf16_f32 v51, v54, v55
	v_cvt_pk_bf16_f32 v52, v56, v57
	v_cvt_pk_bf16_f32 v53, v58, v59
	v_cvt_pk_bf16_f32 v54, v60, v61
	v_cvt_pk_bf16_f32 v55, v62, v63
	ds_write_b16 v180, v48 offset:4672
	ds_write_b16_d16_hi v180, v48 offset:4816
	ds_write_b16 v180, v49 offset:4960
	ds_write_b16_d16_hi v180, v49 offset:5104
	ds_write_b16 v180, v50 offset:5824
	ds_write_b16_d16_hi v180, v50 offset:5968
	ds_write_b16 v180, v51 offset:6112
	ds_write_b16_d16_hi v180, v51 offset:6256
	ds_write_b16 v180, v52 offset:6976
	ds_write_b16_d16_hi v180, v52 offset:7120
	ds_write_b16 v180, v53 offset:7264
	ds_write_b16_d16_hi v180, v53 offset:7408
	ds_write_b16 v180, v54 offset:8128
	ds_write_b16_d16_hi v180, v54 offset:8272
	ds_write_b16 v180, v55 offset:8416
	ds_write_b16_d16_hi v180, v55 offset:8560
	s_waitcnt lgkmcnt(0)
	ds_read_b128 v[0:3], v198 offset:0
	ds_read_b128 v[4:7], v198 offset:1152
	ds_read_b128 v[8:11], v198 offset:2304
	ds_read_b128 v[12:15], v198 offset:3456
	ds_read_b128 v[16:19], v198 offset:4608
	ds_read_b128 v[20:23], v198 offset:5760
	ds_read_b128 v[24:27], v198 offset:6912
	ds_read_b128 v[28:31], v198 offset:8064
	s_waitcnt lgkmcnt(7)
	global_store_dwordx4 v199, v[0:3], s[38:39]
	s_add_u32 s38, s38, 0x8000
	s_addc_u32 s39, s39, 0
	s_waitcnt lgkmcnt(6)
	global_store_dwordx4 v199, v[4:7], s[38:39]
	s_add_u32 s38, s38, 0x8000
	s_addc_u32 s39, s39, 0
	s_waitcnt lgkmcnt(5)
	global_store_dwordx4 v199, v[8:11], s[38:39]
	s_add_u32 s38, s38, 0x8000
	s_addc_u32 s39, s39, 0
	s_waitcnt lgkmcnt(4)
	global_store_dwordx4 v199, v[12:15], s[38:39]
	s_add_u32 s38, s38, 0x8000
	s_addc_u32 s39, s39, 0
	s_waitcnt lgkmcnt(3)
	global_store_dwordx4 v199, v[16:19], s[38:39]
	s_add_u32 s38, s38, 0x8000
	s_addc_u32 s39, s39, 0
	s_waitcnt lgkmcnt(2)
	global_store_dwordx4 v199, v[20:23], s[38:39]
	s_add_u32 s38, s38, 0x8000
	s_addc_u32 s39, s39, 0
	s_waitcnt lgkmcnt(1)
	global_store_dwordx4 v199, v[24:27], s[38:39]
	s_add_u32 s38, s38, 0x8000
	s_addc_u32 s39, s39, 0
	s_waitcnt lgkmcnt(0)
	global_store_dwordx4 v199, v[28:31], s[38:39]
	s_sub_u32 s38, s38, 229248
	s_subb_u32 s39, s39, 0
	v_cvt_pk_bf16_f32 v64, v64, v65
	v_cvt_pk_bf16_f32 v65, v66, v67
	v_cvt_pk_bf16_f32 v66, v68, v69
	v_cvt_pk_bf16_f32 v67, v70, v71
	v_cvt_pk_bf16_f32 v68, v72, v73
	v_cvt_pk_bf16_f32 v69, v74, v75
	v_cvt_pk_bf16_f32 v70, v76, v77
	v_cvt_pk_bf16_f32 v71, v78, v79
	ds_write_b16 v180, v64 offset:0
	ds_write_b16_d16_hi v180, v64 offset:144
	ds_write_b16 v180, v65 offset:288
	ds_write_b16_d16_hi v180, v65 offset:432
	ds_write_b16 v180, v66 offset:1152
	ds_write_b16_d16_hi v180, v66 offset:1296
	ds_write_b16 v180, v67 offset:1440
	ds_write_b16_d16_hi v180, v67 offset:1584
	ds_write_b16 v180, v68 offset:2304
	ds_write_b16_d16_hi v180, v68 offset:2448
	ds_write_b16 v180, v69 offset:2592
	ds_write_b16_d16_hi v180, v69 offset:2736
	ds_write_b16 v180, v70 offset:3456
	ds_write_b16_d16_hi v180, v70 offset:3600
	ds_write_b16 v180, v71 offset:3744
	ds_write_b16_d16_hi v180, v71 offset:3888
	v_cvt_pk_bf16_f32 v80, v80, v81
	v_cvt_pk_bf16_f32 v81, v82, v83
	v_cvt_pk_bf16_f32 v82, v84, v85
	v_cvt_pk_bf16_f32 v83, v86, v87
	v_cvt_pk_bf16_f32 v84, v88, v89
	v_cvt_pk_bf16_f32 v85, v90, v91
	v_cvt_pk_bf16_f32 v86, v92, v93
	v_cvt_pk_bf16_f32 v87, v94, v95
	ds_write_b16 v180, v80 offset:4608
	ds_write_b16_d16_hi v180, v80 offset:4752
	ds_write_b16 v180, v81 offset:4896
	ds_write_b16_d16_hi v180, v81 offset:5040
	ds_write_b16 v180, v82 offset:5760
	ds_write_b16_d16_hi v180, v82 offset:5904
	ds_write_b16 v180, v83 offset:6048
	ds_write_b16_d16_hi v180, v83 offset:6192
	ds_write_b16 v180, v84 offset:6912
	ds_write_b16_d16_hi v180, v84 offset:7056
	ds_write_b16 v180, v85 offset:7200
	ds_write_b16_d16_hi v180, v85 offset:7344
	ds_write_b16 v180, v86 offset:8064
	ds_write_b16_d16_hi v180, v86 offset:8208
	ds_write_b16 v180, v87 offset:8352
	ds_write_b16_d16_hi v180, v87 offset:8496
	v_cvt_pk_bf16_f32 v96, v96, v97
	v_cvt_pk_bf16_f32 v97, v98, v99
	v_cvt_pk_bf16_f32 v98, v100, v101
	v_cvt_pk_bf16_f32 v99, v102, v103
	v_cvt_pk_bf16_f32 v100, v104, v105
	v_cvt_pk_bf16_f32 v101, v106, v107
	v_cvt_pk_bf16_f32 v102, v108, v109
	v_cvt_pk_bf16_f32 v103, v110, v111
	ds_write_b16 v180, v96 offset:64
	ds_write_b16_d16_hi v180, v96 offset:208
	ds_write_b16 v180, v97 offset:352
	ds_write_b16_d16_hi v180, v97 offset:496
	ds_write_b16 v180, v98 offset:1216
	ds_write_b16_d16_hi v180, v98 offset:1360
	ds_write_b16 v180, v99 offset:1504
	ds_write_b16_d16_hi v180, v99 offset:1648
	ds_write_b16 v180, v100 offset:2368
	ds_write_b16_d16_hi v180, v100 offset:2512
	ds_write_b16 v180, v101 offset:2656
	ds_write_b16_d16_hi v180, v101 offset:2800
	ds_write_b16 v180, v102 offset:3520
	ds_write_b16_d16_hi v180, v102 offset:3664
	ds_write_b16 v180, v103 offset:3808
	ds_write_b16_d16_hi v180, v103 offset:3952
	v_cvt_pk_bf16_f32 v112, v112, v113
	v_cvt_pk_bf16_f32 v113, v114, v115
	v_cvt_pk_bf16_f32 v114, v116, v117
	v_cvt_pk_bf16_f32 v115, v118, v119
	v_cvt_pk_bf16_f32 v116, v120, v121
	v_cvt_pk_bf16_f32 v117, v122, v123
	v_cvt_pk_bf16_f32 v118, v124, v125
	v_cvt_pk_bf16_f32 v119, v126, v127
	ds_write_b16 v180, v112 offset:4672
	ds_write_b16_d16_hi v180, v112 offset:4816
	ds_write_b16 v180, v113 offset:4960
	ds_write_b16_d16_hi v180, v113 offset:5104
	ds_write_b16 v180, v114 offset:5824
	ds_write_b16_d16_hi v180, v114 offset:5968
	ds_write_b16 v180, v115 offset:6112
	ds_write_b16_d16_hi v180, v115 offset:6256
	ds_write_b16 v180, v116 offset:6976
	ds_write_b16_d16_hi v180, v116 offset:7120
	ds_write_b16 v180, v117 offset:7264
	ds_write_b16_d16_hi v180, v117 offset:7408
	ds_write_b16 v180, v118 offset:8128
	ds_write_b16_d16_hi v180, v118 offset:8272
	ds_write_b16 v180, v119 offset:8416
	ds_write_b16_d16_hi v180, v119 offset:8560
	s_waitcnt lgkmcnt(0)
	ds_read_b128 v[64:67], v198 offset:0
	ds_read_b128 v[68:71], v198 offset:1152
	ds_read_b128 v[72:75], v198 offset:2304
	ds_read_b128 v[76:79], v198 offset:3456
	ds_read_b128 v[80:83], v198 offset:4608
	ds_read_b128 v[84:87], v198 offset:5760
	ds_read_b128 v[88:91], v198 offset:6912
	ds_read_b128 v[92:95], v198 offset:8064
	s_waitcnt lgkmcnt(7)
	global_store_dwordx4 v199, v[64:67], s[38:39]
	s_add_u32 s38, s38, 0x8000
	s_addc_u32 s39, s39, 0
	s_waitcnt lgkmcnt(6)
	global_store_dwordx4 v199, v[68:71], s[38:39]
	s_add_u32 s38, s38, 0x8000
	s_addc_u32 s39, s39, 0
	s_waitcnt lgkmcnt(5)
	global_store_dwordx4 v199, v[72:75], s[38:39]
	s_add_u32 s38, s38, 0x8000
	s_addc_u32 s39, s39, 0
	s_waitcnt lgkmcnt(4)
	global_store_dwordx4 v199, v[76:79], s[38:39]
	s_add_u32 s38, s38, 0x8000
	s_addc_u32 s39, s39, 0
	s_waitcnt lgkmcnt(3)
	global_store_dwordx4 v199, v[80:83], s[38:39]
	s_add_u32 s38, s38, 0x8000
	s_addc_u32 s39, s39, 0
	s_waitcnt lgkmcnt(2)
	global_store_dwordx4 v199, v[84:87], s[38:39]
	s_add_u32 s38, s38, 0x8000
	s_addc_u32 s39, s39, 0
	s_waitcnt lgkmcnt(1)
	global_store_dwordx4 v199, v[88:91], s[38:39]
	s_add_u32 s38, s38, 0x8000
	s_addc_u32 s39, s39, 0
	s_waitcnt lgkmcnt(0)
	global_store_dwordx4 v199, v[92:95], s[38:39]

.Lpe_notv_L1:
	s_cmp_ge_u32 s25, 9
	s_cbranch_scc1 .Lpe_gates_L1
	s_lshr_b32 s34, s25, 1
	s_cmp_ge_u32 s25, 6
	s_cselect_b32 s35, 1, 0
	s_sub_u32 s34, s34, s35
	s_lshl_b32 s35, s98, 2
	s_add_u32 s35, s35, s34
	s_lshl_b32 s35, s35, 8
	v_readlane_b32 s82, v254, 14
	v_readlane_b32 s83, v254, 15
	s_add_u32 s82, s82, s35
	s_addc_u32 s83, s83, 0
	global_load_dwordx4 v[198:201], v146, s[82:83] offset:0
	global_load_dwordx4 v[202:205], v146, s[82:83] offset:32
	global_load_dwordx4 v[206:209], v146, s[82:83] offset:64
	global_load_dwordx4 v[210:213], v146, s[82:83] offset:96
	global_load_dwordx4 v[214:217], v146, s[82:83] offset:128
	global_load_dwordx4 v[218:221], v146, s[82:83] offset:160
	global_load_dwordx4 v[222:225], v146, s[82:83] offset:192
	global_load_dwordx4 v[226:229], v146, s[82:83] offset:224
	s_and_b32 s35, s34, 1
	s_cmp_eq_u32 s35, 0
	s_cselect_b32 s36, 0x3e000000, 1.0
	s_and_b32 s35, s29, 0x7ff
	s_lshl_b32 s35, s35, 7
	s_add_u32 s96, s72, 0x1ada0000
	s_addc_u32 s97, s73, 0
	s_add_u32 s96, s96, s35
	s_addc_u32 s97, s97, 0
	s_add_u32 s100, s96, 0x40000
	s_addc_u32 s101, s97, 0
	s_cmp_ge_u32 s34, 2
	s_cselect_b32 s37, 1, 0
	s_waitcnt vmcnt(8)
	v_lshlrev_b32_e32 v180, 7, v197
	v_add_u32_e32 v180, v180, v146
	v_mov_b32_e32 v197, 0x358637bd
	v_pk_add_f32 v[128:129], v[128:129], v[130:131]
	v_pk_add_f32 v[136:137], v[136:137], v[138:139]
	v_pk_add_f32 v[164:165], v[164:165], v[166:167]
	v_pk_add_f32 v[246:247], v[246:247], v[248:249]
	v_add_f32_e32 v128, v128, v129
	v_add_f32_e32 v136, v136, v137
	v_add_f32_e32 v164, v164, v165
	v_add_f32_e32 v246, v246, v247
	v_mov_b32_e32 v132, v128
	v_mov_b32_e32 v140, v136
	v_mov_b32_e32 v168, v164
	v_mov_b32_e32 v250, v246
	s_nop 1
	v_permlane32_swap_b32_e32 v132, v128
	v_permlane32_swap_b32_e32 v140, v136
	v_permlane32_swap_b32_e32 v168, v164
	v_permlane32_swap_b32_e32 v250, v246
	v_add_f32_e32 v128, v128, v132
	v_add_f32_e32 v136, v136, v140
	v_add_f32_e32 v164, v164, v168
	v_add_f32_e32 v246, v246, v250
	v_fmamk_f32 v128, v128, 0x3a800000, v197
	v_fmamk_f32 v136, v136, 0x3a800000, v197
	v_fmamk_f32 v164, v164, 0x3a800000, v197
	v_fmamk_f32 v246, v246, 0x3a800000, v197
	v_rsq_f32_e32 v172, v128
	v_rsq_f32_e32 v173, v136
	v_rsq_f32_e32 v174, v164
	v_rsq_f32_e32 v175, v246
	s_nop 0
	s_add_u32 s76, s99, s90
	s_cmp_lt_u32 s76, 0x440
	s_cselect_b32 s80, 1, 0
	s_cselect_b32 s83, 0x200000, 0
	s_lshl_b32 s76, s24, 19
	s_lshl_b32 s77, s26, 16
	s_add_u32 s76, s76, s77
	s_and_b32 s77, s24, 7
	s_lshl_b32 s77, s77, 8
	s_add_u32 s76, s76, s77
	s_add_u32 s78, s72, 0xa120000
	s_addc_u32 s79, s73, 0
	s_add_u32 s78, s78, s76
	s_addc_u32 s79, s79, 0
	s_lshl_b32 s76, s25, 19
	s_add_u32 s76, s76, s83
	s_add_u32 s76, s76, s77
	s_lshl_b32 s77, s26, 16
	s_add_u32 s76, s76, s77
	s_add_u32 s82, s72, 0x880000
	s_addc_u32 s83, s73, 0
	s_add_u32 s82, s82, s76
	s_addc_u32 s83, s83, 0
	s_lshl_b32 s76, s26, 12
	s_mov_b32 m0, s76
	s_nop 0
	global_load_lds_dwordx4 v177, s[78:79]
	s_add_u32 s78, s78, 0x4000
	s_addc_u32 s79, s79, 0
	s_add_u32 s76, s76, 0x400
	s_mov_b32 m0, s76
	s_nop 0
	global_load_lds_dwordx4 v185, s[78:79]
	s_add_u32 s78, s78, 0x4000
	s_addc_u32 s79, s79, 0
	s_add_u32 s76, s76, 0x400
	s_mov_b32 m0, s76
	s_nop 0
	global_load_lds_dwordx4 v177, s[78:79]
	s_add_u32 s78, s78, 0x4000
	s_addc_u32 s79, s79, 0
	s_add_u32 s76, s76, 0x400
	s_mov_b32 m0, s76
	s_nop 0
	global_load_lds_dwordx4 v185, s[78:79]
	s_add_u32 s78, s78, 0x4000
	s_addc_u32 s79, s79, 0
	s_add_u32 s76, s76, 0x400
	s_add_u32 s76, s76, 0x7000
	s_mov_b32 m0, s76
	s_nop 0
	global_load_lds_dwordx4 v177, s[82:83]
	s_add_u32 s82, s82, 0x4000
	s_addc_u32 s83, s83, 0
	s_add_u32 s76, s76, 0x400
	s_mov_b32 m0, s76
	s_nop 0
	global_load_lds_dwordx4 v185, s[82:83]
	s_add_u32 s82, s82, 0x4000
	s_addc_u32 s83, s83, 0
	s_add_u32 s76, s76, 0x400
	s_mov_b32 m0, s76
	s_nop 0
	global_load_lds_dwordx4 v177, s[82:83]
	s_add_u32 s82, s82, 0x4000
	s_addc_u32 s83, s83, 0
	s_add_u32 s76, s76, 0x400
	s_mov_b32 m0, s76
	s_nop 0
	global_load_lds_dwordx4 v185, s[82:83]
	s_add_u32 s82, s82, 0x4000
	s_addc_u32 s83, s83, 0
	s_add_u32 s76, s76, 0x400
	s_cmp_eq_u32 s37, 0
	s_cbranch_scc1 .Lpe_norope_ld_L1
	global_load_dwordx4 v[230:233], v180, s[96:97] offset:0
	global_load_dwordx4 v[234:237], v180, s[96:97] offset:32
	global_load_dwordx4 v[238:241], v180, s[96:97] offset:64
	global_load_dwordx4 v[242:245], v180, s[96:97] offset:96
	global_load_dwordx4 v[148:151], v180, s[100:101] offset:0
	global_load_dwordx4 v[152:155], v180, s[100:101] offset:32
	global_load_dwordx4 v[156:159], v180, s[100:101] offset:64
	global_load_dwordx4 v[160:163], v180, s[100:101] offset:96

.Lpe_gates_L1:
	s_lshl_b32 s35, s98, 11
	s_add_u32 s35, s35, s30
	s_sub_u32 s35, s35, 0x900
	s_lshl_b32 s35, s35, 2
	v_readlane_b32 s82, v254, 12
	v_readlane_b32 s83, v254, 13
	s_add_u32 s82, s82, s35
	s_addc_u32 s83, s83, 0
	global_load_dwordx4 v[198:201], v146, s[82:83] offset:0
	global_load_dwordx4 v[202:205], v146, s[82:83] offset:32
	global_load_dwordx4 v[206:209], v146, s[82:83] offset:64
	global_load_dwordx4 v[210:213], v146, s[82:83] offset:96
	global_load_dwordx4 v[214:217], v146, s[82:83] offset:128
	global_load_dwordx4 v[218:221], v146, s[82:83] offset:160
	global_load_dwordx4 v[222:225], v146, s[82:83] offset:192
	global_load_dwordx4 v[226:229], v146, s[82:83] offset:224
	s_waitcnt vmcnt(8)
	v_mov_b32_e32 v197, 0x358637bd
	v_pk_add_f32 v[128:129], v[128:129], v[130:131]
	v_pk_add_f32 v[136:137], v[136:137], v[138:139]
	v_pk_add_f32 v[164:165], v[164:165], v[166:167]
	v_pk_add_f32 v[246:247], v[246:247], v[248:249]
	v_add_f32_e32 v128, v128, v129
	v_add_f32_e32 v136, v136, v137
	v_add_f32_e32 v164, v164, v165
	v_add_f32_e32 v246, v246, v247
	v_mov_b32_e32 v132, v128
	v_mov_b32_e32 v140, v136
	v_mov_b32_e32 v168, v164
	v_mov_b32_e32 v250, v246
	s_nop 1
	v_permlane32_swap_b32_e32 v132, v128
	v_permlane32_swap_b32_e32 v140, v136
	v_permlane32_swap_b32_e32 v168, v164
	v_permlane32_swap_b32_e32 v250, v246
	v_add_f32_e32 v128, v128, v132
	v_add_f32_e32 v136, v136, v140
	v_add_f32_e32 v164, v164, v168
	v_add_f32_e32 v246, v246, v250
	v_fmamk_f32 v128, v128, 0x3a800000, v197
	v_fmamk_f32 v136, v136, 0x3a800000, v197
	v_fmamk_f32 v164, v164, 0x3a800000, v197
	v_fmamk_f32 v246, v246, 0x3a800000, v197
	v_rsq_f32_e32 v172, v128
	v_rsq_f32_e32 v173, v136
	v_rsq_f32_e32 v174, v164
	v_rsq_f32_e32 v175, v246
	s_nop 0
	s_add_u32 s76, s99, s90
	s_cmp_lt_u32 s76, 0x440
	s_cselect_b32 s80, 1, 0
	s_cselect_b32 s83, 0x200000, 0
	s_lshl_b32 s76, s24, 19
	s_lshl_b32 s77, s26, 16
	s_add_u32 s76, s76, s77
	s_and_b32 s77, s24, 7
	s_lshl_b32 s77, s77, 8
	s_add_u32 s76, s76, s77
	s_add_u32 s78, s72, 0xa120000
	s_addc_u32 s79, s73, 0
	s_add_u32 s78, s78, s76
	s_addc_u32 s79, s79, 0
	s_lshl_b32 s76, s25, 19
	s_add_u32 s76, s76, s83
	s_add_u32 s76, s76, s77
	s_lshl_b32 s77, s26, 16
	s_add_u32 s76, s76, s77
	s_add_u32 s82, s72, 0x880000
	s_addc_u32 s83, s73, 0
	s_add_u32 s82, s82, s76
	s_addc_u32 s83, s83, 0
	s_lshl_b32 s76, s26, 12
	s_mov_b32 m0, s76
	s_nop 0
	global_load_lds_dwordx4 v177, s[78:79]
	s_add_u32 s78, s78, 0x4000
	s_addc_u32 s79, s79, 0
	s_add_u32 s76, s76, 0x400
	s_mov_b32 m0, s76
	s_nop 0
	global_load_lds_dwordx4 v185, s[78:79]
	s_add_u32 s78, s78, 0x4000
	s_addc_u32 s79, s79, 0
	s_add_u32 s76, s76, 0x400
	s_mov_b32 m0, s76
	s_nop 0
	global_load_lds_dwordx4 v177, s[78:79]
	s_add_u32 s78, s78, 0x4000
	s_addc_u32 s79, s79, 0
	s_add_u32 s76, s76, 0x400
	s_mov_b32 m0, s76
	s_nop 0
	global_load_lds_dwordx4 v185, s[78:79]
	s_add_u32 s78, s78, 0x4000
	s_addc_u32 s79, s79, 0
	s_add_u32 s76, s76, 0x400
	s_add_u32 s76, s76, 0x7000
	s_mov_b32 m0, s76
	s_nop 0
	global_load_lds_dwordx4 v177, s[82:83]
	s_add_u32 s82, s82, 0x4000
	s_addc_u32 s83, s83, 0
	s_add_u32 s76, s76, 0x400
	s_mov_b32 m0, s76
	s_nop 0
	global_load_lds_dwordx4 v185, s[82:83]
	s_add_u32 s82, s82, 0x4000
	s_addc_u32 s83, s83, 0
	s_add_u32 s76, s76, 0x400
	s_mov_b32 m0, s76
	s_nop 0
	global_load_lds_dwordx4 v177, s[82:83]
	s_add_u32 s82, s82, 0x4000
	s_addc_u32 s83, s83, 0
	s_add_u32 s76, s76, 0x400
	s_mov_b32 m0, s76
	s_nop 0
	global_load_lds_dwordx4 v185, s[82:83]
	s_add_u32 s82, s82, 0x4000
	s_addc_u32 s83, s83, 0
	s_add_u32 s76, s76, 0x400
	v_mul_f32_e32 v172, 0xbfb8aa3b, v172
	v_mul_f32_e32 v173, 0xbfb8aa3b, v173
	v_mul_f32_e32 v174, 0xbfb8aa3b, v174
	v_mul_f32_e32 v175, 0xbfb8aa3b, v175
	s_waitcnt vmcnt(8)
	v_mul_f32_e32 v198, 0xbfb8aa3b, v198
	v_mul_f32_e32 v199, 0xbfb8aa3b, v199
	v_mul_f32_e32 v200, 0xbfb8aa3b, v200
	v_mul_f32_e32 v201, 0xbfb8aa3b, v201
	v_mul_f32_e32 v202, 0xbfb8aa3b, v202
	v_mul_f32_e32 v203, 0xbfb8aa3b, v203
	v_mul_f32_e32 v204, 0xbfb8aa3b, v204
	v_mul_f32_e32 v205, 0xbfb8aa3b, v205
	v_mul_f32_e32 v206, 0xbfb8aa3b, v206
	v_mul_f32_e32 v207, 0xbfb8aa3b, v207
	v_mul_f32_e32 v208, 0xbfb8aa3b, v208
	v_mul_f32_e32 v209, 0xbfb8aa3b, v209
	v_mul_f32_e32 v210, 0xbfb8aa3b, v210
	v_mul_f32_e32 v211, 0xbfb8aa3b, v211
	v_mul_f32_e32 v212, 0xbfb8aa3b, v212
	v_mul_f32_e32 v213, 0xbfb8aa3b, v213
	v_mul_f32_e32 v214, 0xbfb8aa3b, v214
	v_mul_f32_e32 v215, 0xbfb8aa3b, v215
	v_mul_f32_e32 v216, 0xbfb8aa3b, v216
	v_mul_f32_e32 v217, 0xbfb8aa3b, v217
	v_mul_f32_e32 v218, 0xbfb8aa3b, v218
	v_mul_f32_e32 v219, 0xbfb8aa3b, v219
	v_mul_f32_e32 v220, 0xbfb8aa3b, v220
	v_mul_f32_e32 v221, 0xbfb8aa3b, v221
	v_mul_f32_e32 v222, 0xbfb8aa3b, v222
	v_mul_f32_e32 v223, 0xbfb8aa3b, v223
	v_mul_f32_e32 v224, 0xbfb8aa3b, v224
	v_mul_f32_e32 v225, 0xbfb8aa3b, v225
	v_mul_f32_e32 v226, 0xbfb8aa3b, v226
	v_mul_f32_e32 v227, 0xbfb8aa3b, v227
	v_mul_f32_e32 v228, 0xbfb8aa3b, v228
	v_mul_f32_e32 v229, 0xbfb8aa3b, v229
	v_pk_fma_f32 v[0:1], v[0:1], v[172:173], v[198:199] op_sel_hi:[1,0,1]
	v_pk_fma_f32 v[2:3], v[2:3], v[172:173], v[200:201] op_sel_hi:[1,0,1]
	v_pk_fma_f32 v[4:5], v[4:5], v[172:173], v[202:203] op_sel_hi:[1,0,1]
	v_pk_fma_f32 v[6:7], v[6:7], v[172:173], v[204:205] op_sel_hi:[1,0,1]
	v_pk_fma_f32 v[8:9], v[8:9], v[172:173], v[206:207] op_sel_hi:[1,0,1]
	v_pk_fma_f32 v[10:11], v[10:11], v[172:173], v[208:209] op_sel_hi:[1,0,1]
	v_pk_fma_f32 v[12:13], v[12:13], v[172:173], v[210:211] op_sel_hi:[1,0,1]
	v_pk_fma_f32 v[14:15], v[14:15], v[172:173], v[212:213] op_sel_hi:[1,0,1]
	v_pk_fma_f32 v[16:17], v[16:17], v[172:173], v[214:215] op_sel_hi:[1,0,1]
	v_pk_fma_f32 v[18:19], v[18:19], v[172:173], v[216:217] op_sel_hi:[1,0,1]
	v_pk_fma_f32 v[20:21], v[20:21], v[172:173], v[218:219] op_sel_hi:[1,0,1]
	v_pk_fma_f32 v[22:23], v[22:23], v[172:173], v[220:221] op_sel_hi:[1,0,1]
	v_pk_fma_f32 v[24:25], v[24:25], v[172:173], v[222:223] op_sel_hi:[1,0,1]
	v_pk_fma_f32 v[26:27], v[26:27], v[172:173], v[224:225] op_sel_hi:[1,0,1]
	v_pk_fma_f32 v[28:29], v[28:29], v[172:173], v[226:227] op_sel_hi:[1,0,1]
	v_pk_fma_f32 v[30:31], v[30:31], v[172:173], v[228:229] op_sel_hi:[1,0,1]
	v_exp_f32_e32 v0, v0
	v_exp_f32_e32 v1, v1
	v_exp_f32_e32 v2, v2
	v_exp_f32_e32 v3, v3
	v_exp_f32_e32 v4, v4
	v_exp_f32_e32 v5, v5
	v_exp_f32_e32 v6, v6
	v_exp_f32_e32 v7, v7
	v_exp_f32_e32 v8, v8
	v_exp_f32_e32 v9, v9
	v_exp_f32_e32 v10, v10
	v_exp_f32_e32 v11, v11
	v_exp_f32_e32 v12, v12
	v_exp_f32_e32 v13, v13
	v_exp_f32_e32 v14, v14
	v_exp_f32_e32 v15, v15
	v_exp_f32_e32 v16, v16
	v_exp_f32_e32 v17, v17
	v_exp_f32_e32 v18, v18
	v_exp_f32_e32 v19, v19
	v_exp_f32_e32 v20, v20
	v_exp_f32_e32 v21, v21
	v_exp_f32_e32 v22, v22
	v_exp_f32_e32 v23, v23
	v_exp_f32_e32 v24, v24
	v_exp_f32_e32 v25, v25
	v_exp_f32_e32 v26, v26
	v_exp_f32_e32 v27, v27
	v_exp_f32_e32 v28, v28
	v_exp_f32_e32 v29, v29
	v_exp_f32_e32 v30, v30
	v_exp_f32_e32 v31, v31
	v_pk_add_f32 v[0:1], v[0:1], 1.0 op_sel_hi:[1,0]
	v_pk_add_f32 v[2:3], v[2:3], 1.0 op_sel_hi:[1,0]
	v_pk_add_f32 v[4:5], v[4:5], 1.0 op_sel_hi:[1,0]
	v_pk_add_f32 v[6:7], v[6:7], 1.0 op_sel_hi:[1,0]
	v_pk_add_f32 v[8:9], v[8:9], 1.0 op_sel_hi:[1,0]
	v_pk_add_f32 v[10:11], v[10:11], 1.0 op_sel_hi:[1,0]
	v_pk_add_f32 v[12:13], v[12:13], 1.0 op_sel_hi:[1,0]
	v_pk_add_f32 v[14:15], v[14:15], 1.0 op_sel_hi:[1,0]
	v_pk_add_f32 v[16:17], v[16:17], 1.0 op_sel_hi:[1,0]
	v_pk_add_f32 v[18:19], v[18:19], 1.0 op_sel_hi:[1,0]
	v_pk_add_f32 v[20:21], v[20:21], 1.0 op_sel_hi:[1,0]
	v_pk_add_f32 v[22:23], v[22:23], 1.0 op_sel_hi:[1,0]
	v_pk_add_f32 v[24:25], v[24:25], 1.0 op_sel_hi:[1,0]
	v_pk_add_f32 v[26:27], v[26:27], 1.0 op_sel_hi:[1,0]
	v_pk_add_f32 v[28:29], v[28:29], 1.0 op_sel_hi:[1,0]
	v_pk_add_f32 v[30:31], v[30:31], 1.0 op_sel_hi:[1,0]
	v_rcp_f32_e32 v0, v0
	v_rcp_f32_e32 v1, v1
	v_rcp_f32_e32 v2, v2
	v_rcp_f32_e32 v3, v3
	v_rcp_f32_e32 v4, v4
	v_rcp_f32_e32 v5, v5
	v_rcp_f32_e32 v6, v6
	v_rcp_f32_e32 v7, v7
	v_rcp_f32_e32 v8, v8
	v_rcp_f32_e32 v9, v9
	v_rcp_f32_e32 v10, v10
	v_rcp_f32_e32 v11, v11
	v_rcp_f32_e32 v12, v12
	v_rcp_f32_e32 v13, v13
	v_rcp_f32_e32 v14, v14
	v_rcp_f32_e32 v15, v15
	v_rcp_f32_e32 v16, v16
	v_rcp_f32_e32 v17, v17
	v_rcp_f32_e32 v18, v18
	v_rcp_f32_e32 v19, v19
	v_rcp_f32_e32 v20, v20
	v_rcp_f32_e32 v21, v21
	v_rcp_f32_e32 v22, v22
	v_rcp_f32_e32 v23, v23
	v_rcp_f32_e32 v24, v24
	v_rcp_f32_e32 v25, v25
	v_rcp_f32_e32 v26, v26
	v_rcp_f32_e32 v27, v27
	v_rcp_f32_e32 v28, v28
	v_rcp_f32_e32 v29, v29
	v_rcp_f32_e32 v30, v30
	v_rcp_f32_e32 v31, v31
	s_nop 0
	v_cvt_pk_bf16_f32 v0, v0, v1
	v_cvt_pk_bf16_f32 v1, v2, v3
	v_cvt_pk_bf16_f32 v2, v4, v5
	v_cvt_pk_bf16_f32 v3, v6, v7
	v_cvt_pk_bf16_f32 v4, v8, v9
	v_cvt_pk_bf16_f32 v5, v10, v11
	v_cvt_pk_bf16_f32 v6, v12, v13
	v_cvt_pk_bf16_f32 v7, v14, v15
	v_cvt_pk_bf16_f32 v16, v16, v17
	v_cvt_pk_bf16_f32 v17, v18, v19
	v_cvt_pk_bf16_f32 v18, v20, v21
	v_cvt_pk_bf16_f32 v19, v22, v23
	v_cvt_pk_bf16_f32 v20, v24, v25
	v_cvt_pk_bf16_f32 v21, v26, v27
	v_cvt_pk_bf16_f32 v22, v28, v29
	v_cvt_pk_bf16_f32 v23, v30, v31
	v_permlane32_swap_b32_e32 v0, v2
	v_permlane32_swap_b32_e32 v1, v3
	v_permlane32_swap_b32_e32 v4, v6
	v_permlane32_swap_b32_e32 v5, v7
	v_permlane32_swap_b32_e32 v16, v18
	v_permlane32_swap_b32_e32 v17, v19
	v_permlane32_swap_b32_e32 v20, v22
	v_permlane32_swap_b32_e32 v21, v23
	s_nop 1
	s_mov_b32 vcc_lo, 0x55555555
	s_mov_b32 vcc_hi, 0x55555555
	v_cndmask_b32_dpp v128, v4, v0, vcc quad_perm:[1,0,3,2] row_mask:0xf bank_mask:0xf
	v_cndmask_b32_dpp v129, v5, v1, vcc quad_perm:[1,0,3,2] row_mask:0xf bank_mask:0xf
	v_cndmask_b32_dpp v130, v6, v2, vcc quad_perm:[1,0,3,2] row_mask:0xf bank_mask:0xf
	v_cndmask_b32_dpp v131, v7, v3, vcc quad_perm:[1,0,3,2] row_mask:0xf bank_mask:0xf
	v_cndmask_b32_dpp v136, v20, v16, vcc quad_perm:[1,0,3,2] row_mask:0xf bank_mask:0xf
	v_cndmask_b32_dpp v137, v21, v17, vcc quad_perm:[1,0,3,2] row_mask:0xf bank_mask:0xf
	v_cndmask_b32_dpp v138, v22, v18, vcc quad_perm:[1,0,3,2] row_mask:0xf bank_mask:0xf
	v_cndmask_b32_dpp v139, v23, v19, vcc quad_perm:[1,0,3,2] row_mask:0xf bank_mask:0xf
	s_mov_b32 vcc_lo, 0xaaaaaaaa
	s_mov_b32 vcc_hi, 0xaaaaaaaa
	v_cndmask_b32_dpp v132, v0, v4, vcc quad_perm:[1,0,3,2] row_mask:0xf bank_mask:0xf
	v_cndmask_b32_dpp v133, v1, v5, vcc quad_perm:[1,0,3,2] row_mask:0xf bank_mask:0xf
	v_cndmask_b32_dpp v134, v2, v6, vcc quad_perm:[1,0,3,2] row_mask:0xf bank_mask:0xf
	v_cndmask_b32_dpp v135, v3, v7, vcc quad_perm:[1,0,3,2] row_mask:0xf bank_mask:0xf
	v_cndmask_b32_dpp v140, v16, v20, vcc quad_perm:[1,0,3,2] row_mask:0xf bank_mask:0xf
	v_cndmask_b32_dpp v141, v17, v21, vcc quad_perm:[1,0,3,2] row_mask:0xf bank_mask:0xf
	v_cndmask_b32_dpp v142, v18, v22, vcc quad_perm:[1,0,3,2] row_mask:0xf bank_mask:0xf
	v_cndmask_b32_dpp v143, v19, v23, vcc quad_perm:[1,0,3,2] row_mask:0xf bank_mask:0xf
	s_nop 1
	s_mov_b32 vcc_lo, 0x33333333
	s_mov_b32 vcc_hi, 0x33333333
	v_cndmask_b32_dpp v0, v136, v128, vcc quad_perm:[2,3,0,1] row_mask:0xf bank_mask:0xf
	v_cndmask_b32_dpp v1, v137, v129, vcc quad_perm:[2,3,0,1] row_mask:0xf bank_mask:0xf
	v_cndmask_b32_dpp v2, v138, v130, vcc quad_perm:[2,3,0,1] row_mask:0xf bank_mask:0xf
	v_cndmask_b32_dpp v3, v139, v131, vcc quad_perm:[2,3,0,1] row_mask:0xf bank_mask:0xf
	v_cndmask_b32_dpp v4, v140, v132, vcc quad_perm:[2,3,0,1] row_mask:0xf bank_mask:0xf
	v_cndmask_b32_dpp v5, v141, v133, vcc quad_perm:[2,3,0,1] row_mask:0xf bank_mask:0xf
	v_cndmask_b32_dpp v6, v142, v134, vcc quad_perm:[2,3,0,1] row_mask:0xf bank_mask:0xf
	v_cndmask_b32_dpp v7, v143, v135, vcc quad_perm:[2,3,0,1] row_mask:0xf bank_mask:0xf
	s_mov_b32 vcc_lo, 0xcccccccc
	s_mov_b32 vcc_hi, 0xcccccccc
	v_cndmask_b32_dpp v16, v128, v136, vcc quad_perm:[2,3,0,1] row_mask:0xf bank_mask:0xf
	v_cndmask_b32_dpp v17, v129, v137, vcc quad_perm:[2,3,0,1] row_mask:0xf bank_mask:0xf
	v_cndmask_b32_dpp v18, v130, v138, vcc quad_perm:[2,3,0,1] row_mask:0xf bank_mask:0xf
	v_cndmask_b32_dpp v19, v131, v139, vcc quad_perm:[2,3,0,1] row_mask:0xf bank_mask:0xf
	v_cndmask_b32_dpp v20, v132, v140, vcc quad_perm:[2,3,0,1] row_mask:0xf bank_mask:0xf
	v_cndmask_b32_dpp v21, v133, v141, vcc quad_perm:[2,3,0,1] row_mask:0xf bank_mask:0xf
	v_cndmask_b32_dpp v22, v134, v142, vcc quad_perm:[2,3,0,1] row_mask:0xf bank_mask:0xf
	v_cndmask_b32_dpp v23, v135, v143, vcc quad_perm:[2,3,0,1] row_mask:0xf bank_mask:0xf
	s_add_u32 s76, s74, 0x0
	s_addc_u32 s77, s75, 0
	global_store_dwordx4 v181, v[0:3], s[76:77]
	s_add_u32 s76, s74, 0x2200
	s_addc_u32 s77, s75, 0
	global_store_dwordx4 v181, v[4:7], s[76:77]
	s_add_u32 s76, s74, 0x4400
	s_addc_u32 s77, s75, 0
	global_store_dwordx4 v181, v[16:19], s[76:77]
	s_add_u32 s76, s74, 0x6600
	s_addc_u32 s77, s75, 0
	global_store_dwordx4 v181, v[20:23], s[76:77]
	s_add_u32 s74, s74, 0x44000
	s_addc_u32 s75, s75, 0
	v_pk_fma_f32 v[32:33], v[32:33], v[172:173], v[198:199] op_sel:[0,1,0] op_sel_hi:[1,1,1]
	v_pk_fma_f32 v[34:35], v[34:35], v[172:173], v[200:201] op_sel:[0,1,0] op_sel_hi:[1,1,1]
	v_pk_fma_f32 v[36:37], v[36:37], v[172:173], v[202:203] op_sel:[0,1,0] op_sel_hi:[1,1,1]
	v_pk_fma_f32 v[38:39], v[38:39], v[172:173], v[204:205] op_sel:[0,1,0] op_sel_hi:[1,1,1]
	v_pk_fma_f32 v[40:41], v[40:41], v[172:173], v[206:207] op_sel:[0,1,0] op_sel_hi:[1,1,1]
	v_pk_fma_f32 v[42:43], v[42:43], v[172:173], v[208:209] op_sel:[0,1,0] op_sel_hi:[1,1,1]
	v_pk_fma_f32 v[44:45], v[44:45], v[172:173], v[210:211] op_sel:[0,1,0] op_sel_hi:[1,1,1]
	v_pk_fma_f32 v[46:47], v[46:47], v[172:173], v[212:213] op_sel:[0,1,0] op_sel_hi:[1,1,1]
	v_pk_fma_f32 v[48:49], v[48:49], v[172:173], v[214:215] op_sel:[0,1,0] op_sel_hi:[1,1,1]
	v_pk_fma_f32 v[50:51], v[50:51], v[172:173], v[216:217] op_sel:[0,1,0] op_sel_hi:[1,1,1]
	v_pk_fma_f32 v[52:53], v[52:53], v[172:173], v[218:219] op_sel:[0,1,0] op_sel_hi:[1,1,1]
	v_pk_fma_f32 v[54:55], v[54:55], v[172:173], v[220:221] op_sel:[0,1,0] op_sel_hi:[1,1,1]
	v_pk_fma_f32 v[56:57], v[56:57], v[172:173], v[222:223] op_sel:[0,1,0] op_sel_hi:[1,1,1]
	v_pk_fma_f32 v[58:59], v[58:59], v[172:173], v[224:225] op_sel:[0,1,0] op_sel_hi:[1,1,1]
	v_pk_fma_f32 v[60:61], v[60:61], v[172:173], v[226:227] op_sel:[0,1,0] op_sel_hi:[1,1,1]
	v_pk_fma_f32 v[62:63], v[62:63], v[172:173], v[228:229] op_sel:[0,1,0] op_sel_hi:[1,1,1]
	v_exp_f32_e32 v32, v32
	v_exp_f32_e32 v33, v33
	v_exp_f32_e32 v34, v34
	v_exp_f32_e32 v35, v35
	v_exp_f32_e32 v36, v36
	v_exp_f32_e32 v37, v37
	v_exp_f32_e32 v38, v38
	v_exp_f32_e32 v39, v39
	v_exp_f32_e32 v40, v40
	v_exp_f32_e32 v41, v41
	v_exp_f32_e32 v42, v42
	v_exp_f32_e32 v43, v43
	v_exp_f32_e32 v44, v44
	v_exp_f32_e32 v45, v45
	v_exp_f32_e32 v46, v46
	v_exp_f32_e32 v47, v47
	v_exp_f32_e32 v48, v48
	v_exp_f32_e32 v49, v49
	v_exp_f32_e32 v50, v50
	v_exp_f32_e32 v51, v51
	v_exp_f32_e32 v52, v52
	v_exp_f32_e32 v53, v53
	v_exp_f32_e32 v54, v54
	v_exp_f32_e32 v55, v55
	v_exp_f32_e32 v56, v56
	v_exp_f32_e32 v57, v57
	v_exp_f32_e32 v58, v58
	v_exp_f32_e32 v59, v59
	v_exp_f32_e32 v60, v60
	v_exp_f32_e32 v61, v61
	v_exp_f32_e32 v62, v62
	v_exp_f32_e32 v63, v63
	v_pk_add_f32 v[32:33], v[32:33], 1.0 op_sel_hi:[1,0]
	v_pk_add_f32 v[34:35], v[34:35], 1.0 op_sel_hi:[1,0]
	v_pk_add_f32 v[36:37], v[36:37], 1.0 op_sel_hi:[1,0]
	v_pk_add_f32 v[38:39], v[38:39], 1.0 op_sel_hi:[1,0]
	v_pk_add_f32 v[40:41], v[40:41], 1.0 op_sel_hi:[1,0]
	v_pk_add_f32 v[42:43], v[42:43], 1.0 op_sel_hi:[1,0]
	v_pk_add_f32 v[44:45], v[44:45], 1.0 op_sel_hi:[1,0]
	v_pk_add_f32 v[46:47], v[46:47], 1.0 op_sel_hi:[1,0]
	v_pk_add_f32 v[48:49], v[48:49], 1.0 op_sel_hi:[1,0]
	v_pk_add_f32 v[50:51], v[50:51], 1.0 op_sel_hi:[1,0]
	v_pk_add_f32 v[52:53], v[52:53], 1.0 op_sel_hi:[1,0]
	v_pk_add_f32 v[54:55], v[54:55], 1.0 op_sel_hi:[1,0]
	v_pk_add_f32 v[56:57], v[56:57], 1.0 op_sel_hi:[1,0]
	v_pk_add_f32 v[58:59], v[58:59], 1.0 op_sel_hi:[1,0]
	v_pk_add_f32 v[60:61], v[60:61], 1.0 op_sel_hi:[1,0]
	v_pk_add_f32 v[62:63], v[62:63], 1.0 op_sel_hi:[1,0]
	v_rcp_f32_e32 v32, v32
	v_rcp_f32_e32 v33, v33
	v_rcp_f32_e32 v34, v34
	v_rcp_f32_e32 v35, v35
	v_rcp_f32_e32 v36, v36
	v_rcp_f32_e32 v37, v37
	v_rcp_f32_e32 v38, v38
	v_rcp_f32_e32 v39, v39
	v_rcp_f32_e32 v40, v40
	v_rcp_f32_e32 v41, v41
	v_rcp_f32_e32 v42, v42
	v_rcp_f32_e32 v43, v43
	v_rcp_f32_e32 v44, v44
	v_rcp_f32_e32 v45, v45
	v_rcp_f32_e32 v46, v46
	v_rcp_f32_e32 v47, v47
	v_rcp_f32_e32 v48, v48
	v_rcp_f32_e32 v49, v49
	v_rcp_f32_e32 v50, v50
	v_rcp_f32_e32 v51, v51
	v_rcp_f32_e32 v52, v52
	v_rcp_f32_e32 v53, v53
	v_rcp_f32_e32 v54, v54
	v_rcp_f32_e32 v55, v55
	v_rcp_f32_e32 v56, v56
	v_rcp_f32_e32 v57, v57
	v_rcp_f32_e32 v58, v58
	v_rcp_f32_e32 v59, v59
	v_rcp_f32_e32 v60, v60
	v_rcp_f32_e32 v61, v61
	v_rcp_f32_e32 v62, v62
	v_rcp_f32_e32 v63, v63
	s_nop 0
	v_cvt_pk_bf16_f32 v32, v32, v33
	v_cvt_pk_bf16_f32 v33, v34, v35
	v_cvt_pk_bf16_f32 v34, v36, v37
	v_cvt_pk_bf16_f32 v35, v38, v39
	v_cvt_pk_bf16_f32 v36, v40, v41
	v_cvt_pk_bf16_f32 v37, v42, v43
	v_cvt_pk_bf16_f32 v38, v44, v45
	v_cvt_pk_bf16_f32 v39, v46, v47
	v_cvt_pk_bf16_f32 v48, v48, v49
	v_cvt_pk_bf16_f32 v49, v50, v51
	v_cvt_pk_bf16_f32 v50, v52, v53
	v_cvt_pk_bf16_f32 v51, v54, v55
	v_cvt_pk_bf16_f32 v52, v56, v57
	v_cvt_pk_bf16_f32 v53, v58, v59
	v_cvt_pk_bf16_f32 v54, v60, v61
	v_cvt_pk_bf16_f32 v55, v62, v63
	v_permlane32_swap_b32_e32 v32, v34
	v_permlane32_swap_b32_e32 v33, v35
	v_permlane32_swap_b32_e32 v36, v38
	v_permlane32_swap_b32_e32 v37, v39
	v_permlane32_swap_b32_e32 v48, v50
	v_permlane32_swap_b32_e32 v49, v51
	v_permlane32_swap_b32_e32 v52, v54
	v_permlane32_swap_b32_e32 v53, v55
	s_nop 1
	s_mov_b32 vcc_lo, 0x55555555
	s_mov_b32 vcc_hi, 0x55555555
	v_cndmask_b32_dpp v128, v36, v32, vcc quad_perm:[1,0,3,2] row_mask:0xf bank_mask:0xf
	v_cndmask_b32_dpp v129, v37, v33, vcc quad_perm:[1,0,3,2] row_mask:0xf bank_mask:0xf
	v_cndmask_b32_dpp v130, v38, v34, vcc quad_perm:[1,0,3,2] row_mask:0xf bank_mask:0xf
	v_cndmask_b32_dpp v131, v39, v35, vcc quad_perm:[1,0,3,2] row_mask:0xf bank_mask:0xf
	v_cndmask_b32_dpp v136, v52, v48, vcc quad_perm:[1,0,3,2] row_mask:0xf bank_mask:0xf
	v_cndmask_b32_dpp v137, v53, v49, vcc quad_perm:[1,0,3,2] row_mask:0xf bank_mask:0xf
	v_cndmask_b32_dpp v138, v54, v50, vcc quad_perm:[1,0,3,2] row_mask:0xf bank_mask:0xf
	v_cndmask_b32_dpp v139, v55, v51, vcc quad_perm:[1,0,3,2] row_mask:0xf bank_mask:0xf
	s_mov_b32 vcc_lo, 0xaaaaaaaa
	s_mov_b32 vcc_hi, 0xaaaaaaaa
	v_cndmask_b32_dpp v132, v32, v36, vcc quad_perm:[1,0,3,2] row_mask:0xf bank_mask:0xf
	v_cndmask_b32_dpp v133, v33, v37, vcc quad_perm:[1,0,3,2] row_mask:0xf bank_mask:0xf
	v_cndmask_b32_dpp v134, v34, v38, vcc quad_perm:[1,0,3,2] row_mask:0xf bank_mask:0xf
	v_cndmask_b32_dpp v135, v35, v39, vcc quad_perm:[1,0,3,2] row_mask:0xf bank_mask:0xf
	v_cndmask_b32_dpp v140, v48, v52, vcc quad_perm:[1,0,3,2] row_mask:0xf bank_mask:0xf
	v_cndmask_b32_dpp v141, v49, v53, vcc quad_perm:[1,0,3,2] row_mask:0xf bank_mask:0xf
	v_cndmask_b32_dpp v142, v50, v54, vcc quad_perm:[1,0,3,2] row_mask:0xf bank_mask:0xf
	v_cndmask_b32_dpp v143, v51, v55, vcc quad_perm:[1,0,3,2] row_mask:0xf bank_mask:0xf
	s_nop 1
	s_mov_b32 vcc_lo, 0x33333333
	s_mov_b32 vcc_hi, 0x33333333
	v_cndmask_b32_dpp v32, v136, v128, vcc quad_perm:[2,3,0,1] row_mask:0xf bank_mask:0xf
	v_cndmask_b32_dpp v33, v137, v129, vcc quad_perm:[2,3,0,1] row_mask:0xf bank_mask:0xf
	v_cndmask_b32_dpp v34, v138, v130, vcc quad_perm:[2,3,0,1] row_mask:0xf bank_mask:0xf
	v_cndmask_b32_dpp v35, v139, v131, vcc quad_perm:[2,3,0,1] row_mask:0xf bank_mask:0xf
	v_cndmask_b32_dpp v36, v140, v132, vcc quad_perm:[2,3,0,1] row_mask:0xf bank_mask:0xf
	v_cndmask_b32_dpp v37, v141, v133, vcc quad_perm:[2,3,0,1] row_mask:0xf bank_mask:0xf
	v_cndmask_b32_dpp v38, v142, v134, vcc quad_perm:[2,3,0,1] row_mask:0xf bank_mask:0xf
	v_cndmask_b32_dpp v39, v143, v135, vcc quad_perm:[2,3,0,1] row_mask:0xf bank_mask:0xf
	s_mov_b32 vcc_lo, 0xcccccccc
	s_mov_b32 vcc_hi, 0xcccccccc
	v_cndmask_b32_dpp v48, v128, v136, vcc quad_perm:[2,3,0,1] row_mask:0xf bank_mask:0xf
	v_cndmask_b32_dpp v49, v129, v137, vcc quad_perm:[2,3,0,1] row_mask:0xf bank_mask:0xf
	v_cndmask_b32_dpp v50, v130, v138, vcc quad_perm:[2,3,0,1] row_mask:0xf bank_mask:0xf
	v_cndmask_b32_dpp v51, v131, v139, vcc quad_perm:[2,3,0,1] row_mask:0xf bank_mask:0xf
	v_cndmask_b32_dpp v52, v132, v140, vcc quad_perm:[2,3,0,1] row_mask:0xf bank_mask:0xf
	v_cndmask_b32_dpp v53, v133, v141, vcc quad_perm:[2,3,0,1] row_mask:0xf bank_mask:0xf
	v_cndmask_b32_dpp v54, v134, v142, vcc quad_perm:[2,3,0,1] row_mask:0xf bank_mask:0xf
	v_cndmask_b32_dpp v55, v135, v143, vcc quad_perm:[2,3,0,1] row_mask:0xf bank_mask:0xf
	s_add_u32 s76, s74, 0x0
	s_addc_u32 s77, s75, 0
	global_store_dwordx4 v181, v[32:35], s[76:77]
	s_add_u32 s76, s74, 0x2200
	s_addc_u32 s77, s75, 0
	global_store_dwordx4 v181, v[36:39], s[76:77]
	s_add_u32 s76, s74, 0x4400
	s_addc_u32 s77, s75, 0
	global_store_dwordx4 v181, v[48:51], s[76:77]
	s_add_u32 s76, s74, 0x6600
	s_addc_u32 s77, s75, 0
	global_store_dwordx4 v181, v[52:55], s[76:77]
	s_add_u32 s74, s74, 0x44000
	s_addc_u32 s75, s75, 0
	v_pk_fma_f32 v[64:65], v[64:65], v[174:175], v[198:199] op_sel_hi:[1,0,1]
	v_pk_fma_f32 v[66:67], v[66:67], v[174:175], v[200:201] op_sel_hi:[1,0,1]
	v_pk_fma_f32 v[68:69], v[68:69], v[174:175], v[202:203] op_sel_hi:[1,0,1]
	v_pk_fma_f32 v[70:71], v[70:71], v[174:175], v[204:205] op_sel_hi:[1,0,1]
	v_pk_fma_f32 v[72:73], v[72:73], v[174:175], v[206:207] op_sel_hi:[1,0,1]
	v_pk_fma_f32 v[74:75], v[74:75], v[174:175], v[208:209] op_sel_hi:[1,0,1]
	v_pk_fma_f32 v[76:77], v[76:77], v[174:175], v[210:211] op_sel_hi:[1,0,1]
	v_pk_fma_f32 v[78:79], v[78:79], v[174:175], v[212:213] op_sel_hi:[1,0,1]
	v_pk_fma_f32 v[80:81], v[80:81], v[174:175], v[214:215] op_sel_hi:[1,0,1]
	v_pk_fma_f32 v[82:83], v[82:83], v[174:175], v[216:217] op_sel_hi:[1,0,1]
	v_pk_fma_f32 v[84:85], v[84:85], v[174:175], v[218:219] op_sel_hi:[1,0,1]
	v_pk_fma_f32 v[86:87], v[86:87], v[174:175], v[220:221] op_sel_hi:[1,0,1]
	v_pk_fma_f32 v[88:89], v[88:89], v[174:175], v[222:223] op_sel_hi:[1,0,1]
	v_pk_fma_f32 v[90:91], v[90:91], v[174:175], v[224:225] op_sel_hi:[1,0,1]
	v_pk_fma_f32 v[92:93], v[92:93], v[174:175], v[226:227] op_sel_hi:[1,0,1]
	v_pk_fma_f32 v[94:95], v[94:95], v[174:175], v[228:229] op_sel_hi:[1,0,1]
	v_exp_f32_e32 v64, v64
	v_exp_f32_e32 v65, v65
	v_exp_f32_e32 v66, v66
	v_exp_f32_e32 v67, v67
	v_exp_f32_e32 v68, v68
	v_exp_f32_e32 v69, v69
	v_exp_f32_e32 v70, v70
	v_exp_f32_e32 v71, v71
	v_exp_f32_e32 v72, v72
	v_exp_f32_e32 v73, v73
	v_exp_f32_e32 v74, v74
	v_exp_f32_e32 v75, v75
	v_exp_f32_e32 v76, v76
	v_exp_f32_e32 v77, v77
	v_exp_f32_e32 v78, v78
	v_exp_f32_e32 v79, v79
	v_exp_f32_e32 v80, v80
	v_exp_f32_e32 v81, v81
	v_exp_f32_e32 v82, v82
	v_exp_f32_e32 v83, v83
	v_exp_f32_e32 v84, v84
	v_exp_f32_e32 v85, v85
	v_exp_f32_e32 v86, v86
	v_exp_f32_e32 v87, v87
	v_exp_f32_e32 v88, v88
	v_exp_f32_e32 v89, v89
	v_exp_f32_e32 v90, v90
	v_exp_f32_e32 v91, v91
	v_exp_f32_e32 v92, v92
	v_exp_f32_e32 v93, v93
	v_exp_f32_e32 v94, v94
	v_exp_f32_e32 v95, v95
	v_pk_add_f32 v[64:65], v[64:65], 1.0 op_sel_hi:[1,0]
	v_pk_add_f32 v[66:67], v[66:67], 1.0 op_sel_hi:[1,0]
	v_pk_add_f32 v[68:69], v[68:69], 1.0 op_sel_hi:[1,0]
	v_pk_add_f32 v[70:71], v[70:71], 1.0 op_sel_hi:[1,0]
	v_pk_add_f32 v[72:73], v[72:73], 1.0 op_sel_hi:[1,0]
	v_pk_add_f32 v[74:75], v[74:75], 1.0 op_sel_hi:[1,0]
	v_pk_add_f32 v[76:77], v[76:77], 1.0 op_sel_hi:[1,0]
	v_pk_add_f32 v[78:79], v[78:79], 1.0 op_sel_hi:[1,0]
	v_pk_add_f32 v[80:81], v[80:81], 1.0 op_sel_hi:[1,0]
	v_pk_add_f32 v[82:83], v[82:83], 1.0 op_sel_hi:[1,0]
	v_pk_add_f32 v[84:85], v[84:85], 1.0 op_sel_hi:[1,0]
	v_pk_add_f32 v[86:87], v[86:87], 1.0 op_sel_hi:[1,0]
	v_pk_add_f32 v[88:89], v[88:89], 1.0 op_sel_hi:[1,0]
	v_pk_add_f32 v[90:91], v[90:91], 1.0 op_sel_hi:[1,0]
	v_pk_add_f32 v[92:93], v[92:93], 1.0 op_sel_hi:[1,0]
	v_pk_add_f32 v[94:95], v[94:95], 1.0 op_sel_hi:[1,0]
	v_rcp_f32_e32 v64, v64
	v_rcp_f32_e32 v65, v65
	v_rcp_f32_e32 v66, v66
	v_rcp_f32_e32 v67, v67
	v_rcp_f32_e32 v68, v68
	v_rcp_f32_e32 v69, v69
	v_rcp_f32_e32 v70, v70
	v_rcp_f32_e32 v71, v71
	v_rcp_f32_e32 v72, v72
	v_rcp_f32_e32 v73, v73
	v_rcp_f32_e32 v74, v74
	v_rcp_f32_e32 v75, v75
	v_rcp_f32_e32 v76, v76
	v_rcp_f32_e32 v77, v77
	v_rcp_f32_e32 v78, v78
	v_rcp_f32_e32 v79, v79
	v_rcp_f32_e32 v80, v80
	v_rcp_f32_e32 v81, v81
	v_rcp_f32_e32 v82, v82
	v_rcp_f32_e32 v83, v83
	v_rcp_f32_e32 v84, v84
	v_rcp_f32_e32 v85, v85
	v_rcp_f32_e32 v86, v86
	v_rcp_f32_e32 v87, v87
	v_rcp_f32_e32 v88, v88
	v_rcp_f32_e32 v89, v89
	v_rcp_f32_e32 v90, v90
	v_rcp_f32_e32 v91, v91
	v_rcp_f32_e32 v92, v92
	v_rcp_f32_e32 v93, v93
	v_rcp_f32_e32 v94, v94
	v_rcp_f32_e32 v95, v95
	s_nop 0
	v_cvt_pk_bf16_f32 v64, v64, v65
	v_cvt_pk_bf16_f32 v65, v66, v67
	v_cvt_pk_bf16_f32 v66, v68, v69
	v_cvt_pk_bf16_f32 v67, v70, v71
	v_cvt_pk_bf16_f32 v68, v72, v73
	v_cvt_pk_bf16_f32 v69, v74, v75
	v_cvt_pk_bf16_f32 v70, v76, v77
	v_cvt_pk_bf16_f32 v71, v78, v79
	v_cvt_pk_bf16_f32 v80, v80, v81
	v_cvt_pk_bf16_f32 v81, v82, v83
	v_cvt_pk_bf16_f32 v82, v84, v85
	v_cvt_pk_bf16_f32 v83, v86, v87
	v_cvt_pk_bf16_f32 v84, v88, v89
	v_cvt_pk_bf16_f32 v85, v90, v91
	v_cvt_pk_bf16_f32 v86, v92, v93
	v_cvt_pk_bf16_f32 v87, v94, v95
	v_permlane32_swap_b32_e32 v64, v66
	v_permlane32_swap_b32_e32 v65, v67
	v_permlane32_swap_b32_e32 v68, v70
	v_permlane32_swap_b32_e32 v69, v71
	v_permlane32_swap_b32_e32 v80, v82
	v_permlane32_swap_b32_e32 v81, v83
	v_permlane32_swap_b32_e32 v84, v86
	v_permlane32_swap_b32_e32 v85, v87
	s_nop 1
	s_mov_b32 vcc_lo, 0x55555555
	s_mov_b32 vcc_hi, 0x55555555
	v_cndmask_b32_dpp v128, v68, v64, vcc quad_perm:[1,0,3,2] row_mask:0xf bank_mask:0xf
	v_cndmask_b32_dpp v129, v69, v65, vcc quad_perm:[1,0,3,2] row_mask:0xf bank_mask:0xf
	v_cndmask_b32_dpp v130, v70, v66, vcc quad_perm:[1,0,3,2] row_mask:0xf bank_mask:0xf
	v_cndmask_b32_dpp v131, v71, v67, vcc quad_perm:[1,0,3,2] row_mask:0xf bank_mask:0xf
	v_cndmask_b32_dpp v136, v84, v80, vcc quad_perm:[1,0,3,2] row_mask:0xf bank_mask:0xf
	v_cndmask_b32_dpp v137, v85, v81, vcc quad_perm:[1,0,3,2] row_mask:0xf bank_mask:0xf
	v_cndmask_b32_dpp v138, v86, v82, vcc quad_perm:[1,0,3,2] row_mask:0xf bank_mask:0xf
	v_cndmask_b32_dpp v139, v87, v83, vcc quad_perm:[1,0,3,2] row_mask:0xf bank_mask:0xf
	s_mov_b32 vcc_lo, 0xaaaaaaaa
	s_mov_b32 vcc_hi, 0xaaaaaaaa
	v_cndmask_b32_dpp v132, v64, v68, vcc quad_perm:[1,0,3,2] row_mask:0xf bank_mask:0xf
	v_cndmask_b32_dpp v133, v65, v69, vcc quad_perm:[1,0,3,2] row_mask:0xf bank_mask:0xf
	v_cndmask_b32_dpp v134, v66, v70, vcc quad_perm:[1,0,3,2] row_mask:0xf bank_mask:0xf
	v_cndmask_b32_dpp v135, v67, v71, vcc quad_perm:[1,0,3,2] row_mask:0xf bank_mask:0xf
	v_cndmask_b32_dpp v140, v80, v84, vcc quad_perm:[1,0,3,2] row_mask:0xf bank_mask:0xf
	v_cndmask_b32_dpp v141, v81, v85, vcc quad_perm:[1,0,3,2] row_mask:0xf bank_mask:0xf
	v_cndmask_b32_dpp v142, v82, v86, vcc quad_perm:[1,0,3,2] row_mask:0xf bank_mask:0xf
	v_cndmask_b32_dpp v143, v83, v87, vcc quad_perm:[1,0,3,2] row_mask:0xf bank_mask:0xf
	s_nop 1
	s_mov_b32 vcc_lo, 0x33333333
	s_mov_b32 vcc_hi, 0x33333333
	v_cndmask_b32_dpp v64, v136, v128, vcc quad_perm:[2,3,0,1] row_mask:0xf bank_mask:0xf
	v_cndmask_b32_dpp v65, v137, v129, vcc quad_perm:[2,3,0,1] row_mask:0xf bank_mask:0xf
	v_cndmask_b32_dpp v66, v138, v130, vcc quad_perm:[2,3,0,1] row_mask:0xf bank_mask:0xf
	v_cndmask_b32_dpp v67, v139, v131, vcc quad_perm:[2,3,0,1] row_mask:0xf bank_mask:0xf
	v_cndmask_b32_dpp v68, v140, v132, vcc quad_perm:[2,3,0,1] row_mask:0xf bank_mask:0xf
	v_cndmask_b32_dpp v69, v141, v133, vcc quad_perm:[2,3,0,1] row_mask:0xf bank_mask:0xf
	v_cndmask_b32_dpp v70, v142, v134, vcc quad_perm:[2,3,0,1] row_mask:0xf bank_mask:0xf
	v_cndmask_b32_dpp v71, v143, v135, vcc quad_perm:[2,3,0,1] row_mask:0xf bank_mask:0xf
	s_mov_b32 vcc_lo, 0xcccccccc
	s_mov_b32 vcc_hi, 0xcccccccc
	v_cndmask_b32_dpp v80, v128, v136, vcc quad_perm:[2,3,0,1] row_mask:0xf bank_mask:0xf
	v_cndmask_b32_dpp v81, v129, v137, vcc quad_perm:[2,3,0,1] row_mask:0xf bank_mask:0xf
	v_cndmask_b32_dpp v82, v130, v138, vcc quad_perm:[2,3,0,1] row_mask:0xf bank_mask:0xf
	v_cndmask_b32_dpp v83, v131, v139, vcc quad_perm:[2,3,0,1] row_mask:0xf bank_mask:0xf
	v_cndmask_b32_dpp v84, v132, v140, vcc quad_perm:[2,3,0,1] row_mask:0xf bank_mask:0xf
	v_cndmask_b32_dpp v85, v133, v141, vcc quad_perm:[2,3,0,1] row_mask:0xf bank_mask:0xf
	v_cndmask_b32_dpp v86, v134, v142, vcc quad_perm:[2,3,0,1] row_mask:0xf bank_mask:0xf
	v_cndmask_b32_dpp v87, v135, v143, vcc quad_perm:[2,3,0,1] row_mask:0xf bank_mask:0xf
	s_add_u32 s76, s74, 0x0
	s_addc_u32 s77, s75, 0
	global_store_dwordx4 v181, v[64:67], s[76:77]
	s_add_u32 s76, s74, 0x2200
	s_addc_u32 s77, s75, 0
	global_store_dwordx4 v181, v[68:71], s[76:77]
	s_add_u32 s76, s74, 0x4400
	s_addc_u32 s77, s75, 0
	global_store_dwordx4 v181, v[80:83], s[76:77]
	s_add_u32 s76, s74, 0x6600
	s_addc_u32 s77, s75, 0
	global_store_dwordx4 v181, v[84:87], s[76:77]
	s_add_u32 s74, s74, 0x44000
	s_addc_u32 s75, s75, 0
	v_pk_fma_f32 v[96:97], v[96:97], v[174:175], v[198:199] op_sel:[0,1,0] op_sel_hi:[1,1,1]
	v_pk_fma_f32 v[98:99], v[98:99], v[174:175], v[200:201] op_sel:[0,1,0] op_sel_hi:[1,1,1]
	v_pk_fma_f32 v[100:101], v[100:101], v[174:175], v[202:203] op_sel:[0,1,0] op_sel_hi:[1,1,1]
	v_pk_fma_f32 v[102:103], v[102:103], v[174:175], v[204:205] op_sel:[0,1,0] op_sel_hi:[1,1,1]
	v_pk_fma_f32 v[104:105], v[104:105], v[174:175], v[206:207] op_sel:[0,1,0] op_sel_hi:[1,1,1]
	v_pk_fma_f32 v[106:107], v[106:107], v[174:175], v[208:209] op_sel:[0,1,0] op_sel_hi:[1,1,1]
	v_pk_fma_f32 v[108:109], v[108:109], v[174:175], v[210:211] op_sel:[0,1,0] op_sel_hi:[1,1,1]
	v_pk_fma_f32 v[110:111], v[110:111], v[174:175], v[212:213] op_sel:[0,1,0] op_sel_hi:[1,1,1]
	v_pk_fma_f32 v[112:113], v[112:113], v[174:175], v[214:215] op_sel:[0,1,0] op_sel_hi:[1,1,1]
	v_pk_fma_f32 v[114:115], v[114:115], v[174:175], v[216:217] op_sel:[0,1,0] op_sel_hi:[1,1,1]
	v_pk_fma_f32 v[116:117], v[116:117], v[174:175], v[218:219] op_sel:[0,1,0] op_sel_hi:[1,1,1]
	v_pk_fma_f32 v[118:119], v[118:119], v[174:175], v[220:221] op_sel:[0,1,0] op_sel_hi:[1,1,1]
	v_pk_fma_f32 v[120:121], v[120:121], v[174:175], v[222:223] op_sel:[0,1,0] op_sel_hi:[1,1,1]
	v_pk_fma_f32 v[122:123], v[122:123], v[174:175], v[224:225] op_sel:[0,1,0] op_sel_hi:[1,1,1]
	v_pk_fma_f32 v[124:125], v[124:125], v[174:175], v[226:227] op_sel:[0,1,0] op_sel_hi:[1,1,1]
	v_pk_fma_f32 v[126:127], v[126:127], v[174:175], v[228:229] op_sel:[0,1,0] op_sel_hi:[1,1,1]
	v_exp_f32_e32 v96, v96
	v_exp_f32_e32 v97, v97
	v_exp_f32_e32 v98, v98
	v_exp_f32_e32 v99, v99
	v_exp_f32_e32 v100, v100
	v_exp_f32_e32 v101, v101
	v_exp_f32_e32 v102, v102
	v_exp_f32_e32 v103, v103
	v_exp_f32_e32 v104, v104
	v_exp_f32_e32 v105, v105
	v_exp_f32_e32 v106, v106
	v_exp_f32_e32 v107, v107
	v_exp_f32_e32 v108, v108
	v_exp_f32_e32 v109, v109
	v_exp_f32_e32 v110, v110
	v_exp_f32_e32 v111, v111
	v_exp_f32_e32 v112, v112
	v_exp_f32_e32 v113, v113
	v_exp_f32_e32 v114, v114
	v_exp_f32_e32 v115, v115
	v_exp_f32_e32 v116, v116
	v_exp_f32_e32 v117, v117
	v_exp_f32_e32 v118, v118
	v_exp_f32_e32 v119, v119
	v_exp_f32_e32 v120, v120
	v_exp_f32_e32 v121, v121
	v_exp_f32_e32 v122, v122
	v_exp_f32_e32 v123, v123
	v_exp_f32_e32 v124, v124
	v_exp_f32_e32 v125, v125
	v_exp_f32_e32 v126, v126
	v_exp_f32_e32 v127, v127
	v_pk_add_f32 v[96:97], v[96:97], 1.0 op_sel_hi:[1,0]
	v_pk_add_f32 v[98:99], v[98:99], 1.0 op_sel_hi:[1,0]
	v_pk_add_f32 v[100:101], v[100:101], 1.0 op_sel_hi:[1,0]
	v_pk_add_f32 v[102:103], v[102:103], 1.0 op_sel_hi:[1,0]
	v_pk_add_f32 v[104:105], v[104:105], 1.0 op_sel_hi:[1,0]
	v_pk_add_f32 v[106:107], v[106:107], 1.0 op_sel_hi:[1,0]
	v_pk_add_f32 v[108:109], v[108:109], 1.0 op_sel_hi:[1,0]
	v_pk_add_f32 v[110:111], v[110:111], 1.0 op_sel_hi:[1,0]
	v_pk_add_f32 v[112:113], v[112:113], 1.0 op_sel_hi:[1,0]
	v_pk_add_f32 v[114:115], v[114:115], 1.0 op_sel_hi:[1,0]
	v_pk_add_f32 v[116:117], v[116:117], 1.0 op_sel_hi:[1,0]
	v_pk_add_f32 v[118:119], v[118:119], 1.0 op_sel_hi:[1,0]
	v_pk_add_f32 v[120:121], v[120:121], 1.0 op_sel_hi:[1,0]
	v_pk_add_f32 v[122:123], v[122:123], 1.0 op_sel_hi:[1,0]
	v_pk_add_f32 v[124:125], v[124:125], 1.0 op_sel_hi:[1,0]
	v_pk_add_f32 v[126:127], v[126:127], 1.0 op_sel_hi:[1,0]
	v_rcp_f32_e32 v96, v96
	v_rcp_f32_e32 v97, v97
	v_rcp_f32_e32 v98, v98
	v_rcp_f32_e32 v99, v99
	v_rcp_f32_e32 v100, v100
	v_rcp_f32_e32 v101, v101
	v_rcp_f32_e32 v102, v102
	v_rcp_f32_e32 v103, v103
	v_rcp_f32_e32 v104, v104
	v_rcp_f32_e32 v105, v105
	v_rcp_f32_e32 v106, v106
	v_rcp_f32_e32 v107, v107
	v_rcp_f32_e32 v108, v108
	v_rcp_f32_e32 v109, v109
	v_rcp_f32_e32 v110, v110
	v_rcp_f32_e32 v111, v111
	v_rcp_f32_e32 v112, v112
	v_rcp_f32_e32 v113, v113
	v_rcp_f32_e32 v114, v114
	v_rcp_f32_e32 v115, v115
	v_rcp_f32_e32 v116, v116
	v_rcp_f32_e32 v117, v117
	v_rcp_f32_e32 v118, v118
	v_rcp_f32_e32 v119, v119
	v_rcp_f32_e32 v120, v120
	v_rcp_f32_e32 v121, v121
	v_rcp_f32_e32 v122, v122
	v_rcp_f32_e32 v123, v123
	v_rcp_f32_e32 v124, v124
	v_rcp_f32_e32 v125, v125
	v_rcp_f32_e32 v126, v126
	v_rcp_f32_e32 v127, v127
	s_nop 0
	v_cvt_pk_bf16_f32 v96, v96, v97
	v_cvt_pk_bf16_f32 v97, v98, v99
	v_cvt_pk_bf16_f32 v98, v100, v101
	v_cvt_pk_bf16_f32 v99, v102, v103
	v_cvt_pk_bf16_f32 v100, v104, v105
	v_cvt_pk_bf16_f32 v101, v106, v107
	v_cvt_pk_bf16_f32 v102, v108, v109
	v_cvt_pk_bf16_f32 v103, v110, v111
	v_cvt_pk_bf16_f32 v112, v112, v113
	v_cvt_pk_bf16_f32 v113, v114, v115
	v_cvt_pk_bf16_f32 v114, v116, v117
	v_cvt_pk_bf16_f32 v115, v118, v119
	v_cvt_pk_bf16_f32 v116, v120, v121
	v_cvt_pk_bf16_f32 v117, v122, v123
	v_cvt_pk_bf16_f32 v118, v124, v125
	v_cvt_pk_bf16_f32 v119, v126, v127
	v_permlane32_swap_b32_e32 v96, v98
	v_permlane32_swap_b32_e32 v97, v99
	v_permlane32_swap_b32_e32 v100, v102
	v_permlane32_swap_b32_e32 v101, v103
	v_permlane32_swap_b32_e32 v112, v114
	v_permlane32_swap_b32_e32 v113, v115
	v_permlane32_swap_b32_e32 v116, v118
	v_permlane32_swap_b32_e32 v117, v119
	s_nop 1
	s_mov_b32 vcc_lo, 0x55555555
	s_mov_b32 vcc_hi, 0x55555555
	v_cndmask_b32_dpp v128, v100, v96, vcc quad_perm:[1,0,3,2] row_mask:0xf bank_mask:0xf
	v_cndmask_b32_dpp v129, v101, v97, vcc quad_perm:[1,0,3,2] row_mask:0xf bank_mask:0xf
	v_cndmask_b32_dpp v130, v102, v98, vcc quad_perm:[1,0,3,2] row_mask:0xf bank_mask:0xf
	v_cndmask_b32_dpp v131, v103, v99, vcc quad_perm:[1,0,3,2] row_mask:0xf bank_mask:0xf
	v_cndmask_b32_dpp v136, v116, v112, vcc quad_perm:[1,0,3,2] row_mask:0xf bank_mask:0xf
	v_cndmask_b32_dpp v137, v117, v113, vcc quad_perm:[1,0,3,2] row_mask:0xf bank_mask:0xf
	v_cndmask_b32_dpp v138, v118, v114, vcc quad_perm:[1,0,3,2] row_mask:0xf bank_mask:0xf
	v_cndmask_b32_dpp v139, v119, v115, vcc quad_perm:[1,0,3,2] row_mask:0xf bank_mask:0xf
	s_mov_b32 vcc_lo, 0xaaaaaaaa
	s_mov_b32 vcc_hi, 0xaaaaaaaa
	v_cndmask_b32_dpp v132, v96, v100, vcc quad_perm:[1,0,3,2] row_mask:0xf bank_mask:0xf
	v_cndmask_b32_dpp v133, v97, v101, vcc quad_perm:[1,0,3,2] row_mask:0xf bank_mask:0xf
	v_cndmask_b32_dpp v134, v98, v102, vcc quad_perm:[1,0,3,2] row_mask:0xf bank_mask:0xf
	v_cndmask_b32_dpp v135, v99, v103, vcc quad_perm:[1,0,3,2] row_mask:0xf bank_mask:0xf
	v_cndmask_b32_dpp v140, v112, v116, vcc quad_perm:[1,0,3,2] row_mask:0xf bank_mask:0xf
	v_cndmask_b32_dpp v141, v113, v117, vcc quad_perm:[1,0,3,2] row_mask:0xf bank_mask:0xf
	v_cndmask_b32_dpp v142, v114, v118, vcc quad_perm:[1,0,3,2] row_mask:0xf bank_mask:0xf
	v_cndmask_b32_dpp v143, v115, v119, vcc quad_perm:[1,0,3,2] row_mask:0xf bank_mask:0xf
	s_nop 1
	s_mov_b32 vcc_lo, 0x33333333
	s_mov_b32 vcc_hi, 0x33333333
	v_cndmask_b32_dpp v96, v136, v128, vcc quad_perm:[2,3,0,1] row_mask:0xf bank_mask:0xf
	v_cndmask_b32_dpp v97, v137, v129, vcc quad_perm:[2,3,0,1] row_mask:0xf bank_mask:0xf
	v_cndmask_b32_dpp v98, v138, v130, vcc quad_perm:[2,3,0,1] row_mask:0xf bank_mask:0xf
	v_cndmask_b32_dpp v99, v139, v131, vcc quad_perm:[2,3,0,1] row_mask:0xf bank_mask:0xf
	v_cndmask_b32_dpp v100, v140, v132, vcc quad_perm:[2,3,0,1] row_mask:0xf bank_mask:0xf
	v_cndmask_b32_dpp v101, v141, v133, vcc quad_perm:[2,3,0,1] row_mask:0xf bank_mask:0xf
	v_cndmask_b32_dpp v102, v142, v134, vcc quad_perm:[2,3,0,1] row_mask:0xf bank_mask:0xf
	v_cndmask_b32_dpp v103, v143, v135, vcc quad_perm:[2,3,0,1] row_mask:0xf bank_mask:0xf
	s_mov_b32 vcc_lo, 0xcccccccc
	s_mov_b32 vcc_hi, 0xcccccccc
	v_cndmask_b32_dpp v112, v128, v136, vcc quad_perm:[2,3,0,1] row_mask:0xf bank_mask:0xf
	v_cndmask_b32_dpp v113, v129, v137, vcc quad_perm:[2,3,0,1] row_mask:0xf bank_mask:0xf
	v_cndmask_b32_dpp v114, v130, v138, vcc quad_perm:[2,3,0,1] row_mask:0xf bank_mask:0xf
	v_cndmask_b32_dpp v115, v131, v139, vcc quad_perm:[2,3,0,1] row_mask:0xf bank_mask:0xf
	v_cndmask_b32_dpp v116, v132, v140, vcc quad_perm:[2,3,0,1] row_mask:0xf bank_mask:0xf
	v_cndmask_b32_dpp v117, v133, v141, vcc quad_perm:[2,3,0,1] row_mask:0xf bank_mask:0xf
	v_cndmask_b32_dpp v118, v134, v142, vcc quad_perm:[2,3,0,1] row_mask:0xf bank_mask:0xf
	v_cndmask_b32_dpp v119, v135, v143, vcc quad_perm:[2,3,0,1] row_mask:0xf bank_mask:0xf
	s_add_u32 s76, s74, 0x0
	s_addc_u32 s77, s75, 0
	global_store_dwordx4 v181, v[96:99], s[76:77]
	s_add_u32 s76, s74, 0x2200
	s_addc_u32 s77, s75, 0
	global_store_dwordx4 v181, v[100:103], s[76:77]
	s_add_u32 s76, s74, 0x4400
	s_addc_u32 s77, s75, 0
	global_store_dwordx4 v181, v[112:115], s[76:77]
	s_add_u32 s76, s74, 0x6600
	s_addc_u32 s77, s75, 0
	global_store_dwordx4 v181, v[116:119], s[76:77]
	s_branch .Lpe_ret_L1
.Lpe_vt_L1:
	s_lshl_b32 s35, s34, 2
	s_add_u32 s35, s35, s28
	s_add_u32 s36, s28, 6
	s_cmp_eq_u32 s25, 8
	s_cselect_b32 s35, s36, s35
	s_lshr_b32 s36, s29, 11
	s_mul_i32 s36, s36, 10
	s_add_u32 s36, s36, s35
	s_lshl_b32 s36, s36, 18
	s_and_b32 s37, s29, 0x7ff
	s_lshl_b32 s37, s37, 1
	s_add_u32 s36, s36, s37
	s_add_u32 s38, s72, 0x14920000
	s_addc_u32 s39, s73, 0
	s_add_u32 s38, s38, s36
	s_addc_u32 s39, s39, 0
	s_mul_i32 s36, s26, 10240
	s_add_u32 s36, s36, 0x10000
	v_lshlrev_b32_e32 v180, 1, v197
	v_mul_u32_u24_e32 v181, 36, v146
	v_add3_u32 v180, v180, v181, s36
	v_lshrrev_b32_e32 v181, 3, v179
	v_and_b32_e32 v146, 7, v179
	v_lshlrev_b32_e32 v146, 4, v146
	v_mul_u32_u24_e32 v198, 144, v181
	v_add3_u32 v198, v198, v146, s36
	v_lshl_add_u32 v199, v181, 12, v146
	s_waitcnt vmcnt(0)
	v_mov_b32_e32 v197, 0x358637bd
	v_pk_add_f32 v[128:129], v[128:129], v[130:131]
	v_pk_add_f32 v[136:137], v[136:137], v[138:139]
	v_pk_add_f32 v[164:165], v[164:165], v[166:167]
	v_pk_add_f32 v[246:247], v[246:247], v[248:249]
	v_add_f32_e32 v128, v128, v129
	v_add_f32_e32 v136, v136, v137
	v_add_f32_e32 v164, v164, v165
	v_add_f32_e32 v246, v246, v247
	v_mov_b32_e32 v132, v128
	v_mov_b32_e32 v140, v136
	v_mov_b32_e32 v168, v164
	v_mov_b32_e32 v250, v246
	s_nop 1
	v_permlane32_swap_b32_e32 v132, v128
	v_permlane32_swap_b32_e32 v140, v136
	v_permlane32_swap_b32_e32 v168, v164
	v_permlane32_swap_b32_e32 v250, v246
	v_add_f32_e32 v128, v128, v132
	v_add_f32_e32 v136, v136, v140
	v_add_f32_e32 v164, v164, v168
	v_add_f32_e32 v246, v246, v250
	v_fmamk_f32 v128, v128, 0x3a800000, v197
	v_fmamk_f32 v136, v136, 0x3a800000, v197
	v_fmamk_f32 v164, v164, 0x3a800000, v197
	v_fmamk_f32 v246, v246, 0x3a800000, v197
	v_rsq_f32_e32 v172, v128
	v_rsq_f32_e32 v173, v136
	v_rsq_f32_e32 v174, v164
	v_rsq_f32_e32 v175, v246
	s_nop 0
	s_add_u32 s76, s99, s90
	s_cmp_lt_u32 s76, 0x440
	s_cselect_b32 s80, 1, 0
	s_cselect_b32 s83, 0x200000, 0
	s_lshl_b32 s76, s24, 19
	s_lshl_b32 s77, s26, 16
	s_add_u32 s76, s76, s77
	s_and_b32 s77, s24, 7
	s_lshl_b32 s77, s77, 8
	s_add_u32 s76, s76, s77
	s_add_u32 s78, s72, 0xa120000
	s_addc_u32 s79, s73, 0
	s_add_u32 s78, s78, s76
	s_addc_u32 s79, s79, 0
	s_lshl_b32 s76, s25, 19
	s_add_u32 s76, s76, s83
	s_add_u32 s76, s76, s77
	s_lshl_b32 s77, s26, 16
	s_add_u32 s76, s76, s77
	s_add_u32 s82, s72, 0x880000
	s_addc_u32 s83, s73, 0
	s_add_u32 s82, s82, s76
	s_addc_u32 s83, s83, 0
	s_lshl_b32 s76, s26, 12
	s_mov_b32 m0, s76
	s_nop 0
	global_load_lds_dwordx4 v177, s[78:79]
	s_add_u32 s78, s78, 0x4000
	s_addc_u32 s79, s79, 0
	s_add_u32 s76, s76, 0x400
	s_mov_b32 m0, s76
	s_nop 0
	global_load_lds_dwordx4 v185, s[78:79]
	s_add_u32 s78, s78, 0x4000
	s_addc_u32 s79, s79, 0
	s_add_u32 s76, s76, 0x400
	s_mov_b32 m0, s76
	s_nop 0
	global_load_lds_dwordx4 v177, s[78:79]
	s_add_u32 s78, s78, 0x4000
	s_addc_u32 s79, s79, 0
	s_add_u32 s76, s76, 0x400
	s_mov_b32 m0, s76
	s_nop 0
	global_load_lds_dwordx4 v185, s[78:79]
	s_add_u32 s78, s78, 0x4000
	s_addc_u32 s79, s79, 0
	s_add_u32 s76, s76, 0x400
	s_add_u32 s76, s76, 0x7000
	s_mov_b32 m0, s76
	s_nop 0
	global_load_lds_dwordx4 v177, s[82:83]
	s_add_u32 s82, s82, 0x4000
	s_addc_u32 s83, s83, 0
	s_add_u32 s76, s76, 0x400
	s_mov_b32 m0, s76
	s_nop 0
	global_load_lds_dwordx4 v185, s[82:83]
	s_add_u32 s82, s82, 0x4000
	s_addc_u32 s83, s83, 0
	s_add_u32 s76, s76, 0x400
	s_mov_b32 m0, s76
	s_nop 0
	global_load_lds_dwordx4 v177, s[82:83]
	s_add_u32 s82, s82, 0x4000
	s_addc_u32 s83, s83, 0
	s_add_u32 s76, s76, 0x400
	s_mov_b32 m0, s76
	s_nop 0
	global_load_lds_dwordx4 v185, s[82:83]
	s_add_u32 s82, s82, 0x4000
	s_addc_u32 s83, s83, 0
	s_add_u32 s76, s76, 0x400
	v_pk_mul_f32 v[0:1], v[0:1], v[172:173] op_sel_hi:[1,0]
	v_pk_mul_f32 v[2:3], v[2:3], v[172:173] op_sel_hi:[1,0]
	v_pk_mul_f32 v[4:5], v[4:5], v[172:173] op_sel_hi:[1,0]
	v_pk_mul_f32 v[6:7], v[6:7], v[172:173] op_sel_hi:[1,0]
	v_pk_mul_f32 v[8:9], v[8:9], v[172:173] op_sel_hi:[1,0]
	v_pk_mul_f32 v[10:11], v[10:11], v[172:173] op_sel_hi:[1,0]
	v_pk_mul_f32 v[12:13], v[12:13], v[172:173] op_sel_hi:[1,0]
	v_pk_mul_f32 v[14:15], v[14:15], v[172:173] op_sel_hi:[1,0]
	v_pk_mul_f32 v[16:17], v[16:17], v[172:173] op_sel_hi:[1,0]
	v_pk_mul_f32 v[18:19], v[18:19], v[172:173] op_sel_hi:[1,0]
	v_pk_mul_f32 v[20:21], v[20:21], v[172:173] op_sel_hi:[1,0]
	v_pk_mul_f32 v[22:23], v[22:23], v[172:173] op_sel_hi:[1,0]
	v_pk_mul_f32 v[24:25], v[24:25], v[172:173] op_sel_hi:[1,0]
	v_pk_mul_f32 v[26:27], v[26:27], v[172:173] op_sel_hi:[1,0]
	v_pk_mul_f32 v[28:29], v[28:29], v[172:173] op_sel_hi:[1,0]
	v_pk_mul_f32 v[30:31], v[30:31], v[172:173] op_sel_hi:[1,0]
	v_pk_mul_f32 v[32:33], v[32:33], v[172:173] op_sel:[0,1] op_sel_hi:[1,1]
	v_pk_mul_f32 v[34:35], v[34:35], v[172:173] op_sel:[0,1] op_sel_hi:[1,1]
	v_pk_mul_f32 v[36:37], v[36:37], v[172:173] op_sel:[0,1] op_sel_hi:[1,1]
	v_pk_mul_f32 v[38:39], v[38:39], v[172:173] op_sel:[0,1] op_sel_hi:[1,1]
	v_pk_mul_f32 v[40:41], v[40:41], v[172:173] op_sel:[0,1] op_sel_hi:[1,1]
	v_pk_mul_f32 v[42:43], v[42:43], v[172:173] op_sel:[0,1] op_sel_hi:[1,1]
	v_pk_mul_f32 v[44:45], v[44:45], v[172:173] op_sel:[0,1] op_sel_hi:[1,1]
	v_pk_mul_f32 v[46:47], v[46:47], v[172:173] op_sel:[0,1] op_sel_hi:[1,1]
	v_pk_mul_f32 v[48:49], v[48:49], v[172:173] op_sel:[0,1] op_sel_hi:[1,1]
	v_pk_mul_f32 v[50:51], v[50:51], v[172:173] op_sel:[0,1] op_sel_hi:[1,1]
	v_pk_mul_f32 v[52:53], v[52:53], v[172:173] op_sel:[0,1] op_sel_hi:[1,1]
	v_pk_mul_f32 v[54:55], v[54:55], v[172:173] op_sel:[0,1] op_sel_hi:[1,1]
	v_pk_mul_f32 v[56:57], v[56:57], v[172:173] op_sel:[0,1] op_sel_hi:[1,1]
	v_pk_mul_f32 v[58:59], v[58:59], v[172:173] op_sel:[0,1] op_sel_hi:[1,1]
	v_pk_mul_f32 v[60:61], v[60:61], v[172:173] op_sel:[0,1] op_sel_hi:[1,1]
	v_pk_mul_f32 v[62:63], v[62:63], v[172:173] op_sel:[0,1] op_sel_hi:[1,1]
	v_pk_mul_f32 v[64:65], v[64:65], v[174:175] op_sel_hi:[1,0]
	v_pk_mul_f32 v[66:67], v[66:67], v[174:175] op_sel_hi:[1,0]
	v_pk_mul_f32 v[68:69], v[68:69], v[174:175] op_sel_hi:[1,0]
	v_pk_mul_f32 v[70:71], v[70:71], v[174:175] op_sel_hi:[1,0]
	v_pk_mul_f32 v[72:73], v[72:73], v[174:175] op_sel_hi:[1,0]
	v_pk_mul_f32 v[74:75], v[74:75], v[174:175] op_sel_hi:[1,0]
	v_pk_mul_f32 v[76:77], v[76:77], v[174:175] op_sel_hi:[1,0]
	v_pk_mul_f32 v[78:79], v[78:79], v[174:175] op_sel_hi:[1,0]
	v_pk_mul_f32 v[80:81], v[80:81], v[174:175] op_sel_hi:[1,0]
	v_pk_mul_f32 v[82:83], v[82:83], v[174:175] op_sel_hi:[1,0]
	v_pk_mul_f32 v[84:85], v[84:85], v[174:175] op_sel_hi:[1,0]
	v_pk_mul_f32 v[86:87], v[86:87], v[174:175] op_sel_hi:[1,0]
	v_pk_mul_f32 v[88:89], v[88:89], v[174:175] op_sel_hi:[1,0]
	v_pk_mul_f32 v[90:91], v[90:91], v[174:175] op_sel_hi:[1,0]
	v_pk_mul_f32 v[92:93], v[92:93], v[174:175] op_sel_hi:[1,0]
	v_pk_mul_f32 v[94:95], v[94:95], v[174:175] op_sel_hi:[1,0]
	v_pk_mul_f32 v[96:97], v[96:97], v[174:175] op_sel:[0,1] op_sel_hi:[1,1]
	v_pk_mul_f32 v[98:99], v[98:99], v[174:175] op_sel:[0,1] op_sel_hi:[1,1]
	v_pk_mul_f32 v[100:101], v[100:101], v[174:175] op_sel:[0,1] op_sel_hi:[1,1]
	v_pk_mul_f32 v[102:103], v[102:103], v[174:175] op_sel:[0,1] op_sel_hi:[1,1]
	v_pk_mul_f32 v[104:105], v[104:105], v[174:175] op_sel:[0,1] op_sel_hi:[1,1]
	v_pk_mul_f32 v[106:107], v[106:107], v[174:175] op_sel:[0,1] op_sel_hi:[1,1]
	v_pk_mul_f32 v[108:109], v[108:109], v[174:175] op_sel:[0,1] op_sel_hi:[1,1]
	v_pk_mul_f32 v[110:111], v[110:111], v[174:175] op_sel:[0,1] op_sel_hi:[1,1]
	v_pk_mul_f32 v[112:113], v[112:113], v[174:175] op_sel:[0,1] op_sel_hi:[1,1]
	v_pk_mul_f32 v[114:115], v[114:115], v[174:175] op_sel:[0,1] op_sel_hi:[1,1]
	v_pk_mul_f32 v[116:117], v[116:117], v[174:175] op_sel:[0,1] op_sel_hi:[1,1]
	v_pk_mul_f32 v[118:119], v[118:119], v[174:175] op_sel:[0,1] op_sel_hi:[1,1]
	v_pk_mul_f32 v[120:121], v[120:121], v[174:175] op_sel:[0,1] op_sel_hi:[1,1]
	v_pk_mul_f32 v[122:123], v[122:123], v[174:175] op_sel:[0,1] op_sel_hi:[1,1]
	v_pk_mul_f32 v[124:125], v[124:125], v[174:175] op_sel:[0,1] op_sel_hi:[1,1]
	v_pk_mul_f32 v[126:127], v[126:127], v[174:175] op_sel:[0,1] op_sel_hi:[1,1]
	v_cvt_pk_bf16_f32 v0, v0, v1
	v_cvt_pk_bf16_f32 v1, v2, v3
	v_cvt_pk_bf16_f32 v2, v4, v5
	v_cvt_pk_bf16_f32 v3, v6, v7
	v_cvt_pk_bf16_f32 v4, v8, v9
	v_cvt_pk_bf16_f32 v5, v10, v11
	v_cvt_pk_bf16_f32 v6, v12, v13
	v_cvt_pk_bf16_f32 v7, v14, v15
	ds_write_b16 v180, v0 offset:0
	ds_write_b16_d16_hi v180, v0 offset:144
	ds_write_b16 v180, v1 offset:288
	ds_write_b16_d16_hi v180, v1 offset:432
	ds_write_b16 v180, v2 offset:1152
	ds_write_b16_d16_hi v180, v2 offset:1296
	ds_write_b16 v180, v3 offset:1440
	ds_write_b16_d16_hi v180, v3 offset:1584
	ds_write_b16 v180, v4 offset:2304
	ds_write_b16_d16_hi v180, v4 offset:2448
	ds_write_b16 v180, v5 offset:2592
	ds_write_b16_d16_hi v180, v5 offset:2736
	ds_write_b16 v180, v6 offset:3456
	ds_write_b16_d16_hi v180, v6 offset:3600
	ds_write_b16 v180, v7 offset:3744
	ds_write_b16_d16_hi v180, v7 offset:3888
	v_cvt_pk_bf16_f32 v16, v16, v17
	v_cvt_pk_bf16_f32 v17, v18, v19
	v_cvt_pk_bf16_f32 v18, v20, v21
	v_cvt_pk_bf16_f32 v19, v22, v23
	v_cvt_pk_bf16_f32 v20, v24, v25
	v_cvt_pk_bf16_f32 v21, v26, v27
	v_cvt_pk_bf16_f32 v22, v28, v29
	v_cvt_pk_bf16_f32 v23, v30, v31
	ds_write_b16 v180, v16 offset:4608
	ds_write_b16_d16_hi v180, v16 offset:4752
	ds_write_b16 v180, v17 offset:4896
	ds_write_b16_d16_hi v180, v17 offset:5040
	ds_write_b16 v180, v18 offset:5760
	ds_write_b16_d16_hi v180, v18 offset:5904
	ds_write_b16 v180, v19 offset:6048
	ds_write_b16_d16_hi v180, v19 offset:6192
	ds_write_b16 v180, v20 offset:6912
	ds_write_b16_d16_hi v180, v20 offset:7056
	ds_write_b16 v180, v21 offset:7200
	ds_write_b16_d16_hi v180, v21 offset:7344
	ds_write_b16 v180, v22 offset:8064
	ds_write_b16_d16_hi v180, v22 offset:8208
	ds_write_b16 v180, v23 offset:8352
	ds_write_b16_d16_hi v180, v23 offset:8496
	v_cvt_pk_bf16_f32 v32, v32, v33
	v_cvt_pk_bf16_f32 v33, v34, v35
	v_cvt_pk_bf16_f32 v34, v36, v37
	v_cvt_pk_bf16_f32 v35, v38, v39
	v_cvt_pk_bf16_f32 v36, v40, v41
	v_cvt_pk_bf16_f32 v37, v42, v43
	v_cvt_pk_bf16_f32 v38, v44, v45
	v_cvt_pk_bf16_f32 v39, v46, v47
	ds_write_b16 v180, v32 offset:64
	ds_write_b16_d16_hi v180, v32 offset:208
	ds_write_b16 v180, v33 offset:352
	ds_write_b16_d16_hi v180, v33 offset:496
	ds_write_b16 v180, v34 offset:1216
	ds_write_b16_d16_hi v180, v34 offset:1360
	ds_write_b16 v180, v35 offset:1504
	ds_write_b16_d16_hi v180, v35 offset:1648
	ds_write_b16 v180, v36 offset:2368
	ds_write_b16_d16_hi v180, v36 offset:2512
	ds_write_b16 v180, v37 offset:2656
	ds_write_b16_d16_hi v180, v37 offset:2800
	ds_write_b16 v180, v38 offset:3520
	ds_write_b16_d16_hi v180, v38 offset:3664
	ds_write_b16 v180, v39 offset:3808
	ds_write_b16_d16_hi v180, v39 offset:3952
	v_cvt_pk_bf16_f32 v48, v48, v49
	v_cvt_pk_bf16_f32 v49, v50, v51
	v_cvt_pk_bf16_f32 v50, v52, v53
	v_cvt_pk_bf16_f32 v51, v54, v55
	v_cvt_pk_bf16_f32 v52, v56, v57
	v_cvt_pk_bf16_f32 v53, v58, v59
	v_cvt_pk_bf16_f32 v54, v60, v61
	v_cvt_pk_bf16_f32 v55, v62, v63
	ds_write_b16 v180, v48 offset:4672
	ds_write_b16_d16_hi v180, v48 offset:4816
	ds_write_b16 v180, v49 offset:4960
	ds_write_b16_d16_hi v180, v49 offset:5104
	ds_write_b16 v180, v50 offset:5824
	ds_write_b16_d16_hi v180, v50 offset:5968
	ds_write_b16 v180, v51 offset:6112
	ds_write_b16_d16_hi v180, v51 offset:6256
	ds_write_b16 v180, v52 offset:6976
	ds_write_b16_d16_hi v180, v52 offset:7120
	ds_write_b16 v180, v53 offset:7264
	ds_write_b16_d16_hi v180, v53 offset:7408
	ds_write_b16 v180, v54 offset:8128
	ds_write_b16_d16_hi v180, v54 offset:8272
	ds_write_b16 v180, v55 offset:8416
	ds_write_b16_d16_hi v180, v55 offset:8560
	s_waitcnt lgkmcnt(0)
	ds_read_b128 v[0:3], v198 offset:0
	ds_read_b128 v[4:7], v198 offset:1152
	ds_read_b128 v[8:11], v198 offset:2304
	ds_read_b128 v[12:15], v198 offset:3456
	ds_read_b128 v[16:19], v198 offset:4608
	ds_read_b128 v[20:23], v198 offset:5760
	ds_read_b128 v[24:27], v198 offset:6912
	ds_read_b128 v[28:31], v198 offset:8064
	s_waitcnt lgkmcnt(7)
	global_store_dwordx4 v199, v[0:3], s[38:39]
	s_add_u32 s38, s38, 0x8000
	s_addc_u32 s39, s39, 0
	s_waitcnt lgkmcnt(6)
	global_store_dwordx4 v199, v[4:7], s[38:39]
	s_add_u32 s38, s38, 0x8000
	s_addc_u32 s39, s39, 0
	s_waitcnt lgkmcnt(5)
	global_store_dwordx4 v199, v[8:11], s[38:39]
	s_add_u32 s38, s38, 0x8000
	s_addc_u32 s39, s39, 0
	s_waitcnt lgkmcnt(4)
	global_store_dwordx4 v199, v[12:15], s[38:39]
	s_add_u32 s38, s38, 0x8000
	s_addc_u32 s39, s39, 0
	s_waitcnt lgkmcnt(3)
	global_store_dwordx4 v199, v[16:19], s[38:39]
	s_add_u32 s38, s38, 0x8000
	s_addc_u32 s39, s39, 0
	s_waitcnt lgkmcnt(2)
	global_store_dwordx4 v199, v[20:23], s[38:39]
	s_add_u32 s38, s38, 0x8000
	s_addc_u32 s39, s39, 0
	s_waitcnt lgkmcnt(1)
	global_store_dwordx4 v199, v[24:27], s[38:39]
	s_add_u32 s38, s38, 0x8000
	s_addc_u32 s39, s39, 0
	s_waitcnt lgkmcnt(0)
	global_store_dwordx4 v199, v[28:31], s[38:39]
	s_sub_u32 s38, s38, 229248
	s_subb_u32 s39, s39, 0
	v_cvt_pk_bf16_f32 v64, v64, v65
	v_cvt_pk_bf16_f32 v65, v66, v67
	v_cvt_pk_bf16_f32 v66, v68, v69
	v_cvt_pk_bf16_f32 v67, v70, v71
	v_cvt_pk_bf16_f32 v68, v72, v73
	v_cvt_pk_bf16_f32 v69, v74, v75
	v_cvt_pk_bf16_f32 v70, v76, v77
	v_cvt_pk_bf16_f32 v71, v78, v79
	ds_write_b16 v180, v64 offset:0
	ds_write_b16_d16_hi v180, v64 offset:144
	ds_write_b16 v180, v65 offset:288
	ds_write_b16_d16_hi v180, v65 offset:432
	ds_write_b16 v180, v66 offset:1152
	ds_write_b16_d16_hi v180, v66 offset:1296
	ds_write_b16 v180, v67 offset:1440
	ds_write_b16_d16_hi v180, v67 offset:1584
	ds_write_b16 v180, v68 offset:2304
	ds_write_b16_d16_hi v180, v68 offset:2448
	ds_write_b16 v180, v69 offset:2592
	ds_write_b16_d16_hi v180, v69 offset:2736
	ds_write_b16 v180, v70 offset:3456
	ds_write_b16_d16_hi v180, v70 offset:3600
	ds_write_b16 v180, v71 offset:3744
	ds_write_b16_d16_hi v180, v71 offset:3888
	v_cvt_pk_bf16_f32 v80, v80, v81
	v_cvt_pk_bf16_f32 v81, v82, v83
	v_cvt_pk_bf16_f32 v82, v84, v85
	v_cvt_pk_bf16_f32 v83, v86, v87
	v_cvt_pk_bf16_f32 v84, v88, v89
	v_cvt_pk_bf16_f32 v85, v90, v91
	v_cvt_pk_bf16_f32 v86, v92, v93
	v_cvt_pk_bf16_f32 v87, v94, v95
	ds_write_b16 v180, v80 offset:4608
	ds_write_b16_d16_hi v180, v80 offset:4752
	ds_write_b16 v180, v81 offset:4896
	ds_write_b16_d16_hi v180, v81 offset:5040
	ds_write_b16 v180, v82 offset:5760
	ds_write_b16_d16_hi v180, v82 offset:5904
	ds_write_b16 v180, v83 offset:6048
	ds_write_b16_d16_hi v180, v83 offset:6192
	ds_write_b16 v180, v84 offset:6912
	ds_write_b16_d16_hi v180, v84 offset:7056
	ds_write_b16 v180, v85 offset:7200
	ds_write_b16_d16_hi v180, v85 offset:7344
	ds_write_b16 v180, v86 offset:8064
	ds_write_b16_d16_hi v180, v86 offset:8208
	ds_write_b16 v180, v87 offset:8352
	ds_write_b16_d16_hi v180, v87 offset:8496
	v_cvt_pk_bf16_f32 v96, v96, v97
	v_cvt_pk_bf16_f32 v97, v98, v99
	v_cvt_pk_bf16_f32 v98, v100, v101
	v_cvt_pk_bf16_f32 v99, v102, v103
	v_cvt_pk_bf16_f32 v100, v104, v105
	v_cvt_pk_bf16_f32 v101, v106, v107
	v_cvt_pk_bf16_f32 v102, v108, v109
	v_cvt_pk_bf16_f32 v103, v110, v111
	ds_write_b16 v180, v96 offset:64
	ds_write_b16_d16_hi v180, v96 offset:208
	ds_write_b16 v180, v97 offset:352
	ds_write_b16_d16_hi v180, v97 offset:496
	ds_write_b16 v180, v98 offset:1216
	ds_write_b16_d16_hi v180, v98 offset:1360
	ds_write_b16 v180, v99 offset:1504
	ds_write_b16_d16_hi v180, v99 offset:1648
	ds_write_b16 v180, v100 offset:2368
	ds_write_b16_d16_hi v180, v100 offset:2512
	ds_write_b16 v180, v101 offset:2656
	ds_write_b16_d16_hi v180, v101 offset:2800
	ds_write_b16 v180, v102 offset:3520
	ds_write_b16_d16_hi v180, v102 offset:3664
	ds_write_b16 v180, v103 offset:3808
	ds_write_b16_d16_hi v180, v103 offset:3952
	v_cvt_pk_bf16_f32 v112, v112, v113
	v_cvt_pk_bf16_f32 v113, v114, v115
	v_cvt_pk_bf16_f32 v114, v116, v117
	v_cvt_pk_bf16_f32 v115, v118, v119
	v_cvt_pk_bf16_f32 v116, v120, v121
	v_cvt_pk_bf16_f32 v117, v122, v123
	v_cvt_pk_bf16_f32 v118, v124, v125
	v_cvt_pk_bf16_f32 v119, v126, v127
	ds_write_b16 v180, v112 offset:4672
	ds_write_b16_d16_hi v180, v112 offset:4816
	ds_write_b16 v180, v113 offset:4960
	ds_write_b16_d16_hi v180, v113 offset:5104
	ds_write_b16 v180, v114 offset:5824
	ds_write_b16_d16_hi v180, v114 offset:5968
	ds_write_b16 v180, v115 offset:6112
	ds_write_b16_d16_hi v180, v115 offset:6256
	ds_write_b16 v180, v116 offset:6976
	ds_write_b16_d16_hi v180, v116 offset:7120
	ds_write_b16 v180, v117 offset:7264
	ds_write_b16_d16_hi v180, v117 offset:7408
	ds_write_b16 v180, v118 offset:8128
	ds_write_b16_d16_hi v180, v118 offset:8272
	ds_write_b16 v180, v119 offset:8416
	ds_write_b16_d16_hi v180, v119 offset:8560
	s_waitcnt lgkmcnt(0)
	ds_read_b128 v[64:67], v198 offset:0
	ds_read_b128 v[68:71], v198 offset:1152
	ds_read_b128 v[72:75], v198 offset:2304
	ds_read_b128 v[76:79], v198 offset:3456
	ds_read_b128 v[80:83], v198 offset:4608
	ds_read_b128 v[84:87], v198 offset:5760
	ds_read_b128 v[88:91], v198 offset:6912
	ds_read_b128 v[92:95], v198 offset:8064
	s_waitcnt lgkmcnt(7)
	global_store_dwordx4 v199, v[64:67], s[38:39]
	s_add_u32 s38, s38, 0x8000
	s_addc_u32 s39, s39, 0
	s_waitcnt lgkmcnt(6)
	global_store_dwordx4 v199, v[68:71], s[38:39]
	s_add_u32 s38, s38, 0x8000
	s_addc_u32 s39, s39, 0
	s_waitcnt lgkmcnt(5)
	global_store_dwordx4 v199, v[72:75], s[38:39]
	s_add_u32 s38, s38, 0x8000
	s_addc_u32 s39, s39, 0
	s_waitcnt lgkmcnt(4)
	global_store_dwordx4 v199, v[76:79], s[38:39]
	s_add_u32 s38, s38, 0x8000
	s_addc_u32 s39, s39, 0
	s_waitcnt lgkmcnt(3)
	global_store_dwordx4 v199, v[80:83], s[38:39]
	s_add_u32 s38, s38, 0x8000
	s_addc_u32 s39, s39, 0
	s_waitcnt lgkmcnt(2)
	global_store_dwordx4 v199, v[84:87], s[38:39]
	s_add_u32 s38, s38, 0x8000
	s_addc_u32 s39, s39, 0
	s_waitcnt lgkmcnt(1)
	global_store_dwordx4 v199, v[88:91], s[38:39]
	s_add_u32 s38, s38, 0x8000
	s_addc_u32 s39, s39, 0
	s_waitcnt lgkmcnt(0)
	global_store_dwordx4 v199, v[92:95], s[38:39]
